# pool_unroll window sums with unpack + v_pk_add_f32 instead of quarter-rate v_dot2c
# baseline (speedup 1.0000x reference)
.LBB0_332:
	s_or_b64 exec, exec, s[6:7]
	s_waitcnt lgkmcnt(0)
	global_load_dwordx4 v[82:85], v[144:145], off offset:512
	global_load_dwordx4 v[86:89], v[146:147], off offset:512
	global_load_dwordx4 v[90:93], v[148:149], off offset:512
	global_load_dwordx4 v[94:97], v[150:151], off offset:512
	global_load_dwordx4 v[112:115], v[144:145], off offset:1024
	global_load_dwordx4 v[116:119], v[146:147], off offset:1024
	global_load_dwordx4 v[122:125], v[148:149], off offset:1024
	global_load_dwordx4 v[126:129], v[150:151], off offset:1024
	v_or_b32_e32 v2, s28, v1
	v_min_u32_e32 v3, 15, v2
	v_add_u32_e32 v3, 1, v3
	v_cvt_f32_ubyte0_e32 v3, v3
	v_div_scale_f32 v4, s[6:7], v3, v3, 1.0
	v_rcp_f32_e32 v5, v4
	s_ashr_i32 s8, s30, 6
	s_mul_i32 s10, s8, 15
	v_cmp_lt_u32_e64 s[6:7], s41, v2
	v_fma_f32 v6, -v4, v5, 1.0
	v_fmac_f32_e32 v5, v6, v5
	v_div_scale_f32 v6, vcc, 1.0, v3, 1.0
	v_mul_f32_e32 v7, v6, v5
	v_fma_f32 v8, -v4, v7, v6
	v_fmac_f32_e32 v7, v8, v5
	v_fma_f32 v4, -v4, v7, v6
	v_div_fmas_f32 v4, v4, v5, v7
	v_div_fixup_f32 v159, v4, v3, 1.0
	s_ashr_i32 s11, s10, 31
	v_add_u32_e32 v2, 0xfffff80f, v2
	v_mov_b32_e32 v3, v155
	v_lshl_add_u64 v[2:3], v[2:3], 0, s[10:11]
	v_lshlrev_b64 v[2:3], 11, v[2:3]
	v_lshl_add_u64 v[2:3], s[70:71], 0, v[2:3]
	v_mov_b32_e32 v163, v155
	v_lshl_add_u64 v[2:3], v[2:3], 0, v[162:163]
	v_lshl_add_u64 v[192:193], v[2:3], 0, s[16:17]
	v_mov_b32_e32 v2, 0
	s_mov_b32 s49, 0
	s_mov_b64 s[10:11], 0
	v_mov_b32_e32 v3, v2
	v_mov_b32_e32 v4, v2
	v_mov_b32_e32 v5, v2
	v_mov_b32_e32 v6, v2
	v_mov_b32_e32 v7, v2
	v_mov_b32_e32 v8, v2
	v_mov_b32_e32 v9, v2
	v_mov_b32_e32 v10, v2
	v_mov_b32_e32 v11, v2
	v_mov_b32_e32 v12, v2
	v_mov_b32_e32 v13, v2
	v_mov_b32_e32 v14, v2
	v_mov_b32_e32 v15, v2
	v_mov_b32_e32 v16, v2
	v_mov_b32_e32 v17, v2
	v_mov_b32_e32 v18, v2
	v_mov_b32_e32 v19, v2
	v_mov_b32_e32 v20, v2
	v_mov_b32_e32 v21, v2
	v_mov_b32_e32 v22, v2
	v_mov_b32_e32 v23, v2
	v_mov_b32_e32 v24, v2
	v_mov_b32_e32 v25, v2
	v_mov_b32_e32 v26, v2
	v_mov_b32_e32 v27, v2
	v_mov_b32_e32 v28, v2
	v_mov_b32_e32 v29, v2
	v_mov_b32_e32 v30, v2
	v_mov_b32_e32 v31, v2
	v_mov_b32_e32 v32, v2
	v_mov_b32_e32 v33, v2
	v_mov_b32_e32 v34, v2
	v_mov_b32_e32 v35, v2
	v_mov_b32_e32 v36, v2
	v_mov_b32_e32 v37, v2
	v_mov_b32_e32 v38, v2
	v_mov_b32_e32 v39, v2
	v_mov_b32_e32 v40, v2
	v_mov_b32_e32 v41, v2
	v_mov_b32_e32 v42, v2
	v_mov_b32_e32 v43, v2
	v_mov_b32_e32 v44, v2
	v_mov_b32_e32 v45, v2
	v_mov_b32_e32 v46, v2
	v_mov_b32_e32 v47, v2
	v_mov_b32_e32 v48, v2
	v_mov_b32_e32 v49, v2
	v_mov_b32_e32 v50, v2
	v_mov_b32_e32 v51, v2
	v_mov_b32_e32 v52, v2
	v_mov_b32_e32 v53, v2
	v_mov_b32_e32 v54, v2
	v_mov_b32_e32 v55, v2
	v_mov_b32_e32 v56, v2
	v_mov_b32_e32 v57, v2
	v_mov_b32_e32 v58, v2
	v_mov_b32_e32 v59, v2
	v_mov_b32_e32 v60, v2
	v_mov_b32_e32 v61, v2
	v_mov_b32_e32 v62, v2
	v_mov_b32_e32 v63, v2
	v_mov_b32_e32 v64, v2
	v_mov_b32_e32 v65, v2
	v_lshl_add_u32 v163, v197, 1, v214
	ds_read_b128 v[222:225], v163 offset:4080
	ds_read_b128 v[226:229], v163 offset:3808
	ds_read_b128 v[230:233], v163 offset:3536
	ds_read_b128 v[234:237], v163 offset:3264
	ds_read_b128 v[238:241], v163 offset:2992
	ds_read_b128 v[242:245], v163 offset:2720
	ds_read_b128 v[248:251], v163 offset:2448
	ds_read_b128 v[252:255], v163 offset:2176
	s_waitcnt lgkmcnt(7)
	v_lshlrev_b32_e32 v98, 16, v222
	v_and_b32_e32 v99, 0xffff0000, v222
	v_lshlrev_b32_e32 v100, 16, v223
	v_and_b32_e32 v101, 0xffff0000, v223
	v_lshlrev_b32_e32 v102, 16, v224
	v_and_b32_e32 v103, 0xffff0000, v224
	v_lshlrev_b32_e32 v104, 16, v225
	v_and_b32_e32 v105, 0xffff0000, v225
	ds_read_b128 v[222:225], v163 offset:1904
	s_waitcnt lgkmcnt(7)
	v_lshlrev_b32_e32 v216, 16, v226
	v_and_b32_e32 v217, 0xffff0000, v226
	v_pk_add_f32 v[106:107], v[98:99], v[216:217]
	v_lshlrev_b32_e32 v216, 16, v227
	v_and_b32_e32 v217, 0xffff0000, v227
	v_pk_add_f32 v[108:109], v[100:101], v[216:217]
	v_lshlrev_b32_e32 v216, 16, v228
	v_and_b32_e32 v217, 0xffff0000, v228
	v_pk_add_f32 v[218:219], v[102:103], v[216:217]
	v_lshlrev_b32_e32 v216, 16, v229
	v_and_b32_e32 v217, 0xffff0000, v229
	v_pk_add_f32 v[220:221], v[104:105], v[216:217]
	ds_read_b128 v[226:229], v163 offset:1632
	s_waitcnt lgkmcnt(7)
	v_lshlrev_b32_e32 v216, 16, v230
	v_and_b32_e32 v217, 0xffff0000, v230
	v_pk_add_f32 v[106:107], v[106:107], v[216:217]
	v_lshlrev_b32_e32 v216, 16, v231
	v_and_b32_e32 v217, 0xffff0000, v231
	v_pk_add_f32 v[108:109], v[108:109], v[216:217]
	v_lshlrev_b32_e32 v216, 16, v232
	v_and_b32_e32 v217, 0xffff0000, v232
	v_pk_add_f32 v[218:219], v[218:219], v[216:217]
	v_lshlrev_b32_e32 v216, 16, v233
	v_and_b32_e32 v217, 0xffff0000, v233
	v_pk_add_f32 v[220:221], v[220:221], v[216:217]
	ds_read_b128 v[230:233], v163 offset:1360
	s_waitcnt lgkmcnt(7)
	v_lshlrev_b32_e32 v216, 16, v234
	v_and_b32_e32 v217, 0xffff0000, v234
	v_pk_add_f32 v[106:107], v[106:107], v[216:217]
	v_lshlrev_b32_e32 v216, 16, v235
	v_and_b32_e32 v217, 0xffff0000, v235
	v_pk_add_f32 v[108:109], v[108:109], v[216:217]
	v_lshlrev_b32_e32 v216, 16, v236
	v_and_b32_e32 v217, 0xffff0000, v236
	v_pk_add_f32 v[218:219], v[218:219], v[216:217]
	v_lshlrev_b32_e32 v216, 16, v237
	v_and_b32_e32 v217, 0xffff0000, v237
	v_pk_add_f32 v[220:221], v[220:221], v[216:217]
	ds_read_b128 v[234:237], v163 offset:1088
	s_waitcnt lgkmcnt(7)
	v_lshlrev_b32_e32 v216, 16, v238
	v_and_b32_e32 v217, 0xffff0000, v238
	v_pk_add_f32 v[106:107], v[106:107], v[216:217]
	v_lshlrev_b32_e32 v216, 16, v239
	v_and_b32_e32 v217, 0xffff0000, v239
	v_pk_add_f32 v[108:109], v[108:109], v[216:217]
	v_lshlrev_b32_e32 v216, 16, v240
	v_and_b32_e32 v217, 0xffff0000, v240
	v_pk_add_f32 v[218:219], v[218:219], v[216:217]
	v_lshlrev_b32_e32 v216, 16, v241
	v_and_b32_e32 v217, 0xffff0000, v241
	v_pk_add_f32 v[220:221], v[220:221], v[216:217]
	ds_read_b128 v[238:241], v163 offset:816
	s_waitcnt lgkmcnt(7)
	v_lshlrev_b32_e32 v216, 16, v242
	v_and_b32_e32 v217, 0xffff0000, v242
	v_pk_add_f32 v[106:107], v[106:107], v[216:217]
	v_lshlrev_b32_e32 v216, 16, v243
	v_and_b32_e32 v217, 0xffff0000, v243
	v_pk_add_f32 v[108:109], v[108:109], v[216:217]
	v_lshlrev_b32_e32 v216, 16, v244
	v_and_b32_e32 v217, 0xffff0000, v244
	v_pk_add_f32 v[218:219], v[218:219], v[216:217]
	v_lshlrev_b32_e32 v216, 16, v245
	v_and_b32_e32 v217, 0xffff0000, v245
	v_pk_add_f32 v[220:221], v[220:221], v[216:217]
	ds_read_b128 v[242:245], v163 offset:544
	s_waitcnt lgkmcnt(7)
	v_lshlrev_b32_e32 v216, 16, v248
	v_and_b32_e32 v217, 0xffff0000, v248
	v_pk_add_f32 v[106:107], v[106:107], v[216:217]
	v_lshlrev_b32_e32 v216, 16, v249
	v_and_b32_e32 v217, 0xffff0000, v249
	v_pk_add_f32 v[108:109], v[108:109], v[216:217]
	v_lshlrev_b32_e32 v216, 16, v250
	v_and_b32_e32 v217, 0xffff0000, v250
	v_pk_add_f32 v[218:219], v[218:219], v[216:217]
	v_lshlrev_b32_e32 v216, 16, v251
	v_and_b32_e32 v217, 0xffff0000, v251
	v_pk_add_f32 v[220:221], v[220:221], v[216:217]
	ds_read_b128 v[248:251], v163 offset:272
	s_waitcnt lgkmcnt(7)
	v_lshlrev_b32_e32 v216, 16, v252
	v_and_b32_e32 v217, 0xffff0000, v252
	v_pk_add_f32 v[106:107], v[106:107], v[216:217]
	v_lshlrev_b32_e32 v216, 16, v253
	v_and_b32_e32 v217, 0xffff0000, v253
	v_pk_add_f32 v[108:109], v[108:109], v[216:217]
	v_lshlrev_b32_e32 v216, 16, v254
	v_and_b32_e32 v217, 0xffff0000, v254
	v_pk_add_f32 v[218:219], v[218:219], v[216:217]
	v_lshlrev_b32_e32 v216, 16, v255
	v_and_b32_e32 v217, 0xffff0000, v255
	v_pk_add_f32 v[220:221], v[220:221], v[216:217]
	ds_read_b128 v[252:255], v163 offset:0
	s_waitcnt lgkmcnt(7)
	v_lshlrev_b32_e32 v216, 16, v222
	v_and_b32_e32 v217, 0xffff0000, v222
	v_pk_add_f32 v[106:107], v[106:107], v[216:217]
	v_lshlrev_b32_e32 v216, 16, v223
	v_and_b32_e32 v217, 0xffff0000, v223
	v_pk_add_f32 v[108:109], v[108:109], v[216:217]
	v_lshlrev_b32_e32 v216, 16, v224
	v_and_b32_e32 v217, 0xffff0000, v224
	v_pk_add_f32 v[218:219], v[218:219], v[216:217]
	v_lshlrev_b32_e32 v216, 16, v225
	v_and_b32_e32 v217, 0xffff0000, v225
	v_pk_add_f32 v[220:221], v[220:221], v[216:217]
	ds_read_b128 v[222:225], v163 offset:4112
	s_waitcnt lgkmcnt(7)
	v_lshlrev_b32_e32 v216, 16, v226
	v_and_b32_e32 v217, 0xffff0000, v226
	v_pk_add_f32 v[106:107], v[106:107], v[216:217]
	v_lshlrev_b32_e32 v216, 16, v227
	v_and_b32_e32 v217, 0xffff0000, v227
	v_pk_add_f32 v[108:109], v[108:109], v[216:217]
	v_lshlrev_b32_e32 v216, 16, v228
	v_and_b32_e32 v217, 0xffff0000, v228
	v_pk_add_f32 v[218:219], v[218:219], v[216:217]
	v_lshlrev_b32_e32 v216, 16, v229
	v_and_b32_e32 v217, 0xffff0000, v229
	v_pk_add_f32 v[220:221], v[220:221], v[216:217]
	ds_read_b128 v[226:229], v163 offset:3840
	s_waitcnt lgkmcnt(7)
	v_lshlrev_b32_e32 v216, 16, v230
	v_and_b32_e32 v217, 0xffff0000, v230
	v_pk_add_f32 v[106:107], v[106:107], v[216:217]
	v_lshlrev_b32_e32 v216, 16, v231
	v_and_b32_e32 v217, 0xffff0000, v231
	v_pk_add_f32 v[108:109], v[108:109], v[216:217]
	v_lshlrev_b32_e32 v216, 16, v232
	v_and_b32_e32 v217, 0xffff0000, v232
	v_pk_add_f32 v[218:219], v[218:219], v[216:217]
	v_lshlrev_b32_e32 v216, 16, v233
	v_and_b32_e32 v217, 0xffff0000, v233
	v_pk_add_f32 v[220:221], v[220:221], v[216:217]
	ds_read_b128 v[230:233], v163 offset:3568
	s_waitcnt lgkmcnt(7)
	v_lshlrev_b32_e32 v216, 16, v234
	v_and_b32_e32 v217, 0xffff0000, v234
	v_pk_add_f32 v[106:107], v[106:107], v[216:217]
	v_lshlrev_b32_e32 v216, 16, v235
	v_and_b32_e32 v217, 0xffff0000, v235
	v_pk_add_f32 v[108:109], v[108:109], v[216:217]
	v_lshlrev_b32_e32 v216, 16, v236
	v_and_b32_e32 v217, 0xffff0000, v236
	v_pk_add_f32 v[218:219], v[218:219], v[216:217]
	v_lshlrev_b32_e32 v216, 16, v237
	v_and_b32_e32 v217, 0xffff0000, v237
	v_pk_add_f32 v[220:221], v[220:221], v[216:217]
	ds_read_b128 v[234:237], v163 offset:3296
	s_waitcnt lgkmcnt(7)
	v_lshlrev_b32_e32 v216, 16, v238
	v_and_b32_e32 v217, 0xffff0000, v238
	v_pk_add_f32 v[106:107], v[106:107], v[216:217]
	v_lshlrev_b32_e32 v216, 16, v239
	v_and_b32_e32 v217, 0xffff0000, v239
	v_pk_add_f32 v[108:109], v[108:109], v[216:217]
	v_lshlrev_b32_e32 v216, 16, v240
	v_and_b32_e32 v217, 0xffff0000, v240
	v_pk_add_f32 v[218:219], v[218:219], v[216:217]
	v_lshlrev_b32_e32 v216, 16, v241
	v_and_b32_e32 v217, 0xffff0000, v241
	v_pk_add_f32 v[220:221], v[220:221], v[216:217]
	ds_read_b128 v[238:241], v163 offset:3024
	s_waitcnt lgkmcnt(7)
	v_lshlrev_b32_e32 v216, 16, v242
	v_and_b32_e32 v217, 0xffff0000, v242
	v_pk_add_f32 v[106:107], v[106:107], v[216:217]
	v_lshlrev_b32_e32 v216, 16, v243
	v_and_b32_e32 v217, 0xffff0000, v243
	v_pk_add_f32 v[108:109], v[108:109], v[216:217]
	v_lshlrev_b32_e32 v216, 16, v244
	v_and_b32_e32 v217, 0xffff0000, v244
	v_pk_add_f32 v[218:219], v[218:219], v[216:217]
	v_lshlrev_b32_e32 v216, 16, v245
	v_and_b32_e32 v217, 0xffff0000, v245
	v_pk_add_f32 v[220:221], v[220:221], v[216:217]
	ds_read_b128 v[242:245], v163 offset:2752
	s_waitcnt lgkmcnt(7)
	v_lshlrev_b32_e32 v216, 16, v248
	v_and_b32_e32 v217, 0xffff0000, v248
	v_pk_add_f32 v[106:107], v[106:107], v[216:217]
	v_lshlrev_b32_e32 v216, 16, v249
	v_and_b32_e32 v217, 0xffff0000, v249
	v_pk_add_f32 v[108:109], v[108:109], v[216:217]
	v_lshlrev_b32_e32 v216, 16, v250
	v_and_b32_e32 v217, 0xffff0000, v250
	v_pk_add_f32 v[218:219], v[218:219], v[216:217]
	v_lshlrev_b32_e32 v216, 16, v251
	v_and_b32_e32 v217, 0xffff0000, v251
	v_pk_add_f32 v[220:221], v[220:221], v[216:217]
	ds_read_b128 v[248:251], v163 offset:2480
	s_waitcnt lgkmcnt(7)
	v_lshlrev_b32_e32 v216, 16, v252
	v_and_b32_e32 v217, 0xffff0000, v252
	v_pk_add_f32 v[106:107], v[106:107], v[216:217]
	v_lshlrev_b32_e32 v216, 16, v253
	v_and_b32_e32 v217, 0xffff0000, v253
	v_pk_add_f32 v[108:109], v[108:109], v[216:217]
	v_lshlrev_b32_e32 v216, 16, v254
	v_and_b32_e32 v217, 0xffff0000, v254
	v_pk_add_f32 v[218:219], v[218:219], v[216:217]
	v_lshlrev_b32_e32 v216, 16, v255
	v_and_b32_e32 v217, 0xffff0000, v255
	v_pk_add_f32 v[220:221], v[220:221], v[216:217]
	ds_read_b128 v[252:255], v163 offset:2208
	v_fma_f32 v106, v159, v106, -v98
	v_fma_f32 v107, v159, v107, -v99
	v_fma_f32 v108, v159, v108, -v100
	v_fma_f32 v109, v159, v109, -v101
	v_fma_f32 v218, v159, v218, -v102
	v_fma_f32 v219, v159, v219, -v103
	v_fma_f32 v220, v159, v220, -v104
	v_fma_f32 v221, v159, v221, -v105
	v_cvt_pk_bf16_f32 v106, v106, v107
	v_cvt_pk_bf16_f32 v107, v108, v109
	v_cvt_pk_bf16_f32 v108, v218, v219
	v_cvt_pk_bf16_f32 v109, v220, v221
	s_and_saveexec_b64 s[28:29], s[6:7]
	s_cbranch_execz .Lpu0_0
	global_store_dwordx4 v[192:193], v[98:101], off offset:0
	global_store_dwordx4 v[192:193], v[102:105], off offset:16
.Lpu0_0:
	s_or_b64 exec, exec, s[28:29]
	s_waitcnt vmcnt(8)
	v_mfma_f32_32x32x16_bf16 v[2:17], v[106:109], v[70:73], v[2:17]
	v_mfma_f32_32x32x16_bf16 v[18:33], v[106:109], v[74:77], v[18:33]
	v_mfma_f32_32x32x16_bf16 v[34:49], v[106:109], v[78:81], v[34:49]
	v_mfma_f32_32x32x16_bf16 v[50:65], v[106:109], v[66:69], v[50:65]
	global_load_dwordx4 v[70:73], v[144:145], off offset:1536
	global_load_dwordx4 v[74:77], v[146:147], off offset:1536
	global_load_dwordx4 v[78:81], v[148:149], off offset:1536
	global_load_dwordx4 v[66:69], v[150:151], off offset:1536
	s_waitcnt lgkmcnt(7)
	v_lshlrev_b32_e32 v98, 16, v222
	v_and_b32_e32 v99, 0xffff0000, v222
	v_lshlrev_b32_e32 v100, 16, v223
	v_and_b32_e32 v101, 0xffff0000, v223
	v_lshlrev_b32_e32 v102, 16, v224
	v_and_b32_e32 v103, 0xffff0000, v224
	v_lshlrev_b32_e32 v104, 16, v225
	v_and_b32_e32 v105, 0xffff0000, v225
	ds_read_b128 v[222:225], v163 offset:1936
	s_waitcnt lgkmcnt(7)
	v_lshlrev_b32_e32 v216, 16, v226
	v_and_b32_e32 v217, 0xffff0000, v226
	v_pk_add_f32 v[106:107], v[98:99], v[216:217]
	v_lshlrev_b32_e32 v216, 16, v227
	v_and_b32_e32 v217, 0xffff0000, v227
	v_pk_add_f32 v[108:109], v[100:101], v[216:217]
	v_lshlrev_b32_e32 v216, 16, v228
	v_and_b32_e32 v217, 0xffff0000, v228
	v_pk_add_f32 v[218:219], v[102:103], v[216:217]
	v_lshlrev_b32_e32 v216, 16, v229
	v_and_b32_e32 v217, 0xffff0000, v229
	v_pk_add_f32 v[220:221], v[104:105], v[216:217]
	ds_read_b128 v[226:229], v163 offset:1664
	s_waitcnt lgkmcnt(7)
	v_lshlrev_b32_e32 v216, 16, v230
	v_and_b32_e32 v217, 0xffff0000, v230
	v_pk_add_f32 v[106:107], v[106:107], v[216:217]
	v_lshlrev_b32_e32 v216, 16, v231
	v_and_b32_e32 v217, 0xffff0000, v231
	v_pk_add_f32 v[108:109], v[108:109], v[216:217]
	v_lshlrev_b32_e32 v216, 16, v232
	v_and_b32_e32 v217, 0xffff0000, v232
	v_pk_add_f32 v[218:219], v[218:219], v[216:217]
	v_lshlrev_b32_e32 v216, 16, v233
	v_and_b32_e32 v217, 0xffff0000, v233
	v_pk_add_f32 v[220:221], v[220:221], v[216:217]
	ds_read_b128 v[230:233], v163 offset:1392
	s_waitcnt lgkmcnt(7)
	v_lshlrev_b32_e32 v216, 16, v234
	v_and_b32_e32 v217, 0xffff0000, v234
	v_pk_add_f32 v[106:107], v[106:107], v[216:217]
	v_lshlrev_b32_e32 v216, 16, v235
	v_and_b32_e32 v217, 0xffff0000, v235
	v_pk_add_f32 v[108:109], v[108:109], v[216:217]
	v_lshlrev_b32_e32 v216, 16, v236
	v_and_b32_e32 v217, 0xffff0000, v236
	v_pk_add_f32 v[218:219], v[218:219], v[216:217]
	v_lshlrev_b32_e32 v216, 16, v237
	v_and_b32_e32 v217, 0xffff0000, v237
	v_pk_add_f32 v[220:221], v[220:221], v[216:217]
	ds_read_b128 v[234:237], v163 offset:1120
	s_waitcnt lgkmcnt(7)
	v_lshlrev_b32_e32 v216, 16, v238
	v_and_b32_e32 v217, 0xffff0000, v238
	v_pk_add_f32 v[106:107], v[106:107], v[216:217]
	v_lshlrev_b32_e32 v216, 16, v239
	v_and_b32_e32 v217, 0xffff0000, v239
	v_pk_add_f32 v[108:109], v[108:109], v[216:217]
	v_lshlrev_b32_e32 v216, 16, v240
	v_and_b32_e32 v217, 0xffff0000, v240
	v_pk_add_f32 v[218:219], v[218:219], v[216:217]
	v_lshlrev_b32_e32 v216, 16, v241
	v_and_b32_e32 v217, 0xffff0000, v241
	v_pk_add_f32 v[220:221], v[220:221], v[216:217]
	ds_read_b128 v[238:241], v163 offset:848
	s_waitcnt lgkmcnt(7)
	v_lshlrev_b32_e32 v216, 16, v242
	v_and_b32_e32 v217, 0xffff0000, v242
	v_pk_add_f32 v[106:107], v[106:107], v[216:217]
	v_lshlrev_b32_e32 v216, 16, v243
	v_and_b32_e32 v217, 0xffff0000, v243
	v_pk_add_f32 v[108:109], v[108:109], v[216:217]
	v_lshlrev_b32_e32 v216, 16, v244
	v_and_b32_e32 v217, 0xffff0000, v244
	v_pk_add_f32 v[218:219], v[218:219], v[216:217]
	v_lshlrev_b32_e32 v216, 16, v245
	v_and_b32_e32 v217, 0xffff0000, v245
	v_pk_add_f32 v[220:221], v[220:221], v[216:217]
	ds_read_b128 v[242:245], v163 offset:576
	s_waitcnt lgkmcnt(7)
	v_lshlrev_b32_e32 v216, 16, v248
	v_and_b32_e32 v217, 0xffff0000, v248
	v_pk_add_f32 v[106:107], v[106:107], v[216:217]
	v_lshlrev_b32_e32 v216, 16, v249
	v_and_b32_e32 v217, 0xffff0000, v249
	v_pk_add_f32 v[108:109], v[108:109], v[216:217]
	v_lshlrev_b32_e32 v216, 16, v250
	v_and_b32_e32 v217, 0xffff0000, v250
	v_pk_add_f32 v[218:219], v[218:219], v[216:217]
	v_lshlrev_b32_e32 v216, 16, v251
	v_and_b32_e32 v217, 0xffff0000, v251
	v_pk_add_f32 v[220:221], v[220:221], v[216:217]
	ds_read_b128 v[248:251], v163 offset:304
	s_waitcnt lgkmcnt(7)
	v_lshlrev_b32_e32 v216, 16, v252
	v_and_b32_e32 v217, 0xffff0000, v252
	v_pk_add_f32 v[106:107], v[106:107], v[216:217]
	v_lshlrev_b32_e32 v216, 16, v253
	v_and_b32_e32 v217, 0xffff0000, v253
	v_pk_add_f32 v[108:109], v[108:109], v[216:217]
	v_lshlrev_b32_e32 v216, 16, v254
	v_and_b32_e32 v217, 0xffff0000, v254
	v_pk_add_f32 v[218:219], v[218:219], v[216:217]
	v_lshlrev_b32_e32 v216, 16, v255
	v_and_b32_e32 v217, 0xffff0000, v255
	v_pk_add_f32 v[220:221], v[220:221], v[216:217]
	ds_read_b128 v[252:255], v163 offset:32
	s_waitcnt lgkmcnt(7)
	v_lshlrev_b32_e32 v216, 16, v222
	v_and_b32_e32 v217, 0xffff0000, v222
	v_pk_add_f32 v[106:107], v[106:107], v[216:217]
	v_lshlrev_b32_e32 v216, 16, v223
	v_and_b32_e32 v217, 0xffff0000, v223
	v_pk_add_f32 v[108:109], v[108:109], v[216:217]
	v_lshlrev_b32_e32 v216, 16, v224
	v_and_b32_e32 v217, 0xffff0000, v224
	v_pk_add_f32 v[218:219], v[218:219], v[216:217]
	v_lshlrev_b32_e32 v216, 16, v225
	v_and_b32_e32 v217, 0xffff0000, v225
	v_pk_add_f32 v[220:221], v[220:221], v[216:217]
	ds_read_b128 v[222:225], v163 offset:4144
	s_waitcnt lgkmcnt(7)
	v_lshlrev_b32_e32 v216, 16, v226
	v_and_b32_e32 v217, 0xffff0000, v226
	v_pk_add_f32 v[106:107], v[106:107], v[216:217]
	v_lshlrev_b32_e32 v216, 16, v227
	v_and_b32_e32 v217, 0xffff0000, v227
	v_pk_add_f32 v[108:109], v[108:109], v[216:217]
	v_lshlrev_b32_e32 v216, 16, v228
	v_and_b32_e32 v217, 0xffff0000, v228
	v_pk_add_f32 v[218:219], v[218:219], v[216:217]
	v_lshlrev_b32_e32 v216, 16, v229
	v_and_b32_e32 v217, 0xffff0000, v229
	v_pk_add_f32 v[220:221], v[220:221], v[216:217]
	ds_read_b128 v[226:229], v163 offset:3872
	s_waitcnt lgkmcnt(7)
	v_lshlrev_b32_e32 v216, 16, v230
	v_and_b32_e32 v217, 0xffff0000, v230
	v_pk_add_f32 v[106:107], v[106:107], v[216:217]
	v_lshlrev_b32_e32 v216, 16, v231
	v_and_b32_e32 v217, 0xffff0000, v231
	v_pk_add_f32 v[108:109], v[108:109], v[216:217]
	v_lshlrev_b32_e32 v216, 16, v232
	v_and_b32_e32 v217, 0xffff0000, v232
	v_pk_add_f32 v[218:219], v[218:219], v[216:217]
	v_lshlrev_b32_e32 v216, 16, v233
	v_and_b32_e32 v217, 0xffff0000, v233
	v_pk_add_f32 v[220:221], v[220:221], v[216:217]
	ds_read_b128 v[230:233], v163 offset:3600
	s_waitcnt lgkmcnt(7)
	v_lshlrev_b32_e32 v216, 16, v234
	v_and_b32_e32 v217, 0xffff0000, v234
	v_pk_add_f32 v[106:107], v[106:107], v[216:217]
	v_lshlrev_b32_e32 v216, 16, v235
	v_and_b32_e32 v217, 0xffff0000, v235
	v_pk_add_f32 v[108:109], v[108:109], v[216:217]
	v_lshlrev_b32_e32 v216, 16, v236
	v_and_b32_e32 v217, 0xffff0000, v236
	v_pk_add_f32 v[218:219], v[218:219], v[216:217]
	v_lshlrev_b32_e32 v216, 16, v237
	v_and_b32_e32 v217, 0xffff0000, v237
	v_pk_add_f32 v[220:221], v[220:221], v[216:217]
	ds_read_b128 v[234:237], v163 offset:3328
	s_waitcnt lgkmcnt(7)
	v_lshlrev_b32_e32 v216, 16, v238
	v_and_b32_e32 v217, 0xffff0000, v238
	v_pk_add_f32 v[106:107], v[106:107], v[216:217]
	v_lshlrev_b32_e32 v216, 16, v239
	v_and_b32_e32 v217, 0xffff0000, v239
	v_pk_add_f32 v[108:109], v[108:109], v[216:217]
	v_lshlrev_b32_e32 v216, 16, v240
	v_and_b32_e32 v217, 0xffff0000, v240
	v_pk_add_f32 v[218:219], v[218:219], v[216:217]
	v_lshlrev_b32_e32 v216, 16, v241
	v_and_b32_e32 v217, 0xffff0000, v241
	v_pk_add_f32 v[220:221], v[220:221], v[216:217]
	ds_read_b128 v[238:241], v163 offset:3056
	s_waitcnt lgkmcnt(7)
	v_lshlrev_b32_e32 v216, 16, v242
	v_and_b32_e32 v217, 0xffff0000, v242
	v_pk_add_f32 v[106:107], v[106:107], v[216:217]
	v_lshlrev_b32_e32 v216, 16, v243
	v_and_b32_e32 v217, 0xffff0000, v243
	v_pk_add_f32 v[108:109], v[108:109], v[216:217]
	v_lshlrev_b32_e32 v216, 16, v244
	v_and_b32_e32 v217, 0xffff0000, v244
	v_pk_add_f32 v[218:219], v[218:219], v[216:217]
	v_lshlrev_b32_e32 v216, 16, v245
	v_and_b32_e32 v217, 0xffff0000, v245
	v_pk_add_f32 v[220:221], v[220:221], v[216:217]
	ds_read_b128 v[242:245], v163 offset:2784
	s_waitcnt lgkmcnt(7)
	v_lshlrev_b32_e32 v216, 16, v248
	v_and_b32_e32 v217, 0xffff0000, v248
	v_pk_add_f32 v[106:107], v[106:107], v[216:217]
	v_lshlrev_b32_e32 v216, 16, v249
	v_and_b32_e32 v217, 0xffff0000, v249
	v_pk_add_f32 v[108:109], v[108:109], v[216:217]
	v_lshlrev_b32_e32 v216, 16, v250
	v_and_b32_e32 v217, 0xffff0000, v250
	v_pk_add_f32 v[218:219], v[218:219], v[216:217]
	v_lshlrev_b32_e32 v216, 16, v251
	v_and_b32_e32 v217, 0xffff0000, v251
	v_pk_add_f32 v[220:221], v[220:221], v[216:217]
	ds_read_b128 v[248:251], v163 offset:2512
	s_waitcnt lgkmcnt(7)
	v_lshlrev_b32_e32 v216, 16, v252
	v_and_b32_e32 v217, 0xffff0000, v252
	v_pk_add_f32 v[106:107], v[106:107], v[216:217]
	v_lshlrev_b32_e32 v216, 16, v253
	v_and_b32_e32 v217, 0xffff0000, v253
	v_pk_add_f32 v[108:109], v[108:109], v[216:217]
	v_lshlrev_b32_e32 v216, 16, v254
	v_and_b32_e32 v217, 0xffff0000, v254
	v_pk_add_f32 v[218:219], v[218:219], v[216:217]
	v_lshlrev_b32_e32 v216, 16, v255
	v_and_b32_e32 v217, 0xffff0000, v255
	v_pk_add_f32 v[220:221], v[220:221], v[216:217]
	ds_read_b128 v[252:255], v163 offset:2240
	v_fma_f32 v106, v159, v106, -v98
	v_fma_f32 v107, v159, v107, -v99
	v_fma_f32 v108, v159, v108, -v100
	v_fma_f32 v109, v159, v109, -v101
	v_fma_f32 v218, v159, v218, -v102
	v_fma_f32 v219, v159, v219, -v103
	v_fma_f32 v220, v159, v220, -v104
	v_fma_f32 v221, v159, v221, -v105
	v_cvt_pk_bf16_f32 v106, v106, v107
	v_cvt_pk_bf16_f32 v107, v108, v109
	v_cvt_pk_bf16_f32 v108, v218, v219
	v_cvt_pk_bf16_f32 v109, v220, v221
	s_and_saveexec_b64 s[28:29], s[6:7]
	s_cbranch_execz .Lpu0_1
	global_store_dwordx4 v[192:193], v[98:101], off offset:64
	global_store_dwordx4 v[192:193], v[102:105], off offset:80
.Lpu0_1:
	s_or_b64 exec, exec, s[28:29]
	s_waitcnt vmcnt(8)
	v_mfma_f32_32x32x16_bf16 v[2:17], v[106:109], v[82:85], v[2:17]
	v_mfma_f32_32x32x16_bf16 v[18:33], v[106:109], v[86:89], v[18:33]
	v_mfma_f32_32x32x16_bf16 v[34:49], v[106:109], v[90:93], v[34:49]
	v_mfma_f32_32x32x16_bf16 v[50:65], v[106:109], v[94:97], v[50:65]
	global_load_dwordx4 v[82:85], v[144:145], off offset:2048
	global_load_dwordx4 v[86:89], v[146:147], off offset:2048
	global_load_dwordx4 v[90:93], v[148:149], off offset:2048
	global_load_dwordx4 v[94:97], v[150:151], off offset:2048
	s_waitcnt lgkmcnt(7)
	v_lshlrev_b32_e32 v98, 16, v222
	v_and_b32_e32 v99, 0xffff0000, v222
	v_lshlrev_b32_e32 v100, 16, v223
	v_and_b32_e32 v101, 0xffff0000, v223
	v_lshlrev_b32_e32 v102, 16, v224
	v_and_b32_e32 v103, 0xffff0000, v224
	v_lshlrev_b32_e32 v104, 16, v225
	v_and_b32_e32 v105, 0xffff0000, v225
	ds_read_b128 v[222:225], v163 offset:1968
	s_waitcnt lgkmcnt(7)
	v_lshlrev_b32_e32 v216, 16, v226
	v_and_b32_e32 v217, 0xffff0000, v226
	v_pk_add_f32 v[106:107], v[98:99], v[216:217]
	v_lshlrev_b32_e32 v216, 16, v227
	v_and_b32_e32 v217, 0xffff0000, v227
	v_pk_add_f32 v[108:109], v[100:101], v[216:217]
	v_lshlrev_b32_e32 v216, 16, v228
	v_and_b32_e32 v217, 0xffff0000, v228
	v_pk_add_f32 v[218:219], v[102:103], v[216:217]
	v_lshlrev_b32_e32 v216, 16, v229
	v_and_b32_e32 v217, 0xffff0000, v229
	v_pk_add_f32 v[220:221], v[104:105], v[216:217]
	ds_read_b128 v[226:229], v163 offset:1696
	s_waitcnt lgkmcnt(7)
	v_lshlrev_b32_e32 v216, 16, v230
	v_and_b32_e32 v217, 0xffff0000, v230
	v_pk_add_f32 v[106:107], v[106:107], v[216:217]
	v_lshlrev_b32_e32 v216, 16, v231
	v_and_b32_e32 v217, 0xffff0000, v231
	v_pk_add_f32 v[108:109], v[108:109], v[216:217]
	v_lshlrev_b32_e32 v216, 16, v232
	v_and_b32_e32 v217, 0xffff0000, v232
	v_pk_add_f32 v[218:219], v[218:219], v[216:217]
	v_lshlrev_b32_e32 v216, 16, v233
	v_and_b32_e32 v217, 0xffff0000, v233
	v_pk_add_f32 v[220:221], v[220:221], v[216:217]
	ds_read_b128 v[230:233], v163 offset:1424
	s_waitcnt lgkmcnt(7)
	v_lshlrev_b32_e32 v216, 16, v234
	v_and_b32_e32 v217, 0xffff0000, v234
	v_pk_add_f32 v[106:107], v[106:107], v[216:217]
	v_lshlrev_b32_e32 v216, 16, v235
	v_and_b32_e32 v217, 0xffff0000, v235
	v_pk_add_f32 v[108:109], v[108:109], v[216:217]
	v_lshlrev_b32_e32 v216, 16, v236
	v_and_b32_e32 v217, 0xffff0000, v236
	v_pk_add_f32 v[218:219], v[218:219], v[216:217]
	v_lshlrev_b32_e32 v216, 16, v237
	v_and_b32_e32 v217, 0xffff0000, v237
	v_pk_add_f32 v[220:221], v[220:221], v[216:217]
	ds_read_b128 v[234:237], v163 offset:1152
	s_waitcnt lgkmcnt(7)
	v_lshlrev_b32_e32 v216, 16, v238
	v_and_b32_e32 v217, 0xffff0000, v238
	v_pk_add_f32 v[106:107], v[106:107], v[216:217]
	v_lshlrev_b32_e32 v216, 16, v239
	v_and_b32_e32 v217, 0xffff0000, v239
	v_pk_add_f32 v[108:109], v[108:109], v[216:217]
	v_lshlrev_b32_e32 v216, 16, v240
	v_and_b32_e32 v217, 0xffff0000, v240
	v_pk_add_f32 v[218:219], v[218:219], v[216:217]
	v_lshlrev_b32_e32 v216, 16, v241
	v_and_b32_e32 v217, 0xffff0000, v241
	v_pk_add_f32 v[220:221], v[220:221], v[216:217]
	ds_read_b128 v[238:241], v163 offset:880
	s_waitcnt lgkmcnt(7)
	v_lshlrev_b32_e32 v216, 16, v242
	v_and_b32_e32 v217, 0xffff0000, v242
	v_pk_add_f32 v[106:107], v[106:107], v[216:217]
	v_lshlrev_b32_e32 v216, 16, v243
	v_and_b32_e32 v217, 0xffff0000, v243
	v_pk_add_f32 v[108:109], v[108:109], v[216:217]
	v_lshlrev_b32_e32 v216, 16, v244
	v_and_b32_e32 v217, 0xffff0000, v244
	v_pk_add_f32 v[218:219], v[218:219], v[216:217]
	v_lshlrev_b32_e32 v216, 16, v245
	v_and_b32_e32 v217, 0xffff0000, v245
	v_pk_add_f32 v[220:221], v[220:221], v[216:217]
	ds_read_b128 v[242:245], v163 offset:608
	s_waitcnt lgkmcnt(7)
	v_lshlrev_b32_e32 v216, 16, v248
	v_and_b32_e32 v217, 0xffff0000, v248
	v_pk_add_f32 v[106:107], v[106:107], v[216:217]
	v_lshlrev_b32_e32 v216, 16, v249
	v_and_b32_e32 v217, 0xffff0000, v249
	v_pk_add_f32 v[108:109], v[108:109], v[216:217]
	v_lshlrev_b32_e32 v216, 16, v250
	v_and_b32_e32 v217, 0xffff0000, v250
	v_pk_add_f32 v[218:219], v[218:219], v[216:217]
	v_lshlrev_b32_e32 v216, 16, v251
	v_and_b32_e32 v217, 0xffff0000, v251
	v_pk_add_f32 v[220:221], v[220:221], v[216:217]
	ds_read_b128 v[248:251], v163 offset:336
	s_waitcnt lgkmcnt(7)
	v_lshlrev_b32_e32 v216, 16, v252
	v_and_b32_e32 v217, 0xffff0000, v252
	v_pk_add_f32 v[106:107], v[106:107], v[216:217]
	v_lshlrev_b32_e32 v216, 16, v253
	v_and_b32_e32 v217, 0xffff0000, v253
	v_pk_add_f32 v[108:109], v[108:109], v[216:217]
	v_lshlrev_b32_e32 v216, 16, v254
	v_and_b32_e32 v217, 0xffff0000, v254
	v_pk_add_f32 v[218:219], v[218:219], v[216:217]
	v_lshlrev_b32_e32 v216, 16, v255
	v_and_b32_e32 v217, 0xffff0000, v255
	v_pk_add_f32 v[220:221], v[220:221], v[216:217]
	ds_read_b128 v[252:255], v163 offset:64
	s_waitcnt lgkmcnt(7)
	v_lshlrev_b32_e32 v216, 16, v222
	v_and_b32_e32 v217, 0xffff0000, v222
	v_pk_add_f32 v[106:107], v[106:107], v[216:217]
	v_lshlrev_b32_e32 v216, 16, v223
	v_and_b32_e32 v217, 0xffff0000, v223
	v_pk_add_f32 v[108:109], v[108:109], v[216:217]
	v_lshlrev_b32_e32 v216, 16, v224
	v_and_b32_e32 v217, 0xffff0000, v224
	v_pk_add_f32 v[218:219], v[218:219], v[216:217]
	v_lshlrev_b32_e32 v216, 16, v225
	v_and_b32_e32 v217, 0xffff0000, v225
	v_pk_add_f32 v[220:221], v[220:221], v[216:217]
	ds_read_b128 v[222:225], v163 offset:4176
	s_waitcnt lgkmcnt(7)
	v_lshlrev_b32_e32 v216, 16, v226
	v_and_b32_e32 v217, 0xffff0000, v226
	v_pk_add_f32 v[106:107], v[106:107], v[216:217]
	v_lshlrev_b32_e32 v216, 16, v227
	v_and_b32_e32 v217, 0xffff0000, v227
	v_pk_add_f32 v[108:109], v[108:109], v[216:217]
	v_lshlrev_b32_e32 v216, 16, v228
	v_and_b32_e32 v217, 0xffff0000, v228
	v_pk_add_f32 v[218:219], v[218:219], v[216:217]
	v_lshlrev_b32_e32 v216, 16, v229
	v_and_b32_e32 v217, 0xffff0000, v229
	v_pk_add_f32 v[220:221], v[220:221], v[216:217]
	ds_read_b128 v[226:229], v163 offset:3904
	s_waitcnt lgkmcnt(7)
	v_lshlrev_b32_e32 v216, 16, v230
	v_and_b32_e32 v217, 0xffff0000, v230
	v_pk_add_f32 v[106:107], v[106:107], v[216:217]
	v_lshlrev_b32_e32 v216, 16, v231
	v_and_b32_e32 v217, 0xffff0000, v231
	v_pk_add_f32 v[108:109], v[108:109], v[216:217]
	v_lshlrev_b32_e32 v216, 16, v232
	v_and_b32_e32 v217, 0xffff0000, v232
	v_pk_add_f32 v[218:219], v[218:219], v[216:217]
	v_lshlrev_b32_e32 v216, 16, v233
	v_and_b32_e32 v217, 0xffff0000, v233
	v_pk_add_f32 v[220:221], v[220:221], v[216:217]
	ds_read_b128 v[230:233], v163 offset:3632
	s_waitcnt lgkmcnt(7)
	v_lshlrev_b32_e32 v216, 16, v234
	v_and_b32_e32 v217, 0xffff0000, v234
	v_pk_add_f32 v[106:107], v[106:107], v[216:217]
	v_lshlrev_b32_e32 v216, 16, v235
	v_and_b32_e32 v217, 0xffff0000, v235
	v_pk_add_f32 v[108:109], v[108:109], v[216:217]
	v_lshlrev_b32_e32 v216, 16, v236
	v_and_b32_e32 v217, 0xffff0000, v236
	v_pk_add_f32 v[218:219], v[218:219], v[216:217]
	v_lshlrev_b32_e32 v216, 16, v237
	v_and_b32_e32 v217, 0xffff0000, v237
	v_pk_add_f32 v[220:221], v[220:221], v[216:217]
	ds_read_b128 v[234:237], v163 offset:3360
	s_waitcnt lgkmcnt(7)
	v_lshlrev_b32_e32 v216, 16, v238
	v_and_b32_e32 v217, 0xffff0000, v238
	v_pk_add_f32 v[106:107], v[106:107], v[216:217]
	v_lshlrev_b32_e32 v216, 16, v239
	v_and_b32_e32 v217, 0xffff0000, v239
	v_pk_add_f32 v[108:109], v[108:109], v[216:217]
	v_lshlrev_b32_e32 v216, 16, v240
	v_and_b32_e32 v217, 0xffff0000, v240
	v_pk_add_f32 v[218:219], v[218:219], v[216:217]
	v_lshlrev_b32_e32 v216, 16, v241
	v_and_b32_e32 v217, 0xffff0000, v241
	v_pk_add_f32 v[220:221], v[220:221], v[216:217]
	ds_read_b128 v[238:241], v163 offset:3088
	s_waitcnt lgkmcnt(7)
	v_lshlrev_b32_e32 v216, 16, v242
	v_and_b32_e32 v217, 0xffff0000, v242
	v_pk_add_f32 v[106:107], v[106:107], v[216:217]
	v_lshlrev_b32_e32 v216, 16, v243
	v_and_b32_e32 v217, 0xffff0000, v243
	v_pk_add_f32 v[108:109], v[108:109], v[216:217]
	v_lshlrev_b32_e32 v216, 16, v244
	v_and_b32_e32 v217, 0xffff0000, v244
	v_pk_add_f32 v[218:219], v[218:219], v[216:217]
	v_lshlrev_b32_e32 v216, 16, v245
	v_and_b32_e32 v217, 0xffff0000, v245
	v_pk_add_f32 v[220:221], v[220:221], v[216:217]
	ds_read_b128 v[242:245], v163 offset:2816
	s_waitcnt lgkmcnt(7)
	v_lshlrev_b32_e32 v216, 16, v248
	v_and_b32_e32 v217, 0xffff0000, v248
	v_pk_add_f32 v[106:107], v[106:107], v[216:217]
	v_lshlrev_b32_e32 v216, 16, v249
	v_and_b32_e32 v217, 0xffff0000, v249
	v_pk_add_f32 v[108:109], v[108:109], v[216:217]
	v_lshlrev_b32_e32 v216, 16, v250
	v_and_b32_e32 v217, 0xffff0000, v250
	v_pk_add_f32 v[218:219], v[218:219], v[216:217]
	v_lshlrev_b32_e32 v216, 16, v251
	v_and_b32_e32 v217, 0xffff0000, v251
	v_pk_add_f32 v[220:221], v[220:221], v[216:217]
	ds_read_b128 v[248:251], v163 offset:2544
	s_waitcnt lgkmcnt(7)
	v_lshlrev_b32_e32 v216, 16, v252
	v_and_b32_e32 v217, 0xffff0000, v252
	v_pk_add_f32 v[106:107], v[106:107], v[216:217]
	v_lshlrev_b32_e32 v216, 16, v253
	v_and_b32_e32 v217, 0xffff0000, v253
	v_pk_add_f32 v[108:109], v[108:109], v[216:217]
	v_lshlrev_b32_e32 v216, 16, v254
	v_and_b32_e32 v217, 0xffff0000, v254
	v_pk_add_f32 v[218:219], v[218:219], v[216:217]
	v_lshlrev_b32_e32 v216, 16, v255
	v_and_b32_e32 v217, 0xffff0000, v255
	v_pk_add_f32 v[220:221], v[220:221], v[216:217]
	ds_read_b128 v[252:255], v163 offset:2272
	v_fma_f32 v106, v159, v106, -v98
	v_fma_f32 v107, v159, v107, -v99
	v_fma_f32 v108, v159, v108, -v100
	v_fma_f32 v109, v159, v109, -v101
	v_fma_f32 v218, v159, v218, -v102
	v_fma_f32 v219, v159, v219, -v103
	v_fma_f32 v220, v159, v220, -v104
	v_fma_f32 v221, v159, v221, -v105
	v_cvt_pk_bf16_f32 v106, v106, v107
	v_cvt_pk_bf16_f32 v107, v108, v109
	v_cvt_pk_bf16_f32 v108, v218, v219
	v_cvt_pk_bf16_f32 v109, v220, v221
	s_and_saveexec_b64 s[28:29], s[6:7]
	s_cbranch_execz .Lpu0_2
	global_store_dwordx4 v[192:193], v[98:101], off offset:128
	global_store_dwordx4 v[192:193], v[102:105], off offset:144
.Lpu0_2:
	s_or_b64 exec, exec, s[28:29]
	s_waitcnt vmcnt(8)
	v_mfma_f32_32x32x16_bf16 v[2:17], v[106:109], v[112:115], v[2:17]
	v_mfma_f32_32x32x16_bf16 v[18:33], v[106:109], v[116:119], v[18:33]
	v_mfma_f32_32x32x16_bf16 v[34:49], v[106:109], v[122:125], v[34:49]
	v_mfma_f32_32x32x16_bf16 v[50:65], v[106:109], v[126:129], v[50:65]
	global_load_dwordx4 v[112:115], v[144:145], off offset:2560
	global_load_dwordx4 v[116:119], v[146:147], off offset:2560
	global_load_dwordx4 v[122:125], v[148:149], off offset:2560
	global_load_dwordx4 v[126:129], v[150:151], off offset:2560
	s_waitcnt lgkmcnt(7)
	v_lshlrev_b32_e32 v98, 16, v222
	v_and_b32_e32 v99, 0xffff0000, v222
	v_lshlrev_b32_e32 v100, 16, v223
	v_and_b32_e32 v101, 0xffff0000, v223
	v_lshlrev_b32_e32 v102, 16, v224
	v_and_b32_e32 v103, 0xffff0000, v224
	v_lshlrev_b32_e32 v104, 16, v225
	v_and_b32_e32 v105, 0xffff0000, v225
	ds_read_b128 v[222:225], v163 offset:2000
	s_waitcnt lgkmcnt(7)
	v_lshlrev_b32_e32 v216, 16, v226
	v_and_b32_e32 v217, 0xffff0000, v226
	v_pk_add_f32 v[106:107], v[98:99], v[216:217]
	v_lshlrev_b32_e32 v216, 16, v227
	v_and_b32_e32 v217, 0xffff0000, v227
	v_pk_add_f32 v[108:109], v[100:101], v[216:217]
	v_lshlrev_b32_e32 v216, 16, v228
	v_and_b32_e32 v217, 0xffff0000, v228
	v_pk_add_f32 v[218:219], v[102:103], v[216:217]
	v_lshlrev_b32_e32 v216, 16, v229
	v_and_b32_e32 v217, 0xffff0000, v229
	v_pk_add_f32 v[220:221], v[104:105], v[216:217]
	ds_read_b128 v[226:229], v163 offset:1728
	s_waitcnt lgkmcnt(7)
	v_lshlrev_b32_e32 v216, 16, v230
	v_and_b32_e32 v217, 0xffff0000, v230
	v_pk_add_f32 v[106:107], v[106:107], v[216:217]
	v_lshlrev_b32_e32 v216, 16, v231
	v_and_b32_e32 v217, 0xffff0000, v231
	v_pk_add_f32 v[108:109], v[108:109], v[216:217]
	v_lshlrev_b32_e32 v216, 16, v232
	v_and_b32_e32 v217, 0xffff0000, v232
	v_pk_add_f32 v[218:219], v[218:219], v[216:217]
	v_lshlrev_b32_e32 v216, 16, v233
	v_and_b32_e32 v217, 0xffff0000, v233
	v_pk_add_f32 v[220:221], v[220:221], v[216:217]
	ds_read_b128 v[230:233], v163 offset:1456
	s_waitcnt lgkmcnt(7)
	v_lshlrev_b32_e32 v216, 16, v234
	v_and_b32_e32 v217, 0xffff0000, v234
	v_pk_add_f32 v[106:107], v[106:107], v[216:217]
	v_lshlrev_b32_e32 v216, 16, v235
	v_and_b32_e32 v217, 0xffff0000, v235
	v_pk_add_f32 v[108:109], v[108:109], v[216:217]
	v_lshlrev_b32_e32 v216, 16, v236
	v_and_b32_e32 v217, 0xffff0000, v236
	v_pk_add_f32 v[218:219], v[218:219], v[216:217]
	v_lshlrev_b32_e32 v216, 16, v237
	v_and_b32_e32 v217, 0xffff0000, v237
	v_pk_add_f32 v[220:221], v[220:221], v[216:217]
	ds_read_b128 v[234:237], v163 offset:1184
	s_waitcnt lgkmcnt(7)
	v_lshlrev_b32_e32 v216, 16, v238
	v_and_b32_e32 v217, 0xffff0000, v238
	v_pk_add_f32 v[106:107], v[106:107], v[216:217]
	v_lshlrev_b32_e32 v216, 16, v239
	v_and_b32_e32 v217, 0xffff0000, v239
	v_pk_add_f32 v[108:109], v[108:109], v[216:217]
	v_lshlrev_b32_e32 v216, 16, v240
	v_and_b32_e32 v217, 0xffff0000, v240
	v_pk_add_f32 v[218:219], v[218:219], v[216:217]
	v_lshlrev_b32_e32 v216, 16, v241
	v_and_b32_e32 v217, 0xffff0000, v241
	v_pk_add_f32 v[220:221], v[220:221], v[216:217]
	ds_read_b128 v[238:241], v163 offset:912
	s_waitcnt lgkmcnt(7)
	v_lshlrev_b32_e32 v216, 16, v242
	v_and_b32_e32 v217, 0xffff0000, v242
	v_pk_add_f32 v[106:107], v[106:107], v[216:217]
	v_lshlrev_b32_e32 v216, 16, v243
	v_and_b32_e32 v217, 0xffff0000, v243
	v_pk_add_f32 v[108:109], v[108:109], v[216:217]
	v_lshlrev_b32_e32 v216, 16, v244
	v_and_b32_e32 v217, 0xffff0000, v244
	v_pk_add_f32 v[218:219], v[218:219], v[216:217]
	v_lshlrev_b32_e32 v216, 16, v245
	v_and_b32_e32 v217, 0xffff0000, v245
	v_pk_add_f32 v[220:221], v[220:221], v[216:217]
	ds_read_b128 v[242:245], v163 offset:640
	s_waitcnt lgkmcnt(7)
	v_lshlrev_b32_e32 v216, 16, v248
	v_and_b32_e32 v217, 0xffff0000, v248
	v_pk_add_f32 v[106:107], v[106:107], v[216:217]
	v_lshlrev_b32_e32 v216, 16, v249
	v_and_b32_e32 v217, 0xffff0000, v249
	v_pk_add_f32 v[108:109], v[108:109], v[216:217]
	v_lshlrev_b32_e32 v216, 16, v250
	v_and_b32_e32 v217, 0xffff0000, v250
	v_pk_add_f32 v[218:219], v[218:219], v[216:217]
	v_lshlrev_b32_e32 v216, 16, v251
	v_and_b32_e32 v217, 0xffff0000, v251
	v_pk_add_f32 v[220:221], v[220:221], v[216:217]
	ds_read_b128 v[248:251], v163 offset:368
	s_waitcnt lgkmcnt(7)
	v_lshlrev_b32_e32 v216, 16, v252
	v_and_b32_e32 v217, 0xffff0000, v252
	v_pk_add_f32 v[106:107], v[106:107], v[216:217]
	v_lshlrev_b32_e32 v216, 16, v253
	v_and_b32_e32 v217, 0xffff0000, v253
	v_pk_add_f32 v[108:109], v[108:109], v[216:217]
	v_lshlrev_b32_e32 v216, 16, v254
	v_and_b32_e32 v217, 0xffff0000, v254
	v_pk_add_f32 v[218:219], v[218:219], v[216:217]
	v_lshlrev_b32_e32 v216, 16, v255
	v_and_b32_e32 v217, 0xffff0000, v255
	v_pk_add_f32 v[220:221], v[220:221], v[216:217]
	ds_read_b128 v[252:255], v163 offset:96
	s_waitcnt lgkmcnt(7)
	v_lshlrev_b32_e32 v216, 16, v222
	v_and_b32_e32 v217, 0xffff0000, v222
	v_pk_add_f32 v[106:107], v[106:107], v[216:217]
	v_lshlrev_b32_e32 v216, 16, v223
	v_and_b32_e32 v217, 0xffff0000, v223
	v_pk_add_f32 v[108:109], v[108:109], v[216:217]
	v_lshlrev_b32_e32 v216, 16, v224
	v_and_b32_e32 v217, 0xffff0000, v224
	v_pk_add_f32 v[218:219], v[218:219], v[216:217]
	v_lshlrev_b32_e32 v216, 16, v225
	v_and_b32_e32 v217, 0xffff0000, v225
	v_pk_add_f32 v[220:221], v[220:221], v[216:217]
	ds_read_b128 v[222:225], v163 offset:4208
	s_waitcnt lgkmcnt(7)
	v_lshlrev_b32_e32 v216, 16, v226
	v_and_b32_e32 v217, 0xffff0000, v226
	v_pk_add_f32 v[106:107], v[106:107], v[216:217]
	v_lshlrev_b32_e32 v216, 16, v227
	v_and_b32_e32 v217, 0xffff0000, v227
	v_pk_add_f32 v[108:109], v[108:109], v[216:217]
	v_lshlrev_b32_e32 v216, 16, v228
	v_and_b32_e32 v217, 0xffff0000, v228
	v_pk_add_f32 v[218:219], v[218:219], v[216:217]
	v_lshlrev_b32_e32 v216, 16, v229
	v_and_b32_e32 v217, 0xffff0000, v229
	v_pk_add_f32 v[220:221], v[220:221], v[216:217]
	ds_read_b128 v[226:229], v163 offset:3936
	s_waitcnt lgkmcnt(7)
	v_lshlrev_b32_e32 v216, 16, v230
	v_and_b32_e32 v217, 0xffff0000, v230
	v_pk_add_f32 v[106:107], v[106:107], v[216:217]
	v_lshlrev_b32_e32 v216, 16, v231
	v_and_b32_e32 v217, 0xffff0000, v231
	v_pk_add_f32 v[108:109], v[108:109], v[216:217]
	v_lshlrev_b32_e32 v216, 16, v232
	v_and_b32_e32 v217, 0xffff0000, v232
	v_pk_add_f32 v[218:219], v[218:219], v[216:217]
	v_lshlrev_b32_e32 v216, 16, v233
	v_and_b32_e32 v217, 0xffff0000, v233
	v_pk_add_f32 v[220:221], v[220:221], v[216:217]
	ds_read_b128 v[230:233], v163 offset:3664
	s_waitcnt lgkmcnt(7)
	v_lshlrev_b32_e32 v216, 16, v234
	v_and_b32_e32 v217, 0xffff0000, v234
	v_pk_add_f32 v[106:107], v[106:107], v[216:217]
	v_lshlrev_b32_e32 v216, 16, v235
	v_and_b32_e32 v217, 0xffff0000, v235
	v_pk_add_f32 v[108:109], v[108:109], v[216:217]
	v_lshlrev_b32_e32 v216, 16, v236
	v_and_b32_e32 v217, 0xffff0000, v236
	v_pk_add_f32 v[218:219], v[218:219], v[216:217]
	v_lshlrev_b32_e32 v216, 16, v237
	v_and_b32_e32 v217, 0xffff0000, v237
	v_pk_add_f32 v[220:221], v[220:221], v[216:217]
	ds_read_b128 v[234:237], v163 offset:3392
	s_waitcnt lgkmcnt(7)
	v_lshlrev_b32_e32 v216, 16, v238
	v_and_b32_e32 v217, 0xffff0000, v238
	v_pk_add_f32 v[106:107], v[106:107], v[216:217]
	v_lshlrev_b32_e32 v216, 16, v239
	v_and_b32_e32 v217, 0xffff0000, v239
	v_pk_add_f32 v[108:109], v[108:109], v[216:217]
	v_lshlrev_b32_e32 v216, 16, v240
	v_and_b32_e32 v217, 0xffff0000, v240
	v_pk_add_f32 v[218:219], v[218:219], v[216:217]
	v_lshlrev_b32_e32 v216, 16, v241
	v_and_b32_e32 v217, 0xffff0000, v241
	v_pk_add_f32 v[220:221], v[220:221], v[216:217]
	ds_read_b128 v[238:241], v163 offset:3120
	s_waitcnt lgkmcnt(7)
	v_lshlrev_b32_e32 v216, 16, v242
	v_and_b32_e32 v217, 0xffff0000, v242
	v_pk_add_f32 v[106:107], v[106:107], v[216:217]
	v_lshlrev_b32_e32 v216, 16, v243
	v_and_b32_e32 v217, 0xffff0000, v243
	v_pk_add_f32 v[108:109], v[108:109], v[216:217]
	v_lshlrev_b32_e32 v216, 16, v244
	v_and_b32_e32 v217, 0xffff0000, v244
	v_pk_add_f32 v[218:219], v[218:219], v[216:217]
	v_lshlrev_b32_e32 v216, 16, v245
	v_and_b32_e32 v217, 0xffff0000, v245
	v_pk_add_f32 v[220:221], v[220:221], v[216:217]
	ds_read_b128 v[242:245], v163 offset:2848
	s_waitcnt lgkmcnt(7)
	v_lshlrev_b32_e32 v216, 16, v248
	v_and_b32_e32 v217, 0xffff0000, v248
	v_pk_add_f32 v[106:107], v[106:107], v[216:217]
	v_lshlrev_b32_e32 v216, 16, v249
	v_and_b32_e32 v217, 0xffff0000, v249
	v_pk_add_f32 v[108:109], v[108:109], v[216:217]
	v_lshlrev_b32_e32 v216, 16, v250
	v_and_b32_e32 v217, 0xffff0000, v250
	v_pk_add_f32 v[218:219], v[218:219], v[216:217]
	v_lshlrev_b32_e32 v216, 16, v251
	v_and_b32_e32 v217, 0xffff0000, v251
	v_pk_add_f32 v[220:221], v[220:221], v[216:217]
	ds_read_b128 v[248:251], v163 offset:2576
	s_waitcnt lgkmcnt(7)
	v_lshlrev_b32_e32 v216, 16, v252
	v_and_b32_e32 v217, 0xffff0000, v252
	v_pk_add_f32 v[106:107], v[106:107], v[216:217]
	v_lshlrev_b32_e32 v216, 16, v253
	v_and_b32_e32 v217, 0xffff0000, v253
	v_pk_add_f32 v[108:109], v[108:109], v[216:217]
	v_lshlrev_b32_e32 v216, 16, v254
	v_and_b32_e32 v217, 0xffff0000, v254
	v_pk_add_f32 v[218:219], v[218:219], v[216:217]
	v_lshlrev_b32_e32 v216, 16, v255
	v_and_b32_e32 v217, 0xffff0000, v255
	v_pk_add_f32 v[220:221], v[220:221], v[216:217]
	ds_read_b128 v[252:255], v163 offset:2304
	v_fma_f32 v106, v159, v106, -v98
	v_fma_f32 v107, v159, v107, -v99
	v_fma_f32 v108, v159, v108, -v100
	v_fma_f32 v109, v159, v109, -v101
	v_fma_f32 v218, v159, v218, -v102
	v_fma_f32 v219, v159, v219, -v103
	v_fma_f32 v220, v159, v220, -v104
	v_fma_f32 v221, v159, v221, -v105
	v_cvt_pk_bf16_f32 v106, v106, v107
	v_cvt_pk_bf16_f32 v107, v108, v109
	v_cvt_pk_bf16_f32 v108, v218, v219
	v_cvt_pk_bf16_f32 v109, v220, v221
	s_and_saveexec_b64 s[28:29], s[6:7]
	s_cbranch_execz .Lpu0_3
	global_store_dwordx4 v[192:193], v[98:101], off offset:192
	global_store_dwordx4 v[192:193], v[102:105], off offset:208
.Lpu0_3:
	s_or_b64 exec, exec, s[28:29]
	s_waitcnt vmcnt(8)
	v_mfma_f32_32x32x16_bf16 v[2:17], v[106:109], v[70:73], v[2:17]
	v_mfma_f32_32x32x16_bf16 v[18:33], v[106:109], v[74:77], v[18:33]
	v_mfma_f32_32x32x16_bf16 v[34:49], v[106:109], v[78:81], v[34:49]
	v_mfma_f32_32x32x16_bf16 v[50:65], v[106:109], v[66:69], v[50:65]
	global_load_dwordx4 v[70:73], v[144:145], off offset:3072
	global_load_dwordx4 v[74:77], v[146:147], off offset:3072
	global_load_dwordx4 v[78:81], v[148:149], off offset:3072
	global_load_dwordx4 v[66:69], v[150:151], off offset:3072
	s_waitcnt lgkmcnt(7)
	v_lshlrev_b32_e32 v98, 16, v222
	v_and_b32_e32 v99, 0xffff0000, v222
	v_lshlrev_b32_e32 v100, 16, v223
	v_and_b32_e32 v101, 0xffff0000, v223
	v_lshlrev_b32_e32 v102, 16, v224
	v_and_b32_e32 v103, 0xffff0000, v224
	v_lshlrev_b32_e32 v104, 16, v225
	v_and_b32_e32 v105, 0xffff0000, v225
	ds_read_b128 v[222:225], v163 offset:2032
	s_waitcnt lgkmcnt(7)
	v_lshlrev_b32_e32 v216, 16, v226
	v_and_b32_e32 v217, 0xffff0000, v226
	v_pk_add_f32 v[106:107], v[98:99], v[216:217]
	v_lshlrev_b32_e32 v216, 16, v227
	v_and_b32_e32 v217, 0xffff0000, v227
	v_pk_add_f32 v[108:109], v[100:101], v[216:217]
	v_lshlrev_b32_e32 v216, 16, v228
	v_and_b32_e32 v217, 0xffff0000, v228
	v_pk_add_f32 v[218:219], v[102:103], v[216:217]
	v_lshlrev_b32_e32 v216, 16, v229
	v_and_b32_e32 v217, 0xffff0000, v229
	v_pk_add_f32 v[220:221], v[104:105], v[216:217]
	ds_read_b128 v[226:229], v163 offset:1760
	s_waitcnt lgkmcnt(7)
	v_lshlrev_b32_e32 v216, 16, v230
	v_and_b32_e32 v217, 0xffff0000, v230
	v_pk_add_f32 v[106:107], v[106:107], v[216:217]
	v_lshlrev_b32_e32 v216, 16, v231
	v_and_b32_e32 v217, 0xffff0000, v231
	v_pk_add_f32 v[108:109], v[108:109], v[216:217]
	v_lshlrev_b32_e32 v216, 16, v232
	v_and_b32_e32 v217, 0xffff0000, v232
	v_pk_add_f32 v[218:219], v[218:219], v[216:217]
	v_lshlrev_b32_e32 v216, 16, v233
	v_and_b32_e32 v217, 0xffff0000, v233
	v_pk_add_f32 v[220:221], v[220:221], v[216:217]
	ds_read_b128 v[230:233], v163 offset:1488
	s_waitcnt lgkmcnt(7)
	v_lshlrev_b32_e32 v216, 16, v234
	v_and_b32_e32 v217, 0xffff0000, v234
	v_pk_add_f32 v[106:107], v[106:107], v[216:217]
	v_lshlrev_b32_e32 v216, 16, v235
	v_and_b32_e32 v217, 0xffff0000, v235
	v_pk_add_f32 v[108:109], v[108:109], v[216:217]
	v_lshlrev_b32_e32 v216, 16, v236
	v_and_b32_e32 v217, 0xffff0000, v236
	v_pk_add_f32 v[218:219], v[218:219], v[216:217]
	v_lshlrev_b32_e32 v216, 16, v237
	v_and_b32_e32 v217, 0xffff0000, v237
	v_pk_add_f32 v[220:221], v[220:221], v[216:217]
	ds_read_b128 v[234:237], v163 offset:1216
	s_waitcnt lgkmcnt(7)
	v_lshlrev_b32_e32 v216, 16, v238
	v_and_b32_e32 v217, 0xffff0000, v238
	v_pk_add_f32 v[106:107], v[106:107], v[216:217]
	v_lshlrev_b32_e32 v216, 16, v239
	v_and_b32_e32 v217, 0xffff0000, v239
	v_pk_add_f32 v[108:109], v[108:109], v[216:217]
	v_lshlrev_b32_e32 v216, 16, v240
	v_and_b32_e32 v217, 0xffff0000, v240
	v_pk_add_f32 v[218:219], v[218:219], v[216:217]
	v_lshlrev_b32_e32 v216, 16, v241
	v_and_b32_e32 v217, 0xffff0000, v241
	v_pk_add_f32 v[220:221], v[220:221], v[216:217]
	ds_read_b128 v[238:241], v163 offset:944
	s_waitcnt lgkmcnt(7)
	v_lshlrev_b32_e32 v216, 16, v242
	v_and_b32_e32 v217, 0xffff0000, v242
	v_pk_add_f32 v[106:107], v[106:107], v[216:217]
	v_lshlrev_b32_e32 v216, 16, v243
	v_and_b32_e32 v217, 0xffff0000, v243
	v_pk_add_f32 v[108:109], v[108:109], v[216:217]
	v_lshlrev_b32_e32 v216, 16, v244
	v_and_b32_e32 v217, 0xffff0000, v244
	v_pk_add_f32 v[218:219], v[218:219], v[216:217]
	v_lshlrev_b32_e32 v216, 16, v245
	v_and_b32_e32 v217, 0xffff0000, v245
	v_pk_add_f32 v[220:221], v[220:221], v[216:217]
	ds_read_b128 v[242:245], v163 offset:672
	s_waitcnt lgkmcnt(7)
	v_lshlrev_b32_e32 v216, 16, v248
	v_and_b32_e32 v217, 0xffff0000, v248
	v_pk_add_f32 v[106:107], v[106:107], v[216:217]
	v_lshlrev_b32_e32 v216, 16, v249
	v_and_b32_e32 v217, 0xffff0000, v249
	v_pk_add_f32 v[108:109], v[108:109], v[216:217]
	v_lshlrev_b32_e32 v216, 16, v250
	v_and_b32_e32 v217, 0xffff0000, v250
	v_pk_add_f32 v[218:219], v[218:219], v[216:217]
	v_lshlrev_b32_e32 v216, 16, v251
	v_and_b32_e32 v217, 0xffff0000, v251
	v_pk_add_f32 v[220:221], v[220:221], v[216:217]
	ds_read_b128 v[248:251], v163 offset:400
	s_waitcnt lgkmcnt(7)
	v_lshlrev_b32_e32 v216, 16, v252
	v_and_b32_e32 v217, 0xffff0000, v252
	v_pk_add_f32 v[106:107], v[106:107], v[216:217]
	v_lshlrev_b32_e32 v216, 16, v253
	v_and_b32_e32 v217, 0xffff0000, v253
	v_pk_add_f32 v[108:109], v[108:109], v[216:217]
	v_lshlrev_b32_e32 v216, 16, v254
	v_and_b32_e32 v217, 0xffff0000, v254
	v_pk_add_f32 v[218:219], v[218:219], v[216:217]
	v_lshlrev_b32_e32 v216, 16, v255
	v_and_b32_e32 v217, 0xffff0000, v255
	v_pk_add_f32 v[220:221], v[220:221], v[216:217]
	ds_read_b128 v[252:255], v163 offset:128
	s_waitcnt lgkmcnt(7)
	v_lshlrev_b32_e32 v216, 16, v222
	v_and_b32_e32 v217, 0xffff0000, v222
	v_pk_add_f32 v[106:107], v[106:107], v[216:217]
	v_lshlrev_b32_e32 v216, 16, v223
	v_and_b32_e32 v217, 0xffff0000, v223
	v_pk_add_f32 v[108:109], v[108:109], v[216:217]
	v_lshlrev_b32_e32 v216, 16, v224
	v_and_b32_e32 v217, 0xffff0000, v224
	v_pk_add_f32 v[218:219], v[218:219], v[216:217]
	v_lshlrev_b32_e32 v216, 16, v225
	v_and_b32_e32 v217, 0xffff0000, v225
	v_pk_add_f32 v[220:221], v[220:221], v[216:217]
	ds_read_b128 v[222:225], v163 offset:4240
	s_waitcnt lgkmcnt(7)
	v_lshlrev_b32_e32 v216, 16, v226
	v_and_b32_e32 v217, 0xffff0000, v226
	v_pk_add_f32 v[106:107], v[106:107], v[216:217]
	v_lshlrev_b32_e32 v216, 16, v227
	v_and_b32_e32 v217, 0xffff0000, v227
	v_pk_add_f32 v[108:109], v[108:109], v[216:217]
	v_lshlrev_b32_e32 v216, 16, v228
	v_and_b32_e32 v217, 0xffff0000, v228
	v_pk_add_f32 v[218:219], v[218:219], v[216:217]
	v_lshlrev_b32_e32 v216, 16, v229
	v_and_b32_e32 v217, 0xffff0000, v229
	v_pk_add_f32 v[220:221], v[220:221], v[216:217]
	ds_read_b128 v[226:229], v163 offset:3968
	s_waitcnt lgkmcnt(7)
	v_lshlrev_b32_e32 v216, 16, v230
	v_and_b32_e32 v217, 0xffff0000, v230
	v_pk_add_f32 v[106:107], v[106:107], v[216:217]
	v_lshlrev_b32_e32 v216, 16, v231
	v_and_b32_e32 v217, 0xffff0000, v231
	v_pk_add_f32 v[108:109], v[108:109], v[216:217]
	v_lshlrev_b32_e32 v216, 16, v232
	v_and_b32_e32 v217, 0xffff0000, v232
	v_pk_add_f32 v[218:219], v[218:219], v[216:217]
	v_lshlrev_b32_e32 v216, 16, v233
	v_and_b32_e32 v217, 0xffff0000, v233
	v_pk_add_f32 v[220:221], v[220:221], v[216:217]
	ds_read_b128 v[230:233], v163 offset:3696
	s_waitcnt lgkmcnt(7)
	v_lshlrev_b32_e32 v216, 16, v234
	v_and_b32_e32 v217, 0xffff0000, v234
	v_pk_add_f32 v[106:107], v[106:107], v[216:217]
	v_lshlrev_b32_e32 v216, 16, v235
	v_and_b32_e32 v217, 0xffff0000, v235
	v_pk_add_f32 v[108:109], v[108:109], v[216:217]
	v_lshlrev_b32_e32 v216, 16, v236
	v_and_b32_e32 v217, 0xffff0000, v236
	v_pk_add_f32 v[218:219], v[218:219], v[216:217]
	v_lshlrev_b32_e32 v216, 16, v237
	v_and_b32_e32 v217, 0xffff0000, v237
	v_pk_add_f32 v[220:221], v[220:221], v[216:217]
	ds_read_b128 v[234:237], v163 offset:3424
	s_waitcnt lgkmcnt(7)
	v_lshlrev_b32_e32 v216, 16, v238
	v_and_b32_e32 v217, 0xffff0000, v238
	v_pk_add_f32 v[106:107], v[106:107], v[216:217]
	v_lshlrev_b32_e32 v216, 16, v239
	v_and_b32_e32 v217, 0xffff0000, v239
	v_pk_add_f32 v[108:109], v[108:109], v[216:217]
	v_lshlrev_b32_e32 v216, 16, v240
	v_and_b32_e32 v217, 0xffff0000, v240
	v_pk_add_f32 v[218:219], v[218:219], v[216:217]
	v_lshlrev_b32_e32 v216, 16, v241
	v_and_b32_e32 v217, 0xffff0000, v241
	v_pk_add_f32 v[220:221], v[220:221], v[216:217]
	ds_read_b128 v[238:241], v163 offset:3152
	s_waitcnt lgkmcnt(7)
	v_lshlrev_b32_e32 v216, 16, v242
	v_and_b32_e32 v217, 0xffff0000, v242
	v_pk_add_f32 v[106:107], v[106:107], v[216:217]
	v_lshlrev_b32_e32 v216, 16, v243
	v_and_b32_e32 v217, 0xffff0000, v243
	v_pk_add_f32 v[108:109], v[108:109], v[216:217]
	v_lshlrev_b32_e32 v216, 16, v244
	v_and_b32_e32 v217, 0xffff0000, v244
	v_pk_add_f32 v[218:219], v[218:219], v[216:217]
	v_lshlrev_b32_e32 v216, 16, v245
	v_and_b32_e32 v217, 0xffff0000, v245
	v_pk_add_f32 v[220:221], v[220:221], v[216:217]
	ds_read_b128 v[242:245], v163 offset:2880
	s_waitcnt lgkmcnt(7)
	v_lshlrev_b32_e32 v216, 16, v248
	v_and_b32_e32 v217, 0xffff0000, v248
	v_pk_add_f32 v[106:107], v[106:107], v[216:217]
	v_lshlrev_b32_e32 v216, 16, v249
	v_and_b32_e32 v217, 0xffff0000, v249
	v_pk_add_f32 v[108:109], v[108:109], v[216:217]
	v_lshlrev_b32_e32 v216, 16, v250
	v_and_b32_e32 v217, 0xffff0000, v250
	v_pk_add_f32 v[218:219], v[218:219], v[216:217]
	v_lshlrev_b32_e32 v216, 16, v251
	v_and_b32_e32 v217, 0xffff0000, v251
	v_pk_add_f32 v[220:221], v[220:221], v[216:217]
	ds_read_b128 v[248:251], v163 offset:2608
	s_waitcnt lgkmcnt(7)
	v_lshlrev_b32_e32 v216, 16, v252
	v_and_b32_e32 v217, 0xffff0000, v252
	v_pk_add_f32 v[106:107], v[106:107], v[216:217]
	v_lshlrev_b32_e32 v216, 16, v253
	v_and_b32_e32 v217, 0xffff0000, v253
	v_pk_add_f32 v[108:109], v[108:109], v[216:217]
	v_lshlrev_b32_e32 v216, 16, v254
	v_and_b32_e32 v217, 0xffff0000, v254
	v_pk_add_f32 v[218:219], v[218:219], v[216:217]
	v_lshlrev_b32_e32 v216, 16, v255
	v_and_b32_e32 v217, 0xffff0000, v255
	v_pk_add_f32 v[220:221], v[220:221], v[216:217]
	ds_read_b128 v[252:255], v163 offset:2336
	v_fma_f32 v106, v159, v106, -v98
	v_fma_f32 v107, v159, v107, -v99
	v_fma_f32 v108, v159, v108, -v100
	v_fma_f32 v109, v159, v109, -v101
	v_fma_f32 v218, v159, v218, -v102
	v_fma_f32 v219, v159, v219, -v103
	v_fma_f32 v220, v159, v220, -v104
	v_fma_f32 v221, v159, v221, -v105
	v_cvt_pk_bf16_f32 v106, v106, v107
	v_cvt_pk_bf16_f32 v107, v108, v109
	v_cvt_pk_bf16_f32 v108, v218, v219
	v_cvt_pk_bf16_f32 v109, v220, v221
	s_and_saveexec_b64 s[28:29], s[6:7]
	s_cbranch_execz .Lpu0_4
	global_store_dwordx4 v[192:193], v[98:101], off offset:256
	global_store_dwordx4 v[192:193], v[102:105], off offset:272
.Lpu0_4:
	s_or_b64 exec, exec, s[28:29]
	s_waitcnt vmcnt(8)
	v_mfma_f32_32x32x16_bf16 v[2:17], v[106:109], v[82:85], v[2:17]
	v_mfma_f32_32x32x16_bf16 v[18:33], v[106:109], v[86:89], v[18:33]
	v_mfma_f32_32x32x16_bf16 v[34:49], v[106:109], v[90:93], v[34:49]
	v_mfma_f32_32x32x16_bf16 v[50:65], v[106:109], v[94:97], v[50:65]
	global_load_dwordx4 v[82:85], v[144:145], off offset:3584
	global_load_dwordx4 v[86:89], v[146:147], off offset:3584
	global_load_dwordx4 v[90:93], v[148:149], off offset:3584
	global_load_dwordx4 v[94:97], v[150:151], off offset:3584
	s_waitcnt lgkmcnt(7)
	v_lshlrev_b32_e32 v98, 16, v222
	v_and_b32_e32 v99, 0xffff0000, v222
	v_lshlrev_b32_e32 v100, 16, v223
	v_and_b32_e32 v101, 0xffff0000, v223
	v_lshlrev_b32_e32 v102, 16, v224
	v_and_b32_e32 v103, 0xffff0000, v224
	v_lshlrev_b32_e32 v104, 16, v225
	v_and_b32_e32 v105, 0xffff0000, v225
	ds_read_b128 v[222:225], v163 offset:2064
	s_waitcnt lgkmcnt(7)
	v_lshlrev_b32_e32 v216, 16, v226
	v_and_b32_e32 v217, 0xffff0000, v226
	v_pk_add_f32 v[106:107], v[98:99], v[216:217]
	v_lshlrev_b32_e32 v216, 16, v227
	v_and_b32_e32 v217, 0xffff0000, v227
	v_pk_add_f32 v[108:109], v[100:101], v[216:217]
	v_lshlrev_b32_e32 v216, 16, v228
	v_and_b32_e32 v217, 0xffff0000, v228
	v_pk_add_f32 v[218:219], v[102:103], v[216:217]
	v_lshlrev_b32_e32 v216, 16, v229
	v_and_b32_e32 v217, 0xffff0000, v229
	v_pk_add_f32 v[220:221], v[104:105], v[216:217]
	ds_read_b128 v[226:229], v163 offset:1792
	s_waitcnt lgkmcnt(7)
	v_lshlrev_b32_e32 v216, 16, v230
	v_and_b32_e32 v217, 0xffff0000, v230
	v_pk_add_f32 v[106:107], v[106:107], v[216:217]
	v_lshlrev_b32_e32 v216, 16, v231
	v_and_b32_e32 v217, 0xffff0000, v231
	v_pk_add_f32 v[108:109], v[108:109], v[216:217]
	v_lshlrev_b32_e32 v216, 16, v232
	v_and_b32_e32 v217, 0xffff0000, v232
	v_pk_add_f32 v[218:219], v[218:219], v[216:217]
	v_lshlrev_b32_e32 v216, 16, v233
	v_and_b32_e32 v217, 0xffff0000, v233
	v_pk_add_f32 v[220:221], v[220:221], v[216:217]
	ds_read_b128 v[230:233], v163 offset:1520
	s_waitcnt lgkmcnt(7)
	v_lshlrev_b32_e32 v216, 16, v234
	v_and_b32_e32 v217, 0xffff0000, v234
	v_pk_add_f32 v[106:107], v[106:107], v[216:217]
	v_lshlrev_b32_e32 v216, 16, v235
	v_and_b32_e32 v217, 0xffff0000, v235
	v_pk_add_f32 v[108:109], v[108:109], v[216:217]
	v_lshlrev_b32_e32 v216, 16, v236
	v_and_b32_e32 v217, 0xffff0000, v236
	v_pk_add_f32 v[218:219], v[218:219], v[216:217]
	v_lshlrev_b32_e32 v216, 16, v237
	v_and_b32_e32 v217, 0xffff0000, v237
	v_pk_add_f32 v[220:221], v[220:221], v[216:217]
	ds_read_b128 v[234:237], v163 offset:1248
	s_waitcnt lgkmcnt(7)
	v_lshlrev_b32_e32 v216, 16, v238
	v_and_b32_e32 v217, 0xffff0000, v238
	v_pk_add_f32 v[106:107], v[106:107], v[216:217]
	v_lshlrev_b32_e32 v216, 16, v239
	v_and_b32_e32 v217, 0xffff0000, v239
	v_pk_add_f32 v[108:109], v[108:109], v[216:217]
	v_lshlrev_b32_e32 v216, 16, v240
	v_and_b32_e32 v217, 0xffff0000, v240
	v_pk_add_f32 v[218:219], v[218:219], v[216:217]
	v_lshlrev_b32_e32 v216, 16, v241
	v_and_b32_e32 v217, 0xffff0000, v241
	v_pk_add_f32 v[220:221], v[220:221], v[216:217]
	ds_read_b128 v[238:241], v163 offset:976
	s_waitcnt lgkmcnt(7)
	v_lshlrev_b32_e32 v216, 16, v242
	v_and_b32_e32 v217, 0xffff0000, v242
	v_pk_add_f32 v[106:107], v[106:107], v[216:217]
	v_lshlrev_b32_e32 v216, 16, v243
	v_and_b32_e32 v217, 0xffff0000, v243
	v_pk_add_f32 v[108:109], v[108:109], v[216:217]
	v_lshlrev_b32_e32 v216, 16, v244
	v_and_b32_e32 v217, 0xffff0000, v244
	v_pk_add_f32 v[218:219], v[218:219], v[216:217]
	v_lshlrev_b32_e32 v216, 16, v245
	v_and_b32_e32 v217, 0xffff0000, v245
	v_pk_add_f32 v[220:221], v[220:221], v[216:217]
	ds_read_b128 v[242:245], v163 offset:704
	s_waitcnt lgkmcnt(7)
	v_lshlrev_b32_e32 v216, 16, v248
	v_and_b32_e32 v217, 0xffff0000, v248
	v_pk_add_f32 v[106:107], v[106:107], v[216:217]
	v_lshlrev_b32_e32 v216, 16, v249
	v_and_b32_e32 v217, 0xffff0000, v249
	v_pk_add_f32 v[108:109], v[108:109], v[216:217]
	v_lshlrev_b32_e32 v216, 16, v250
	v_and_b32_e32 v217, 0xffff0000, v250
	v_pk_add_f32 v[218:219], v[218:219], v[216:217]
	v_lshlrev_b32_e32 v216, 16, v251
	v_and_b32_e32 v217, 0xffff0000, v251
	v_pk_add_f32 v[220:221], v[220:221], v[216:217]
	ds_read_b128 v[248:251], v163 offset:432
	s_waitcnt lgkmcnt(7)
	v_lshlrev_b32_e32 v216, 16, v252
	v_and_b32_e32 v217, 0xffff0000, v252
	v_pk_add_f32 v[106:107], v[106:107], v[216:217]
	v_lshlrev_b32_e32 v216, 16, v253
	v_and_b32_e32 v217, 0xffff0000, v253
	v_pk_add_f32 v[108:109], v[108:109], v[216:217]
	v_lshlrev_b32_e32 v216, 16, v254
	v_and_b32_e32 v217, 0xffff0000, v254
	v_pk_add_f32 v[218:219], v[218:219], v[216:217]
	v_lshlrev_b32_e32 v216, 16, v255
	v_and_b32_e32 v217, 0xffff0000, v255
	v_pk_add_f32 v[220:221], v[220:221], v[216:217]
	ds_read_b128 v[252:255], v163 offset:160
	s_waitcnt lgkmcnt(7)
	v_lshlrev_b32_e32 v216, 16, v222
	v_and_b32_e32 v217, 0xffff0000, v222
	v_pk_add_f32 v[106:107], v[106:107], v[216:217]
	v_lshlrev_b32_e32 v216, 16, v223
	v_and_b32_e32 v217, 0xffff0000, v223
	v_pk_add_f32 v[108:109], v[108:109], v[216:217]
	v_lshlrev_b32_e32 v216, 16, v224
	v_and_b32_e32 v217, 0xffff0000, v224
	v_pk_add_f32 v[218:219], v[218:219], v[216:217]
	v_lshlrev_b32_e32 v216, 16, v225
	v_and_b32_e32 v217, 0xffff0000, v225
	v_pk_add_f32 v[220:221], v[220:221], v[216:217]
	ds_read_b128 v[222:225], v163 offset:4272
	s_waitcnt lgkmcnt(7)
	v_lshlrev_b32_e32 v216, 16, v226
	v_and_b32_e32 v217, 0xffff0000, v226
	v_pk_add_f32 v[106:107], v[106:107], v[216:217]
	v_lshlrev_b32_e32 v216, 16, v227
	v_and_b32_e32 v217, 0xffff0000, v227
	v_pk_add_f32 v[108:109], v[108:109], v[216:217]
	v_lshlrev_b32_e32 v216, 16, v228
	v_and_b32_e32 v217, 0xffff0000, v228
	v_pk_add_f32 v[218:219], v[218:219], v[216:217]
	v_lshlrev_b32_e32 v216, 16, v229
	v_and_b32_e32 v217, 0xffff0000, v229
	v_pk_add_f32 v[220:221], v[220:221], v[216:217]
	ds_read_b128 v[226:229], v163 offset:4000
	s_waitcnt lgkmcnt(7)
	v_lshlrev_b32_e32 v216, 16, v230
	v_and_b32_e32 v217, 0xffff0000, v230
	v_pk_add_f32 v[106:107], v[106:107], v[216:217]
	v_lshlrev_b32_e32 v216, 16, v231
	v_and_b32_e32 v217, 0xffff0000, v231
	v_pk_add_f32 v[108:109], v[108:109], v[216:217]
	v_lshlrev_b32_e32 v216, 16, v232
	v_and_b32_e32 v217, 0xffff0000, v232
	v_pk_add_f32 v[218:219], v[218:219], v[216:217]
	v_lshlrev_b32_e32 v216, 16, v233
	v_and_b32_e32 v217, 0xffff0000, v233
	v_pk_add_f32 v[220:221], v[220:221], v[216:217]
	ds_read_b128 v[230:233], v163 offset:3728
	s_waitcnt lgkmcnt(7)
	v_lshlrev_b32_e32 v216, 16, v234
	v_and_b32_e32 v217, 0xffff0000, v234
	v_pk_add_f32 v[106:107], v[106:107], v[216:217]
	v_lshlrev_b32_e32 v216, 16, v235
	v_and_b32_e32 v217, 0xffff0000, v235
	v_pk_add_f32 v[108:109], v[108:109], v[216:217]
	v_lshlrev_b32_e32 v216, 16, v236
	v_and_b32_e32 v217, 0xffff0000, v236
	v_pk_add_f32 v[218:219], v[218:219], v[216:217]
	v_lshlrev_b32_e32 v216, 16, v237
	v_and_b32_e32 v217, 0xffff0000, v237
	v_pk_add_f32 v[220:221], v[220:221], v[216:217]
	ds_read_b128 v[234:237], v163 offset:3456
	s_waitcnt lgkmcnt(7)
	v_lshlrev_b32_e32 v216, 16, v238
	v_and_b32_e32 v217, 0xffff0000, v238
	v_pk_add_f32 v[106:107], v[106:107], v[216:217]
	v_lshlrev_b32_e32 v216, 16, v239
	v_and_b32_e32 v217, 0xffff0000, v239
	v_pk_add_f32 v[108:109], v[108:109], v[216:217]
	v_lshlrev_b32_e32 v216, 16, v240
	v_and_b32_e32 v217, 0xffff0000, v240
	v_pk_add_f32 v[218:219], v[218:219], v[216:217]
	v_lshlrev_b32_e32 v216, 16, v241
	v_and_b32_e32 v217, 0xffff0000, v241
	v_pk_add_f32 v[220:221], v[220:221], v[216:217]
	ds_read_b128 v[238:241], v163 offset:3184
	s_waitcnt lgkmcnt(7)
	v_lshlrev_b32_e32 v216, 16, v242
	v_and_b32_e32 v217, 0xffff0000, v242
	v_pk_add_f32 v[106:107], v[106:107], v[216:217]
	v_lshlrev_b32_e32 v216, 16, v243
	v_and_b32_e32 v217, 0xffff0000, v243
	v_pk_add_f32 v[108:109], v[108:109], v[216:217]
	v_lshlrev_b32_e32 v216, 16, v244
	v_and_b32_e32 v217, 0xffff0000, v244
	v_pk_add_f32 v[218:219], v[218:219], v[216:217]
	v_lshlrev_b32_e32 v216, 16, v245
	v_and_b32_e32 v217, 0xffff0000, v245
	v_pk_add_f32 v[220:221], v[220:221], v[216:217]
	ds_read_b128 v[242:245], v163 offset:2912
	s_waitcnt lgkmcnt(7)
	v_lshlrev_b32_e32 v216, 16, v248
	v_and_b32_e32 v217, 0xffff0000, v248
	v_pk_add_f32 v[106:107], v[106:107], v[216:217]
	v_lshlrev_b32_e32 v216, 16, v249
	v_and_b32_e32 v217, 0xffff0000, v249
	v_pk_add_f32 v[108:109], v[108:109], v[216:217]
	v_lshlrev_b32_e32 v216, 16, v250
	v_and_b32_e32 v217, 0xffff0000, v250
	v_pk_add_f32 v[218:219], v[218:219], v[216:217]
	v_lshlrev_b32_e32 v216, 16, v251
	v_and_b32_e32 v217, 0xffff0000, v251
	v_pk_add_f32 v[220:221], v[220:221], v[216:217]
	ds_read_b128 v[248:251], v163 offset:2640
	s_waitcnt lgkmcnt(7)
	v_lshlrev_b32_e32 v216, 16, v252
	v_and_b32_e32 v217, 0xffff0000, v252
	v_pk_add_f32 v[106:107], v[106:107], v[216:217]
	v_lshlrev_b32_e32 v216, 16, v253
	v_and_b32_e32 v217, 0xffff0000, v253
	v_pk_add_f32 v[108:109], v[108:109], v[216:217]
	v_lshlrev_b32_e32 v216, 16, v254
	v_and_b32_e32 v217, 0xffff0000, v254
	v_pk_add_f32 v[218:219], v[218:219], v[216:217]
	v_lshlrev_b32_e32 v216, 16, v255
	v_and_b32_e32 v217, 0xffff0000, v255
	v_pk_add_f32 v[220:221], v[220:221], v[216:217]
	ds_read_b128 v[252:255], v163 offset:2368
	v_fma_f32 v106, v159, v106, -v98
	v_fma_f32 v107, v159, v107, -v99
	v_fma_f32 v108, v159, v108, -v100
	v_fma_f32 v109, v159, v109, -v101
	v_fma_f32 v218, v159, v218, -v102
	v_fma_f32 v219, v159, v219, -v103
	v_fma_f32 v220, v159, v220, -v104
	v_fma_f32 v221, v159, v221, -v105
	v_cvt_pk_bf16_f32 v106, v106, v107
	v_cvt_pk_bf16_f32 v107, v108, v109
	v_cvt_pk_bf16_f32 v108, v218, v219
	v_cvt_pk_bf16_f32 v109, v220, v221
	s_and_saveexec_b64 s[28:29], s[6:7]
	s_cbranch_execz .Lpu0_5
	global_store_dwordx4 v[192:193], v[98:101], off offset:320
	global_store_dwordx4 v[192:193], v[102:105], off offset:336
.Lpu0_5:
	s_or_b64 exec, exec, s[28:29]
	s_waitcnt vmcnt(8)
	v_mfma_f32_32x32x16_bf16 v[2:17], v[106:109], v[112:115], v[2:17]
	v_mfma_f32_32x32x16_bf16 v[18:33], v[106:109], v[116:119], v[18:33]
	v_mfma_f32_32x32x16_bf16 v[34:49], v[106:109], v[122:125], v[34:49]
	v_mfma_f32_32x32x16_bf16 v[50:65], v[106:109], v[126:129], v[50:65]
	s_waitcnt lgkmcnt(7)
	v_lshlrev_b32_e32 v98, 16, v222
	v_and_b32_e32 v99, 0xffff0000, v222
	v_lshlrev_b32_e32 v100, 16, v223
	v_and_b32_e32 v101, 0xffff0000, v223
	v_lshlrev_b32_e32 v102, 16, v224
	v_and_b32_e32 v103, 0xffff0000, v224
	v_lshlrev_b32_e32 v104, 16, v225
	v_and_b32_e32 v105, 0xffff0000, v225
	ds_read_b128 v[222:225], v163 offset:2096
	s_waitcnt lgkmcnt(7)
	v_lshlrev_b32_e32 v216, 16, v226
	v_and_b32_e32 v217, 0xffff0000, v226
	v_pk_add_f32 v[106:107], v[98:99], v[216:217]
	v_lshlrev_b32_e32 v216, 16, v227
	v_and_b32_e32 v217, 0xffff0000, v227
	v_pk_add_f32 v[108:109], v[100:101], v[216:217]
	v_lshlrev_b32_e32 v216, 16, v228
	v_and_b32_e32 v217, 0xffff0000, v228
	v_pk_add_f32 v[218:219], v[102:103], v[216:217]
	v_lshlrev_b32_e32 v216, 16, v229
	v_and_b32_e32 v217, 0xffff0000, v229
	v_pk_add_f32 v[220:221], v[104:105], v[216:217]
	ds_read_b128 v[226:229], v163 offset:1824
	s_waitcnt lgkmcnt(7)
	v_lshlrev_b32_e32 v216, 16, v230
	v_and_b32_e32 v217, 0xffff0000, v230
	v_pk_add_f32 v[106:107], v[106:107], v[216:217]
	v_lshlrev_b32_e32 v216, 16, v231
	v_and_b32_e32 v217, 0xffff0000, v231
	v_pk_add_f32 v[108:109], v[108:109], v[216:217]
	v_lshlrev_b32_e32 v216, 16, v232
	v_and_b32_e32 v217, 0xffff0000, v232
	v_pk_add_f32 v[218:219], v[218:219], v[216:217]
	v_lshlrev_b32_e32 v216, 16, v233
	v_and_b32_e32 v217, 0xffff0000, v233
	v_pk_add_f32 v[220:221], v[220:221], v[216:217]
	ds_read_b128 v[230:233], v163 offset:1552
	s_waitcnt lgkmcnt(7)
	v_lshlrev_b32_e32 v216, 16, v234
	v_and_b32_e32 v217, 0xffff0000, v234
	v_pk_add_f32 v[106:107], v[106:107], v[216:217]
	v_lshlrev_b32_e32 v216, 16, v235
	v_and_b32_e32 v217, 0xffff0000, v235
	v_pk_add_f32 v[108:109], v[108:109], v[216:217]
	v_lshlrev_b32_e32 v216, 16, v236
	v_and_b32_e32 v217, 0xffff0000, v236
	v_pk_add_f32 v[218:219], v[218:219], v[216:217]
	v_lshlrev_b32_e32 v216, 16, v237
	v_and_b32_e32 v217, 0xffff0000, v237
	v_pk_add_f32 v[220:221], v[220:221], v[216:217]
	ds_read_b128 v[234:237], v163 offset:1280
	s_waitcnt lgkmcnt(7)
	v_lshlrev_b32_e32 v216, 16, v238
	v_and_b32_e32 v217, 0xffff0000, v238
	v_pk_add_f32 v[106:107], v[106:107], v[216:217]
	v_lshlrev_b32_e32 v216, 16, v239
	v_and_b32_e32 v217, 0xffff0000, v239
	v_pk_add_f32 v[108:109], v[108:109], v[216:217]
	v_lshlrev_b32_e32 v216, 16, v240
	v_and_b32_e32 v217, 0xffff0000, v240
	v_pk_add_f32 v[218:219], v[218:219], v[216:217]
	v_lshlrev_b32_e32 v216, 16, v241
	v_and_b32_e32 v217, 0xffff0000, v241
	v_pk_add_f32 v[220:221], v[220:221], v[216:217]
	ds_read_b128 v[238:241], v163 offset:1008
	s_waitcnt lgkmcnt(7)
	v_lshlrev_b32_e32 v216, 16, v242
	v_and_b32_e32 v217, 0xffff0000, v242
	v_pk_add_f32 v[106:107], v[106:107], v[216:217]
	v_lshlrev_b32_e32 v216, 16, v243
	v_and_b32_e32 v217, 0xffff0000, v243
	v_pk_add_f32 v[108:109], v[108:109], v[216:217]
	v_lshlrev_b32_e32 v216, 16, v244
	v_and_b32_e32 v217, 0xffff0000, v244
	v_pk_add_f32 v[218:219], v[218:219], v[216:217]
	v_lshlrev_b32_e32 v216, 16, v245
	v_and_b32_e32 v217, 0xffff0000, v245
	v_pk_add_f32 v[220:221], v[220:221], v[216:217]
	ds_read_b128 v[242:245], v163 offset:736
	s_waitcnt lgkmcnt(7)
	v_lshlrev_b32_e32 v216, 16, v248
	v_and_b32_e32 v217, 0xffff0000, v248
	v_pk_add_f32 v[106:107], v[106:107], v[216:217]
	v_lshlrev_b32_e32 v216, 16, v249
	v_and_b32_e32 v217, 0xffff0000, v249
	v_pk_add_f32 v[108:109], v[108:109], v[216:217]
	v_lshlrev_b32_e32 v216, 16, v250
	v_and_b32_e32 v217, 0xffff0000, v250
	v_pk_add_f32 v[218:219], v[218:219], v[216:217]
	v_lshlrev_b32_e32 v216, 16, v251
	v_and_b32_e32 v217, 0xffff0000, v251
	v_pk_add_f32 v[220:221], v[220:221], v[216:217]
	ds_read_b128 v[248:251], v163 offset:464
	s_waitcnt lgkmcnt(7)
	v_lshlrev_b32_e32 v216, 16, v252
	v_and_b32_e32 v217, 0xffff0000, v252
	v_pk_add_f32 v[106:107], v[106:107], v[216:217]
	v_lshlrev_b32_e32 v216, 16, v253
	v_and_b32_e32 v217, 0xffff0000, v253
	v_pk_add_f32 v[108:109], v[108:109], v[216:217]
	v_lshlrev_b32_e32 v216, 16, v254
	v_and_b32_e32 v217, 0xffff0000, v254
	v_pk_add_f32 v[218:219], v[218:219], v[216:217]
	v_lshlrev_b32_e32 v216, 16, v255
	v_and_b32_e32 v217, 0xffff0000, v255
	v_pk_add_f32 v[220:221], v[220:221], v[216:217]
	ds_read_b128 v[252:255], v163 offset:192
	s_waitcnt lgkmcnt(7)
	v_lshlrev_b32_e32 v216, 16, v222
	v_and_b32_e32 v217, 0xffff0000, v222
	v_pk_add_f32 v[106:107], v[106:107], v[216:217]
	v_lshlrev_b32_e32 v216, 16, v223
	v_and_b32_e32 v217, 0xffff0000, v223
	v_pk_add_f32 v[108:109], v[108:109], v[216:217]
	v_lshlrev_b32_e32 v216, 16, v224
	v_and_b32_e32 v217, 0xffff0000, v224
	v_pk_add_f32 v[218:219], v[218:219], v[216:217]
	v_lshlrev_b32_e32 v216, 16, v225
	v_and_b32_e32 v217, 0xffff0000, v225
	v_pk_add_f32 v[220:221], v[220:221], v[216:217]
	ds_read_b128 v[222:225], v163 offset:4304
	s_waitcnt lgkmcnt(7)
	v_lshlrev_b32_e32 v216, 16, v226
	v_and_b32_e32 v217, 0xffff0000, v226
	v_pk_add_f32 v[106:107], v[106:107], v[216:217]
	v_lshlrev_b32_e32 v216, 16, v227
	v_and_b32_e32 v217, 0xffff0000, v227
	v_pk_add_f32 v[108:109], v[108:109], v[216:217]
	v_lshlrev_b32_e32 v216, 16, v228
	v_and_b32_e32 v217, 0xffff0000, v228
	v_pk_add_f32 v[218:219], v[218:219], v[216:217]
	v_lshlrev_b32_e32 v216, 16, v229
	v_and_b32_e32 v217, 0xffff0000, v229
	v_pk_add_f32 v[220:221], v[220:221], v[216:217]
	ds_read_b128 v[226:229], v163 offset:4032
	s_waitcnt lgkmcnt(7)
	v_lshlrev_b32_e32 v216, 16, v230
	v_and_b32_e32 v217, 0xffff0000, v230
	v_pk_add_f32 v[106:107], v[106:107], v[216:217]
	v_lshlrev_b32_e32 v216, 16, v231
	v_and_b32_e32 v217, 0xffff0000, v231
	v_pk_add_f32 v[108:109], v[108:109], v[216:217]
	v_lshlrev_b32_e32 v216, 16, v232
	v_and_b32_e32 v217, 0xffff0000, v232
	v_pk_add_f32 v[218:219], v[218:219], v[216:217]
	v_lshlrev_b32_e32 v216, 16, v233
	v_and_b32_e32 v217, 0xffff0000, v233
	v_pk_add_f32 v[220:221], v[220:221], v[216:217]
	ds_read_b128 v[230:233], v163 offset:3760
	s_waitcnt lgkmcnt(7)
	v_lshlrev_b32_e32 v216, 16, v234
	v_and_b32_e32 v217, 0xffff0000, v234
	v_pk_add_f32 v[106:107], v[106:107], v[216:217]
	v_lshlrev_b32_e32 v216, 16, v235
	v_and_b32_e32 v217, 0xffff0000, v235
	v_pk_add_f32 v[108:109], v[108:109], v[216:217]
	v_lshlrev_b32_e32 v216, 16, v236
	v_and_b32_e32 v217, 0xffff0000, v236
	v_pk_add_f32 v[218:219], v[218:219], v[216:217]
	v_lshlrev_b32_e32 v216, 16, v237
	v_and_b32_e32 v217, 0xffff0000, v237
	v_pk_add_f32 v[220:221], v[220:221], v[216:217]
	ds_read_b128 v[234:237], v163 offset:3488
	s_waitcnt lgkmcnt(7)
	v_lshlrev_b32_e32 v216, 16, v238
	v_and_b32_e32 v217, 0xffff0000, v238
	v_pk_add_f32 v[106:107], v[106:107], v[216:217]
	v_lshlrev_b32_e32 v216, 16, v239
	v_and_b32_e32 v217, 0xffff0000, v239
	v_pk_add_f32 v[108:109], v[108:109], v[216:217]
	v_lshlrev_b32_e32 v216, 16, v240
	v_and_b32_e32 v217, 0xffff0000, v240
	v_pk_add_f32 v[218:219], v[218:219], v[216:217]
	v_lshlrev_b32_e32 v216, 16, v241
	v_and_b32_e32 v217, 0xffff0000, v241
	v_pk_add_f32 v[220:221], v[220:221], v[216:217]
	ds_read_b128 v[238:241], v163 offset:3216
	s_waitcnt lgkmcnt(7)
	v_lshlrev_b32_e32 v216, 16, v242
	v_and_b32_e32 v217, 0xffff0000, v242
	v_pk_add_f32 v[106:107], v[106:107], v[216:217]
	v_lshlrev_b32_e32 v216, 16, v243
	v_and_b32_e32 v217, 0xffff0000, v243
	v_pk_add_f32 v[108:109], v[108:109], v[216:217]
	v_lshlrev_b32_e32 v216, 16, v244
	v_and_b32_e32 v217, 0xffff0000, v244
	v_pk_add_f32 v[218:219], v[218:219], v[216:217]
	v_lshlrev_b32_e32 v216, 16, v245
	v_and_b32_e32 v217, 0xffff0000, v245
	v_pk_add_f32 v[220:221], v[220:221], v[216:217]
	ds_read_b128 v[242:245], v163 offset:2944
	s_waitcnt lgkmcnt(7)
	v_lshlrev_b32_e32 v216, 16, v248
	v_and_b32_e32 v217, 0xffff0000, v248
	v_pk_add_f32 v[106:107], v[106:107], v[216:217]
	v_lshlrev_b32_e32 v216, 16, v249
	v_and_b32_e32 v217, 0xffff0000, v249
	v_pk_add_f32 v[108:109], v[108:109], v[216:217]
	v_lshlrev_b32_e32 v216, 16, v250
	v_and_b32_e32 v217, 0xffff0000, v250
	v_pk_add_f32 v[218:219], v[218:219], v[216:217]
	v_lshlrev_b32_e32 v216, 16, v251
	v_and_b32_e32 v217, 0xffff0000, v251
	v_pk_add_f32 v[220:221], v[220:221], v[216:217]
	ds_read_b128 v[248:251], v163 offset:2672
	s_waitcnt lgkmcnt(7)
	v_lshlrev_b32_e32 v216, 16, v252
	v_and_b32_e32 v217, 0xffff0000, v252
	v_pk_add_f32 v[106:107], v[106:107], v[216:217]
	v_lshlrev_b32_e32 v216, 16, v253
	v_and_b32_e32 v217, 0xffff0000, v253
	v_pk_add_f32 v[108:109], v[108:109], v[216:217]
	v_lshlrev_b32_e32 v216, 16, v254
	v_and_b32_e32 v217, 0xffff0000, v254
	v_pk_add_f32 v[218:219], v[218:219], v[216:217]
	v_lshlrev_b32_e32 v216, 16, v255
	v_and_b32_e32 v217, 0xffff0000, v255
	v_pk_add_f32 v[220:221], v[220:221], v[216:217]
	ds_read_b128 v[252:255], v163 offset:2400
	v_fma_f32 v106, v159, v106, -v98
	v_fma_f32 v107, v159, v107, -v99
	v_fma_f32 v108, v159, v108, -v100
	v_fma_f32 v109, v159, v109, -v101
	v_fma_f32 v218, v159, v218, -v102
	v_fma_f32 v219, v159, v219, -v103
	v_fma_f32 v220, v159, v220, -v104
	v_fma_f32 v221, v159, v221, -v105
	v_cvt_pk_bf16_f32 v106, v106, v107
	v_cvt_pk_bf16_f32 v107, v108, v109
	v_cvt_pk_bf16_f32 v108, v218, v219
	v_cvt_pk_bf16_f32 v109, v220, v221
	s_and_saveexec_b64 s[28:29], s[6:7]
	s_cbranch_execz .Lpu0_6
	global_store_dwordx4 v[192:193], v[98:101], off offset:384
	global_store_dwordx4 v[192:193], v[102:105], off offset:400
.Lpu0_6:
	s_or_b64 exec, exec, s[28:29]
	s_waitcnt vmcnt(4)
	v_mfma_f32_32x32x16_bf16 v[2:17], v[106:109], v[70:73], v[2:17]
	v_mfma_f32_32x32x16_bf16 v[18:33], v[106:109], v[74:77], v[18:33]
	v_mfma_f32_32x32x16_bf16 v[34:49], v[106:109], v[78:81], v[34:49]
	v_mfma_f32_32x32x16_bf16 v[50:65], v[106:109], v[66:69], v[50:65]
	s_waitcnt lgkmcnt(7)
	v_lshlrev_b32_e32 v98, 16, v222
	v_and_b32_e32 v99, 0xffff0000, v222
	v_lshlrev_b32_e32 v100, 16, v223
	v_and_b32_e32 v101, 0xffff0000, v223
	v_lshlrev_b32_e32 v102, 16, v224
	v_and_b32_e32 v103, 0xffff0000, v224
	v_lshlrev_b32_e32 v104, 16, v225
	v_and_b32_e32 v105, 0xffff0000, v225
	ds_read_b128 v[222:225], v163 offset:2128
	s_waitcnt lgkmcnt(7)
	v_lshlrev_b32_e32 v216, 16, v226
	v_and_b32_e32 v217, 0xffff0000, v226
	v_pk_add_f32 v[106:107], v[98:99], v[216:217]
	v_lshlrev_b32_e32 v216, 16, v227
	v_and_b32_e32 v217, 0xffff0000, v227
	v_pk_add_f32 v[108:109], v[100:101], v[216:217]
	v_lshlrev_b32_e32 v216, 16, v228
	v_and_b32_e32 v217, 0xffff0000, v228
	v_pk_add_f32 v[218:219], v[102:103], v[216:217]
	v_lshlrev_b32_e32 v216, 16, v229
	v_and_b32_e32 v217, 0xffff0000, v229
	v_pk_add_f32 v[220:221], v[104:105], v[216:217]
	ds_read_b128 v[226:229], v163 offset:1856
	s_waitcnt lgkmcnt(7)
	v_lshlrev_b32_e32 v216, 16, v230
	v_and_b32_e32 v217, 0xffff0000, v230
	v_pk_add_f32 v[106:107], v[106:107], v[216:217]
	v_lshlrev_b32_e32 v216, 16, v231
	v_and_b32_e32 v217, 0xffff0000, v231
	v_pk_add_f32 v[108:109], v[108:109], v[216:217]
	v_lshlrev_b32_e32 v216, 16, v232
	v_and_b32_e32 v217, 0xffff0000, v232
	v_pk_add_f32 v[218:219], v[218:219], v[216:217]
	v_lshlrev_b32_e32 v216, 16, v233
	v_and_b32_e32 v217, 0xffff0000, v233
	v_pk_add_f32 v[220:221], v[220:221], v[216:217]
	ds_read_b128 v[230:233], v163 offset:1584
	s_waitcnt lgkmcnt(7)
	v_lshlrev_b32_e32 v216, 16, v234
	v_and_b32_e32 v217, 0xffff0000, v234
	v_pk_add_f32 v[106:107], v[106:107], v[216:217]
	v_lshlrev_b32_e32 v216, 16, v235
	v_and_b32_e32 v217, 0xffff0000, v235
	v_pk_add_f32 v[108:109], v[108:109], v[216:217]
	v_lshlrev_b32_e32 v216, 16, v236
	v_and_b32_e32 v217, 0xffff0000, v236
	v_pk_add_f32 v[218:219], v[218:219], v[216:217]
	v_lshlrev_b32_e32 v216, 16, v237
	v_and_b32_e32 v217, 0xffff0000, v237
	v_pk_add_f32 v[220:221], v[220:221], v[216:217]
	ds_read_b128 v[234:237], v163 offset:1312
	s_waitcnt lgkmcnt(7)
	v_lshlrev_b32_e32 v216, 16, v238
	v_and_b32_e32 v217, 0xffff0000, v238
	v_pk_add_f32 v[106:107], v[106:107], v[216:217]
	v_lshlrev_b32_e32 v216, 16, v239
	v_and_b32_e32 v217, 0xffff0000, v239
	v_pk_add_f32 v[108:109], v[108:109], v[216:217]
	v_lshlrev_b32_e32 v216, 16, v240
	v_and_b32_e32 v217, 0xffff0000, v240
	v_pk_add_f32 v[218:219], v[218:219], v[216:217]
	v_lshlrev_b32_e32 v216, 16, v241
	v_and_b32_e32 v217, 0xffff0000, v241
	v_pk_add_f32 v[220:221], v[220:221], v[216:217]
	ds_read_b128 v[238:241], v163 offset:1040
	s_waitcnt lgkmcnt(7)
	v_lshlrev_b32_e32 v216, 16, v242
	v_and_b32_e32 v217, 0xffff0000, v242
	v_pk_add_f32 v[106:107], v[106:107], v[216:217]
	v_lshlrev_b32_e32 v216, 16, v243
	v_and_b32_e32 v217, 0xffff0000, v243
	v_pk_add_f32 v[108:109], v[108:109], v[216:217]
	v_lshlrev_b32_e32 v216, 16, v244
	v_and_b32_e32 v217, 0xffff0000, v244
	v_pk_add_f32 v[218:219], v[218:219], v[216:217]
	v_lshlrev_b32_e32 v216, 16, v245
	v_and_b32_e32 v217, 0xffff0000, v245
	v_pk_add_f32 v[220:221], v[220:221], v[216:217]
	ds_read_b128 v[242:245], v163 offset:768
	s_waitcnt lgkmcnt(7)
	v_lshlrev_b32_e32 v216, 16, v248
	v_and_b32_e32 v217, 0xffff0000, v248
	v_pk_add_f32 v[106:107], v[106:107], v[216:217]
	v_lshlrev_b32_e32 v216, 16, v249
	v_and_b32_e32 v217, 0xffff0000, v249
	v_pk_add_f32 v[108:109], v[108:109], v[216:217]
	v_lshlrev_b32_e32 v216, 16, v250
	v_and_b32_e32 v217, 0xffff0000, v250
	v_pk_add_f32 v[218:219], v[218:219], v[216:217]
	v_lshlrev_b32_e32 v216, 16, v251
	v_and_b32_e32 v217, 0xffff0000, v251
	v_pk_add_f32 v[220:221], v[220:221], v[216:217]
	ds_read_b128 v[248:251], v163 offset:496
	s_waitcnt lgkmcnt(7)
	v_lshlrev_b32_e32 v216, 16, v252
	v_and_b32_e32 v217, 0xffff0000, v252
	v_pk_add_f32 v[106:107], v[106:107], v[216:217]
	v_lshlrev_b32_e32 v216, 16, v253
	v_and_b32_e32 v217, 0xffff0000, v253
	v_pk_add_f32 v[108:109], v[108:109], v[216:217]
	v_lshlrev_b32_e32 v216, 16, v254
	v_and_b32_e32 v217, 0xffff0000, v254
	v_pk_add_f32 v[218:219], v[218:219], v[216:217]
	v_lshlrev_b32_e32 v216, 16, v255
	v_and_b32_e32 v217, 0xffff0000, v255
	v_pk_add_f32 v[220:221], v[220:221], v[216:217]
	ds_read_b128 v[252:255], v163 offset:224
	s_waitcnt lgkmcnt(7)
	v_lshlrev_b32_e32 v216, 16, v222
	v_and_b32_e32 v217, 0xffff0000, v222
	v_pk_add_f32 v[106:107], v[106:107], v[216:217]
	v_lshlrev_b32_e32 v216, 16, v223
	v_and_b32_e32 v217, 0xffff0000, v223
	v_pk_add_f32 v[108:109], v[108:109], v[216:217]
	v_lshlrev_b32_e32 v216, 16, v224
	v_and_b32_e32 v217, 0xffff0000, v224
	v_pk_add_f32 v[218:219], v[218:219], v[216:217]
	v_lshlrev_b32_e32 v216, 16, v225
	v_and_b32_e32 v217, 0xffff0000, v225
	v_pk_add_f32 v[220:221], v[220:221], v[216:217]
	s_waitcnt lgkmcnt(6)
	v_lshlrev_b32_e32 v216, 16, v226
	v_and_b32_e32 v217, 0xffff0000, v226
	v_pk_add_f32 v[106:107], v[106:107], v[216:217]
	v_lshlrev_b32_e32 v216, 16, v227
	v_and_b32_e32 v217, 0xffff0000, v227
	v_pk_add_f32 v[108:109], v[108:109], v[216:217]
	v_lshlrev_b32_e32 v216, 16, v228
	v_and_b32_e32 v217, 0xffff0000, v228
	v_pk_add_f32 v[218:219], v[218:219], v[216:217]
	v_lshlrev_b32_e32 v216, 16, v229
	v_and_b32_e32 v217, 0xffff0000, v229
	v_pk_add_f32 v[220:221], v[220:221], v[216:217]
	s_waitcnt lgkmcnt(5)
	v_lshlrev_b32_e32 v216, 16, v230
	v_and_b32_e32 v217, 0xffff0000, v230
	v_pk_add_f32 v[106:107], v[106:107], v[216:217]
	v_lshlrev_b32_e32 v216, 16, v231
	v_and_b32_e32 v217, 0xffff0000, v231
	v_pk_add_f32 v[108:109], v[108:109], v[216:217]
	v_lshlrev_b32_e32 v216, 16, v232
	v_and_b32_e32 v217, 0xffff0000, v232
	v_pk_add_f32 v[218:219], v[218:219], v[216:217]
	v_lshlrev_b32_e32 v216, 16, v233
	v_and_b32_e32 v217, 0xffff0000, v233
	v_pk_add_f32 v[220:221], v[220:221], v[216:217]
	s_waitcnt lgkmcnt(4)
	v_lshlrev_b32_e32 v216, 16, v234
	v_and_b32_e32 v217, 0xffff0000, v234
	v_pk_add_f32 v[106:107], v[106:107], v[216:217]
	v_lshlrev_b32_e32 v216, 16, v235
	v_and_b32_e32 v217, 0xffff0000, v235
	v_pk_add_f32 v[108:109], v[108:109], v[216:217]
	v_lshlrev_b32_e32 v216, 16, v236
	v_and_b32_e32 v217, 0xffff0000, v236
	v_pk_add_f32 v[218:219], v[218:219], v[216:217]
	v_lshlrev_b32_e32 v216, 16, v237
	v_and_b32_e32 v217, 0xffff0000, v237
	v_pk_add_f32 v[220:221], v[220:221], v[216:217]
	s_waitcnt lgkmcnt(3)
	v_lshlrev_b32_e32 v216, 16, v238
	v_and_b32_e32 v217, 0xffff0000, v238
	v_pk_add_f32 v[106:107], v[106:107], v[216:217]
	v_lshlrev_b32_e32 v216, 16, v239
	v_and_b32_e32 v217, 0xffff0000, v239
	v_pk_add_f32 v[108:109], v[108:109], v[216:217]
	v_lshlrev_b32_e32 v216, 16, v240
	v_and_b32_e32 v217, 0xffff0000, v240
	v_pk_add_f32 v[218:219], v[218:219], v[216:217]
	v_lshlrev_b32_e32 v216, 16, v241
	v_and_b32_e32 v217, 0xffff0000, v241
	v_pk_add_f32 v[220:221], v[220:221], v[216:217]
	s_waitcnt lgkmcnt(2)
	v_lshlrev_b32_e32 v216, 16, v242
	v_and_b32_e32 v217, 0xffff0000, v242
	v_pk_add_f32 v[106:107], v[106:107], v[216:217]
	v_lshlrev_b32_e32 v216, 16, v243
	v_and_b32_e32 v217, 0xffff0000, v243
	v_pk_add_f32 v[108:109], v[108:109], v[216:217]
	v_lshlrev_b32_e32 v216, 16, v244
	v_and_b32_e32 v217, 0xffff0000, v244
	v_pk_add_f32 v[218:219], v[218:219], v[216:217]
	v_lshlrev_b32_e32 v216, 16, v245
	v_and_b32_e32 v217, 0xffff0000, v245
	v_pk_add_f32 v[220:221], v[220:221], v[216:217]
	s_waitcnt lgkmcnt(1)
	v_lshlrev_b32_e32 v216, 16, v248
	v_and_b32_e32 v217, 0xffff0000, v248
	v_pk_add_f32 v[106:107], v[106:107], v[216:217]
	v_lshlrev_b32_e32 v216, 16, v249
	v_and_b32_e32 v217, 0xffff0000, v249
	v_pk_add_f32 v[108:109], v[108:109], v[216:217]
	v_lshlrev_b32_e32 v216, 16, v250
	v_and_b32_e32 v217, 0xffff0000, v250
	v_pk_add_f32 v[218:219], v[218:219], v[216:217]
	v_lshlrev_b32_e32 v216, 16, v251
	v_and_b32_e32 v217, 0xffff0000, v251
	v_pk_add_f32 v[220:221], v[220:221], v[216:217]
	s_waitcnt lgkmcnt(0)
	v_lshlrev_b32_e32 v216, 16, v252
	v_and_b32_e32 v217, 0xffff0000, v252
	v_pk_add_f32 v[106:107], v[106:107], v[216:217]
	v_lshlrev_b32_e32 v216, 16, v253
	v_and_b32_e32 v217, 0xffff0000, v253
	v_pk_add_f32 v[108:109], v[108:109], v[216:217]
	v_lshlrev_b32_e32 v216, 16, v254
	v_and_b32_e32 v217, 0xffff0000, v254
	v_pk_add_f32 v[218:219], v[218:219], v[216:217]
	v_lshlrev_b32_e32 v216, 16, v255
	v_and_b32_e32 v217, 0xffff0000, v255
	v_pk_add_f32 v[220:221], v[220:221], v[216:217]
	v_fma_f32 v106, v159, v106, -v98
	v_fma_f32 v107, v159, v107, -v99
	v_fma_f32 v108, v159, v108, -v100
	v_fma_f32 v109, v159, v109, -v101
	v_fma_f32 v218, v159, v218, -v102
	v_fma_f32 v219, v159, v219, -v103
	v_fma_f32 v220, v159, v220, -v104
	v_fma_f32 v221, v159, v221, -v105
	v_cvt_pk_bf16_f32 v106, v106, v107
	v_cvt_pk_bf16_f32 v107, v108, v109
	v_cvt_pk_bf16_f32 v108, v218, v219
	v_cvt_pk_bf16_f32 v109, v220, v221
	s_and_saveexec_b64 s[28:29], s[6:7]
	s_cbranch_execz .Lpu0_7
	global_store_dwordx4 v[192:193], v[98:101], off offset:448
	global_store_dwordx4 v[192:193], v[102:105], off offset:464

.LBB0_355:
	s_or_b64 exec, exec, s[6:7]
	s_waitcnt lgkmcnt(0)
	global_load_dwordx4 v[82:85], v[112:113], off offset:512
	global_load_dwordx4 v[86:89], v[114:115], off offset:512
	global_load_dwordx4 v[90:93], v[116:117], off offset:512
	global_load_dwordx4 v[94:97], v[118:119], off offset:512
	global_load_dwordx4 v[222:225], v[112:113], off offset:1024
	global_load_dwordx4 v[226:229], v[114:115], off offset:1024
	global_load_dwordx4 v[230:233], v[116:117], off offset:1024
	global_load_dwordx4 v[234:237], v[118:119], off offset:1024
	v_or_b32_e32 v2, s28, v1
	v_min_u32_e32 v3, 7, v2
	v_add_u32_e32 v3, 1, v3
	v_cvt_f32_ubyte0_e32 v3, v3
	v_div_scale_f32 v4, s[6:7], v3, v3, 1.0
	v_rcp_f32_e32 v5, v4
	s_ashr_i32 s8, s30, 6
	s_mul_i32 s10, s8, 15
	v_cmp_lt_u32_e64 s[6:7], s41, v2
	v_fma_f32 v6, -v4, v5, 1.0
	v_fmac_f32_e32 v5, v6, v5
	v_div_scale_f32 v6, vcc, 1.0, v3, 1.0
	v_mul_f32_e32 v7, v6, v5
	v_fma_f32 v8, -v4, v7, v6
	v_fmac_f32_e32 v7, v8, v5
	v_fma_f32 v4, -v4, v7, v6
	v_div_fmas_f32 v4, v4, v5, v7
	v_div_fixup_f32 v159, v4, v3, 1.0
	s_ashr_i32 s11, s10, 31
	v_add_u32_e32 v2, 0xfffff80f, v2
	v_mov_b32_e32 v3, v155
	v_lshl_add_u64 v[2:3], v[2:3], 0, s[10:11]
	v_lshlrev_b64 v[2:3], 11, v[2:3]
	v_lshl_add_u64 v[2:3], s[70:71], 0, v[2:3]
	v_mov_b32_e32 v163, v155
	v_lshl_add_u64 v[2:3], v[2:3], 0, v[162:163]
	v_lshl_add_u64 v[192:193], v[2:3], 0, s[20:21]
	v_mov_b32_e32 v2, 0
	s_mov_b32 s49, 0
	s_mov_b64 s[10:11], 0
	v_mov_b32_e32 v3, v2
	v_mov_b32_e32 v4, v2
	v_mov_b32_e32 v5, v2
	v_mov_b32_e32 v6, v2
	v_mov_b32_e32 v7, v2
	v_mov_b32_e32 v8, v2
	v_mov_b32_e32 v9, v2
	v_mov_b32_e32 v10, v2
	v_mov_b32_e32 v11, v2
	v_mov_b32_e32 v12, v2
	v_mov_b32_e32 v13, v2
	v_mov_b32_e32 v14, v2
	v_mov_b32_e32 v15, v2
	v_mov_b32_e32 v16, v2
	v_mov_b32_e32 v17, v2
	v_mov_b32_e32 v18, v2
	v_mov_b32_e32 v19, v2
	v_mov_b32_e32 v20, v2
	v_mov_b32_e32 v21, v2
	v_mov_b32_e32 v22, v2
	v_mov_b32_e32 v23, v2
	v_mov_b32_e32 v24, v2
	v_mov_b32_e32 v25, v2
	v_mov_b32_e32 v26, v2
	v_mov_b32_e32 v27, v2
	v_mov_b32_e32 v28, v2
	v_mov_b32_e32 v29, v2
	v_mov_b32_e32 v30, v2
	v_mov_b32_e32 v31, v2
	v_mov_b32_e32 v32, v2
	v_mov_b32_e32 v33, v2
	v_mov_b32_e32 v34, v2
	v_mov_b32_e32 v35, v2
	v_mov_b32_e32 v36, v2
	v_mov_b32_e32 v37, v2
	v_mov_b32_e32 v38, v2
	v_mov_b32_e32 v39, v2
	v_mov_b32_e32 v40, v2
	v_mov_b32_e32 v41, v2
	v_mov_b32_e32 v42, v2
	v_mov_b32_e32 v43, v2
	v_mov_b32_e32 v44, v2
	v_mov_b32_e32 v45, v2
	v_mov_b32_e32 v46, v2
	v_mov_b32_e32 v47, v2
	v_mov_b32_e32 v48, v2
	v_mov_b32_e32 v49, v2
	v_mov_b32_e32 v50, v2
	v_mov_b32_e32 v51, v2
	v_mov_b32_e32 v52, v2
	v_mov_b32_e32 v53, v2
	v_mov_b32_e32 v54, v2
	v_mov_b32_e32 v55, v2
	v_mov_b32_e32 v56, v2
	v_mov_b32_e32 v57, v2
	v_mov_b32_e32 v58, v2
	v_mov_b32_e32 v59, v2
	v_mov_b32_e32 v60, v2
	v_mov_b32_e32 v61, v2
	v_mov_b32_e32 v62, v2
	v_mov_b32_e32 v63, v2
	v_mov_b32_e32 v64, v2
	v_mov_b32_e32 v65, v2
	v_lshl_add_u32 v163, v197, 1, v214
	ds_read_b128 v[238:241], v163 offset:4080
	ds_read_b128 v[242:245], v163 offset:3808
	ds_read_b128 v[248:251], v163 offset:3536
	ds_read_b128 v[252:255], v163 offset:3264
	s_waitcnt lgkmcnt(3)
	v_lshlrev_b32_e32 v98, 16, v238
	v_and_b32_e32 v99, 0xffff0000, v238
	v_lshlrev_b32_e32 v100, 16, v239
	v_and_b32_e32 v101, 0xffff0000, v239
	v_lshlrev_b32_e32 v102, 16, v240
	v_and_b32_e32 v103, 0xffff0000, v240
	v_lshlrev_b32_e32 v104, 16, v241
	v_and_b32_e32 v105, 0xffff0000, v241
	ds_read_b128 v[238:241], v163 offset:2992
	s_waitcnt lgkmcnt(3)
	v_lshlrev_b32_e32 v216, 16, v242
	v_and_b32_e32 v217, 0xffff0000, v242
	v_pk_add_f32 v[106:107], v[98:99], v[216:217]
	v_lshlrev_b32_e32 v216, 16, v243
	v_and_b32_e32 v217, 0xffff0000, v243
	v_pk_add_f32 v[108:109], v[100:101], v[216:217]
	v_lshlrev_b32_e32 v216, 16, v244
	v_and_b32_e32 v217, 0xffff0000, v244
	v_pk_add_f32 v[218:219], v[102:103], v[216:217]
	v_lshlrev_b32_e32 v216, 16, v245
	v_and_b32_e32 v217, 0xffff0000, v245
	v_pk_add_f32 v[220:221], v[104:105], v[216:217]
	ds_read_b128 v[242:245], v163 offset:2720
	s_waitcnt lgkmcnt(3)
	v_lshlrev_b32_e32 v216, 16, v248
	v_and_b32_e32 v217, 0xffff0000, v248
	v_pk_add_f32 v[106:107], v[106:107], v[216:217]
	v_lshlrev_b32_e32 v216, 16, v249
	v_and_b32_e32 v217, 0xffff0000, v249
	v_pk_add_f32 v[108:109], v[108:109], v[216:217]
	v_lshlrev_b32_e32 v216, 16, v250
	v_and_b32_e32 v217, 0xffff0000, v250
	v_pk_add_f32 v[218:219], v[218:219], v[216:217]
	v_lshlrev_b32_e32 v216, 16, v251
	v_and_b32_e32 v217, 0xffff0000, v251
	v_pk_add_f32 v[220:221], v[220:221], v[216:217]
	ds_read_b128 v[248:251], v163 offset:2448
	s_waitcnt lgkmcnt(3)
	v_lshlrev_b32_e32 v216, 16, v252
	v_and_b32_e32 v217, 0xffff0000, v252
	v_pk_add_f32 v[106:107], v[106:107], v[216:217]
	v_lshlrev_b32_e32 v216, 16, v253
	v_and_b32_e32 v217, 0xffff0000, v253
	v_pk_add_f32 v[108:109], v[108:109], v[216:217]
	v_lshlrev_b32_e32 v216, 16, v254
	v_and_b32_e32 v217, 0xffff0000, v254
	v_pk_add_f32 v[218:219], v[218:219], v[216:217]
	v_lshlrev_b32_e32 v216, 16, v255
	v_and_b32_e32 v217, 0xffff0000, v255
	v_pk_add_f32 v[220:221], v[220:221], v[216:217]
	ds_read_b128 v[252:255], v163 offset:2176
	s_waitcnt lgkmcnt(3)
	v_lshlrev_b32_e32 v216, 16, v238
	v_and_b32_e32 v217, 0xffff0000, v238
	v_pk_add_f32 v[106:107], v[106:107], v[216:217]
	v_lshlrev_b32_e32 v216, 16, v239
	v_and_b32_e32 v217, 0xffff0000, v239
	v_pk_add_f32 v[108:109], v[108:109], v[216:217]
	v_lshlrev_b32_e32 v216, 16, v240
	v_and_b32_e32 v217, 0xffff0000, v240
	v_pk_add_f32 v[218:219], v[218:219], v[216:217]
	v_lshlrev_b32_e32 v216, 16, v241
	v_and_b32_e32 v217, 0xffff0000, v241
	v_pk_add_f32 v[220:221], v[220:221], v[216:217]
	ds_read_b128 v[238:241], v163 offset:4112
	s_waitcnt lgkmcnt(3)
	v_lshlrev_b32_e32 v216, 16, v242
	v_and_b32_e32 v217, 0xffff0000, v242
	v_pk_add_f32 v[106:107], v[106:107], v[216:217]
	v_lshlrev_b32_e32 v216, 16, v243
	v_and_b32_e32 v217, 0xffff0000, v243
	v_pk_add_f32 v[108:109], v[108:109], v[216:217]
	v_lshlrev_b32_e32 v216, 16, v244
	v_and_b32_e32 v217, 0xffff0000, v244
	v_pk_add_f32 v[218:219], v[218:219], v[216:217]
	v_lshlrev_b32_e32 v216, 16, v245
	v_and_b32_e32 v217, 0xffff0000, v245
	v_pk_add_f32 v[220:221], v[220:221], v[216:217]
	ds_read_b128 v[242:245], v163 offset:3840
	s_waitcnt lgkmcnt(3)
	v_lshlrev_b32_e32 v216, 16, v248
	v_and_b32_e32 v217, 0xffff0000, v248
	v_pk_add_f32 v[106:107], v[106:107], v[216:217]
	v_lshlrev_b32_e32 v216, 16, v249
	v_and_b32_e32 v217, 0xffff0000, v249
	v_pk_add_f32 v[108:109], v[108:109], v[216:217]
	v_lshlrev_b32_e32 v216, 16, v250
	v_and_b32_e32 v217, 0xffff0000, v250
	v_pk_add_f32 v[218:219], v[218:219], v[216:217]
	v_lshlrev_b32_e32 v216, 16, v251
	v_and_b32_e32 v217, 0xffff0000, v251
	v_pk_add_f32 v[220:221], v[220:221], v[216:217]
	ds_read_b128 v[248:251], v163 offset:3568
	s_waitcnt lgkmcnt(3)
	v_lshlrev_b32_e32 v216, 16, v252
	v_and_b32_e32 v217, 0xffff0000, v252
	v_pk_add_f32 v[106:107], v[106:107], v[216:217]
	v_lshlrev_b32_e32 v216, 16, v253
	v_and_b32_e32 v217, 0xffff0000, v253
	v_pk_add_f32 v[108:109], v[108:109], v[216:217]
	v_lshlrev_b32_e32 v216, 16, v254
	v_and_b32_e32 v217, 0xffff0000, v254
	v_pk_add_f32 v[218:219], v[218:219], v[216:217]
	v_lshlrev_b32_e32 v216, 16, v255
	v_and_b32_e32 v217, 0xffff0000, v255
	v_pk_add_f32 v[220:221], v[220:221], v[216:217]
	ds_read_b128 v[252:255], v163 offset:3296
	v_fma_f32 v106, v159, v106, -v98
	v_fma_f32 v107, v159, v107, -v99
	v_fma_f32 v108, v159, v108, -v100
	v_fma_f32 v109, v159, v109, -v101
	v_fma_f32 v218, v159, v218, -v102
	v_fma_f32 v219, v159, v219, -v103
	v_fma_f32 v220, v159, v220, -v104
	v_fma_f32 v221, v159, v221, -v105
	v_cvt_pk_bf16_f32 v106, v106, v107
	v_cvt_pk_bf16_f32 v107, v108, v109
	v_cvt_pk_bf16_f32 v108, v218, v219
	v_cvt_pk_bf16_f32 v109, v220, v221
	s_and_saveexec_b64 s[28:29], s[6:7]
	s_cbranch_execz .Lpu1_0
	global_store_dwordx4 v[192:193], v[98:101], off offset:0
	global_store_dwordx4 v[192:193], v[102:105], off offset:16
.Lpu1_0:
	s_or_b64 exec, exec, s[28:29]
	s_waitcnt vmcnt(8)
	v_mfma_f32_32x32x16_bf16 v[2:17], v[106:109], v[70:73], v[2:17]
	v_mfma_f32_32x32x16_bf16 v[18:33], v[106:109], v[74:77], v[18:33]
	v_mfma_f32_32x32x16_bf16 v[34:49], v[106:109], v[78:81], v[34:49]
	v_mfma_f32_32x32x16_bf16 v[50:65], v[106:109], v[66:69], v[50:65]
	global_load_dwordx4 v[70:73], v[112:113], off offset:1536
	global_load_dwordx4 v[74:77], v[114:115], off offset:1536
	global_load_dwordx4 v[78:81], v[116:117], off offset:1536
	global_load_dwordx4 v[66:69], v[118:119], off offset:1536
	s_waitcnt lgkmcnt(3)
	v_lshlrev_b32_e32 v98, 16, v238
	v_and_b32_e32 v99, 0xffff0000, v238
	v_lshlrev_b32_e32 v100, 16, v239
	v_and_b32_e32 v101, 0xffff0000, v239
	v_lshlrev_b32_e32 v102, 16, v240
	v_and_b32_e32 v103, 0xffff0000, v240
	v_lshlrev_b32_e32 v104, 16, v241
	v_and_b32_e32 v105, 0xffff0000, v241
	ds_read_b128 v[238:241], v163 offset:3024
	s_waitcnt lgkmcnt(3)
	v_lshlrev_b32_e32 v216, 16, v242
	v_and_b32_e32 v217, 0xffff0000, v242
	v_pk_add_f32 v[106:107], v[98:99], v[216:217]
	v_lshlrev_b32_e32 v216, 16, v243
	v_and_b32_e32 v217, 0xffff0000, v243
	v_pk_add_f32 v[108:109], v[100:101], v[216:217]
	v_lshlrev_b32_e32 v216, 16, v244
	v_and_b32_e32 v217, 0xffff0000, v244
	v_pk_add_f32 v[218:219], v[102:103], v[216:217]
	v_lshlrev_b32_e32 v216, 16, v245
	v_and_b32_e32 v217, 0xffff0000, v245
	v_pk_add_f32 v[220:221], v[104:105], v[216:217]
	ds_read_b128 v[242:245], v163 offset:2752
	s_waitcnt lgkmcnt(3)
	v_lshlrev_b32_e32 v216, 16, v248
	v_and_b32_e32 v217, 0xffff0000, v248
	v_pk_add_f32 v[106:107], v[106:107], v[216:217]
	v_lshlrev_b32_e32 v216, 16, v249
	v_and_b32_e32 v217, 0xffff0000, v249
	v_pk_add_f32 v[108:109], v[108:109], v[216:217]
	v_lshlrev_b32_e32 v216, 16, v250
	v_and_b32_e32 v217, 0xffff0000, v250
	v_pk_add_f32 v[218:219], v[218:219], v[216:217]
	v_lshlrev_b32_e32 v216, 16, v251
	v_and_b32_e32 v217, 0xffff0000, v251
	v_pk_add_f32 v[220:221], v[220:221], v[216:217]
	ds_read_b128 v[248:251], v163 offset:2480
	s_waitcnt lgkmcnt(3)
	v_lshlrev_b32_e32 v216, 16, v252
	v_and_b32_e32 v217, 0xffff0000, v252
	v_pk_add_f32 v[106:107], v[106:107], v[216:217]
	v_lshlrev_b32_e32 v216, 16, v253
	v_and_b32_e32 v217, 0xffff0000, v253
	v_pk_add_f32 v[108:109], v[108:109], v[216:217]
	v_lshlrev_b32_e32 v216, 16, v254
	v_and_b32_e32 v217, 0xffff0000, v254
	v_pk_add_f32 v[218:219], v[218:219], v[216:217]
	v_lshlrev_b32_e32 v216, 16, v255
	v_and_b32_e32 v217, 0xffff0000, v255
	v_pk_add_f32 v[220:221], v[220:221], v[216:217]
	ds_read_b128 v[252:255], v163 offset:2208
	s_waitcnt lgkmcnt(3)
	v_lshlrev_b32_e32 v216, 16, v238
	v_and_b32_e32 v217, 0xffff0000, v238
	v_pk_add_f32 v[106:107], v[106:107], v[216:217]
	v_lshlrev_b32_e32 v216, 16, v239
	v_and_b32_e32 v217, 0xffff0000, v239
	v_pk_add_f32 v[108:109], v[108:109], v[216:217]
	v_lshlrev_b32_e32 v216, 16, v240
	v_and_b32_e32 v217, 0xffff0000, v240
	v_pk_add_f32 v[218:219], v[218:219], v[216:217]
	v_lshlrev_b32_e32 v216, 16, v241
	v_and_b32_e32 v217, 0xffff0000, v241
	v_pk_add_f32 v[220:221], v[220:221], v[216:217]
	ds_read_b128 v[238:241], v163 offset:4144
	s_waitcnt lgkmcnt(3)
	v_lshlrev_b32_e32 v216, 16, v242
	v_and_b32_e32 v217, 0xffff0000, v242
	v_pk_add_f32 v[106:107], v[106:107], v[216:217]
	v_lshlrev_b32_e32 v216, 16, v243
	v_and_b32_e32 v217, 0xffff0000, v243
	v_pk_add_f32 v[108:109], v[108:109], v[216:217]
	v_lshlrev_b32_e32 v216, 16, v244
	v_and_b32_e32 v217, 0xffff0000, v244
	v_pk_add_f32 v[218:219], v[218:219], v[216:217]
	v_lshlrev_b32_e32 v216, 16, v245
	v_and_b32_e32 v217, 0xffff0000, v245
	v_pk_add_f32 v[220:221], v[220:221], v[216:217]
	ds_read_b128 v[242:245], v163 offset:3872
	s_waitcnt lgkmcnt(3)
	v_lshlrev_b32_e32 v216, 16, v248
	v_and_b32_e32 v217, 0xffff0000, v248
	v_pk_add_f32 v[106:107], v[106:107], v[216:217]
	v_lshlrev_b32_e32 v216, 16, v249
	v_and_b32_e32 v217, 0xffff0000, v249
	v_pk_add_f32 v[108:109], v[108:109], v[216:217]
	v_lshlrev_b32_e32 v216, 16, v250
	v_and_b32_e32 v217, 0xffff0000, v250
	v_pk_add_f32 v[218:219], v[218:219], v[216:217]
	v_lshlrev_b32_e32 v216, 16, v251
	v_and_b32_e32 v217, 0xffff0000, v251
	v_pk_add_f32 v[220:221], v[220:221], v[216:217]
	ds_read_b128 v[248:251], v163 offset:3600
	s_waitcnt lgkmcnt(3)
	v_lshlrev_b32_e32 v216, 16, v252
	v_and_b32_e32 v217, 0xffff0000, v252
	v_pk_add_f32 v[106:107], v[106:107], v[216:217]
	v_lshlrev_b32_e32 v216, 16, v253
	v_and_b32_e32 v217, 0xffff0000, v253
	v_pk_add_f32 v[108:109], v[108:109], v[216:217]
	v_lshlrev_b32_e32 v216, 16, v254
	v_and_b32_e32 v217, 0xffff0000, v254
	v_pk_add_f32 v[218:219], v[218:219], v[216:217]
	v_lshlrev_b32_e32 v216, 16, v255
	v_and_b32_e32 v217, 0xffff0000, v255
	v_pk_add_f32 v[220:221], v[220:221], v[216:217]
	ds_read_b128 v[252:255], v163 offset:3328
	v_fma_f32 v106, v159, v106, -v98
	v_fma_f32 v107, v159, v107, -v99
	v_fma_f32 v108, v159, v108, -v100
	v_fma_f32 v109, v159, v109, -v101
	v_fma_f32 v218, v159, v218, -v102
	v_fma_f32 v219, v159, v219, -v103
	v_fma_f32 v220, v159, v220, -v104
	v_fma_f32 v221, v159, v221, -v105
	v_cvt_pk_bf16_f32 v106, v106, v107
	v_cvt_pk_bf16_f32 v107, v108, v109
	v_cvt_pk_bf16_f32 v108, v218, v219
	v_cvt_pk_bf16_f32 v109, v220, v221
	s_and_saveexec_b64 s[28:29], s[6:7]
	s_cbranch_execz .Lpu1_1
	global_store_dwordx4 v[192:193], v[98:101], off offset:64
	global_store_dwordx4 v[192:193], v[102:105], off offset:80
.Lpu1_1:
	s_or_b64 exec, exec, s[28:29]
	s_waitcnt vmcnt(8)
	v_mfma_f32_32x32x16_bf16 v[2:17], v[106:109], v[82:85], v[2:17]
	v_mfma_f32_32x32x16_bf16 v[18:33], v[106:109], v[86:89], v[18:33]
	v_mfma_f32_32x32x16_bf16 v[34:49], v[106:109], v[90:93], v[34:49]
	v_mfma_f32_32x32x16_bf16 v[50:65], v[106:109], v[94:97], v[50:65]
	global_load_dwordx4 v[82:85], v[112:113], off offset:2048
	global_load_dwordx4 v[86:89], v[114:115], off offset:2048
	global_load_dwordx4 v[90:93], v[116:117], off offset:2048
	global_load_dwordx4 v[94:97], v[118:119], off offset:2048
	s_waitcnt lgkmcnt(3)
	v_lshlrev_b32_e32 v98, 16, v238
	v_and_b32_e32 v99, 0xffff0000, v238
	v_lshlrev_b32_e32 v100, 16, v239
	v_and_b32_e32 v101, 0xffff0000, v239
	v_lshlrev_b32_e32 v102, 16, v240
	v_and_b32_e32 v103, 0xffff0000, v240
	v_lshlrev_b32_e32 v104, 16, v241
	v_and_b32_e32 v105, 0xffff0000, v241
	ds_read_b128 v[238:241], v163 offset:3056
	s_waitcnt lgkmcnt(3)
	v_lshlrev_b32_e32 v216, 16, v242
	v_and_b32_e32 v217, 0xffff0000, v242
	v_pk_add_f32 v[106:107], v[98:99], v[216:217]
	v_lshlrev_b32_e32 v216, 16, v243
	v_and_b32_e32 v217, 0xffff0000, v243
	v_pk_add_f32 v[108:109], v[100:101], v[216:217]
	v_lshlrev_b32_e32 v216, 16, v244
	v_and_b32_e32 v217, 0xffff0000, v244
	v_pk_add_f32 v[218:219], v[102:103], v[216:217]
	v_lshlrev_b32_e32 v216, 16, v245
	v_and_b32_e32 v217, 0xffff0000, v245
	v_pk_add_f32 v[220:221], v[104:105], v[216:217]
	ds_read_b128 v[242:245], v163 offset:2784
	s_waitcnt lgkmcnt(3)
	v_lshlrev_b32_e32 v216, 16, v248
	v_and_b32_e32 v217, 0xffff0000, v248
	v_pk_add_f32 v[106:107], v[106:107], v[216:217]
	v_lshlrev_b32_e32 v216, 16, v249
	v_and_b32_e32 v217, 0xffff0000, v249
	v_pk_add_f32 v[108:109], v[108:109], v[216:217]
	v_lshlrev_b32_e32 v216, 16, v250
	v_and_b32_e32 v217, 0xffff0000, v250
	v_pk_add_f32 v[218:219], v[218:219], v[216:217]
	v_lshlrev_b32_e32 v216, 16, v251
	v_and_b32_e32 v217, 0xffff0000, v251
	v_pk_add_f32 v[220:221], v[220:221], v[216:217]
	ds_read_b128 v[248:251], v163 offset:2512
	s_waitcnt lgkmcnt(3)
	v_lshlrev_b32_e32 v216, 16, v252
	v_and_b32_e32 v217, 0xffff0000, v252
	v_pk_add_f32 v[106:107], v[106:107], v[216:217]
	v_lshlrev_b32_e32 v216, 16, v253
	v_and_b32_e32 v217, 0xffff0000, v253
	v_pk_add_f32 v[108:109], v[108:109], v[216:217]
	v_lshlrev_b32_e32 v216, 16, v254
	v_and_b32_e32 v217, 0xffff0000, v254
	v_pk_add_f32 v[218:219], v[218:219], v[216:217]
	v_lshlrev_b32_e32 v216, 16, v255
	v_and_b32_e32 v217, 0xffff0000, v255
	v_pk_add_f32 v[220:221], v[220:221], v[216:217]
	ds_read_b128 v[252:255], v163 offset:2240
	s_waitcnt lgkmcnt(3)
	v_lshlrev_b32_e32 v216, 16, v238
	v_and_b32_e32 v217, 0xffff0000, v238
	v_pk_add_f32 v[106:107], v[106:107], v[216:217]
	v_lshlrev_b32_e32 v216, 16, v239
	v_and_b32_e32 v217, 0xffff0000, v239
	v_pk_add_f32 v[108:109], v[108:109], v[216:217]
	v_lshlrev_b32_e32 v216, 16, v240
	v_and_b32_e32 v217, 0xffff0000, v240
	v_pk_add_f32 v[218:219], v[218:219], v[216:217]
	v_lshlrev_b32_e32 v216, 16, v241
	v_and_b32_e32 v217, 0xffff0000, v241
	v_pk_add_f32 v[220:221], v[220:221], v[216:217]
	ds_read_b128 v[238:241], v163 offset:4176
	s_waitcnt lgkmcnt(3)
	v_lshlrev_b32_e32 v216, 16, v242
	v_and_b32_e32 v217, 0xffff0000, v242
	v_pk_add_f32 v[106:107], v[106:107], v[216:217]
	v_lshlrev_b32_e32 v216, 16, v243
	v_and_b32_e32 v217, 0xffff0000, v243
	v_pk_add_f32 v[108:109], v[108:109], v[216:217]
	v_lshlrev_b32_e32 v216, 16, v244
	v_and_b32_e32 v217, 0xffff0000, v244
	v_pk_add_f32 v[218:219], v[218:219], v[216:217]
	v_lshlrev_b32_e32 v216, 16, v245
	v_and_b32_e32 v217, 0xffff0000, v245
	v_pk_add_f32 v[220:221], v[220:221], v[216:217]
	ds_read_b128 v[242:245], v163 offset:3904
	s_waitcnt lgkmcnt(3)
	v_lshlrev_b32_e32 v216, 16, v248
	v_and_b32_e32 v217, 0xffff0000, v248
	v_pk_add_f32 v[106:107], v[106:107], v[216:217]
	v_lshlrev_b32_e32 v216, 16, v249
	v_and_b32_e32 v217, 0xffff0000, v249
	v_pk_add_f32 v[108:109], v[108:109], v[216:217]
	v_lshlrev_b32_e32 v216, 16, v250
	v_and_b32_e32 v217, 0xffff0000, v250
	v_pk_add_f32 v[218:219], v[218:219], v[216:217]
	v_lshlrev_b32_e32 v216, 16, v251
	v_and_b32_e32 v217, 0xffff0000, v251
	v_pk_add_f32 v[220:221], v[220:221], v[216:217]
	ds_read_b128 v[248:251], v163 offset:3632
	s_waitcnt lgkmcnt(3)
	v_lshlrev_b32_e32 v216, 16, v252
	v_and_b32_e32 v217, 0xffff0000, v252
	v_pk_add_f32 v[106:107], v[106:107], v[216:217]
	v_lshlrev_b32_e32 v216, 16, v253
	v_and_b32_e32 v217, 0xffff0000, v253
	v_pk_add_f32 v[108:109], v[108:109], v[216:217]
	v_lshlrev_b32_e32 v216, 16, v254
	v_and_b32_e32 v217, 0xffff0000, v254
	v_pk_add_f32 v[218:219], v[218:219], v[216:217]
	v_lshlrev_b32_e32 v216, 16, v255
	v_and_b32_e32 v217, 0xffff0000, v255
	v_pk_add_f32 v[220:221], v[220:221], v[216:217]
	ds_read_b128 v[252:255], v163 offset:3360
	v_fma_f32 v106, v159, v106, -v98
	v_fma_f32 v107, v159, v107, -v99
	v_fma_f32 v108, v159, v108, -v100
	v_fma_f32 v109, v159, v109, -v101
	v_fma_f32 v218, v159, v218, -v102
	v_fma_f32 v219, v159, v219, -v103
	v_fma_f32 v220, v159, v220, -v104
	v_fma_f32 v221, v159, v221, -v105
	v_cvt_pk_bf16_f32 v106, v106, v107
	v_cvt_pk_bf16_f32 v107, v108, v109
	v_cvt_pk_bf16_f32 v108, v218, v219
	v_cvt_pk_bf16_f32 v109, v220, v221
	s_and_saveexec_b64 s[28:29], s[6:7]
	s_cbranch_execz .Lpu1_2
	global_store_dwordx4 v[192:193], v[98:101], off offset:128
	global_store_dwordx4 v[192:193], v[102:105], off offset:144
.Lpu1_2:
	s_or_b64 exec, exec, s[28:29]
	s_waitcnt vmcnt(8)
	v_mfma_f32_32x32x16_bf16 v[2:17], v[106:109], v[222:225], v[2:17]
	v_mfma_f32_32x32x16_bf16 v[18:33], v[106:109], v[226:229], v[18:33]
	v_mfma_f32_32x32x16_bf16 v[34:49], v[106:109], v[230:233], v[34:49]
	v_mfma_f32_32x32x16_bf16 v[50:65], v[106:109], v[234:237], v[50:65]
	global_load_dwordx4 v[222:225], v[112:113], off offset:2560
	global_load_dwordx4 v[226:229], v[114:115], off offset:2560
	global_load_dwordx4 v[230:233], v[116:117], off offset:2560
	global_load_dwordx4 v[234:237], v[118:119], off offset:2560
	s_waitcnt lgkmcnt(3)
	v_lshlrev_b32_e32 v98, 16, v238
	v_and_b32_e32 v99, 0xffff0000, v238
	v_lshlrev_b32_e32 v100, 16, v239
	v_and_b32_e32 v101, 0xffff0000, v239
	v_lshlrev_b32_e32 v102, 16, v240
	v_and_b32_e32 v103, 0xffff0000, v240
	v_lshlrev_b32_e32 v104, 16, v241
	v_and_b32_e32 v105, 0xffff0000, v241
	ds_read_b128 v[238:241], v163 offset:3088
	s_waitcnt lgkmcnt(3)
	v_lshlrev_b32_e32 v216, 16, v242
	v_and_b32_e32 v217, 0xffff0000, v242
	v_pk_add_f32 v[106:107], v[98:99], v[216:217]
	v_lshlrev_b32_e32 v216, 16, v243
	v_and_b32_e32 v217, 0xffff0000, v243
	v_pk_add_f32 v[108:109], v[100:101], v[216:217]
	v_lshlrev_b32_e32 v216, 16, v244
	v_and_b32_e32 v217, 0xffff0000, v244
	v_pk_add_f32 v[218:219], v[102:103], v[216:217]
	v_lshlrev_b32_e32 v216, 16, v245
	v_and_b32_e32 v217, 0xffff0000, v245
	v_pk_add_f32 v[220:221], v[104:105], v[216:217]
	ds_read_b128 v[242:245], v163 offset:2816
	s_waitcnt lgkmcnt(3)
	v_lshlrev_b32_e32 v216, 16, v248
	v_and_b32_e32 v217, 0xffff0000, v248
	v_pk_add_f32 v[106:107], v[106:107], v[216:217]
	v_lshlrev_b32_e32 v216, 16, v249
	v_and_b32_e32 v217, 0xffff0000, v249
	v_pk_add_f32 v[108:109], v[108:109], v[216:217]
	v_lshlrev_b32_e32 v216, 16, v250
	v_and_b32_e32 v217, 0xffff0000, v250
	v_pk_add_f32 v[218:219], v[218:219], v[216:217]
	v_lshlrev_b32_e32 v216, 16, v251
	v_and_b32_e32 v217, 0xffff0000, v251
	v_pk_add_f32 v[220:221], v[220:221], v[216:217]
	ds_read_b128 v[248:251], v163 offset:2544
	s_waitcnt lgkmcnt(3)
	v_lshlrev_b32_e32 v216, 16, v252
	v_and_b32_e32 v217, 0xffff0000, v252
	v_pk_add_f32 v[106:107], v[106:107], v[216:217]
	v_lshlrev_b32_e32 v216, 16, v253
	v_and_b32_e32 v217, 0xffff0000, v253
	v_pk_add_f32 v[108:109], v[108:109], v[216:217]
	v_lshlrev_b32_e32 v216, 16, v254
	v_and_b32_e32 v217, 0xffff0000, v254
	v_pk_add_f32 v[218:219], v[218:219], v[216:217]
	v_lshlrev_b32_e32 v216, 16, v255
	v_and_b32_e32 v217, 0xffff0000, v255
	v_pk_add_f32 v[220:221], v[220:221], v[216:217]
	ds_read_b128 v[252:255], v163 offset:2272
	s_waitcnt lgkmcnt(3)
	v_lshlrev_b32_e32 v216, 16, v238
	v_and_b32_e32 v217, 0xffff0000, v238
	v_pk_add_f32 v[106:107], v[106:107], v[216:217]
	v_lshlrev_b32_e32 v216, 16, v239
	v_and_b32_e32 v217, 0xffff0000, v239
	v_pk_add_f32 v[108:109], v[108:109], v[216:217]
	v_lshlrev_b32_e32 v216, 16, v240
	v_and_b32_e32 v217, 0xffff0000, v240
	v_pk_add_f32 v[218:219], v[218:219], v[216:217]
	v_lshlrev_b32_e32 v216, 16, v241
	v_and_b32_e32 v217, 0xffff0000, v241
	v_pk_add_f32 v[220:221], v[220:221], v[216:217]
	ds_read_b128 v[238:241], v163 offset:4208
	s_waitcnt lgkmcnt(3)
	v_lshlrev_b32_e32 v216, 16, v242
	v_and_b32_e32 v217, 0xffff0000, v242
	v_pk_add_f32 v[106:107], v[106:107], v[216:217]
	v_lshlrev_b32_e32 v216, 16, v243
	v_and_b32_e32 v217, 0xffff0000, v243
	v_pk_add_f32 v[108:109], v[108:109], v[216:217]
	v_lshlrev_b32_e32 v216, 16, v244
	v_and_b32_e32 v217, 0xffff0000, v244
	v_pk_add_f32 v[218:219], v[218:219], v[216:217]
	v_lshlrev_b32_e32 v216, 16, v245
	v_and_b32_e32 v217, 0xffff0000, v245
	v_pk_add_f32 v[220:221], v[220:221], v[216:217]
	ds_read_b128 v[242:245], v163 offset:3936
	s_waitcnt lgkmcnt(3)
	v_lshlrev_b32_e32 v216, 16, v248
	v_and_b32_e32 v217, 0xffff0000, v248
	v_pk_add_f32 v[106:107], v[106:107], v[216:217]
	v_lshlrev_b32_e32 v216, 16, v249
	v_and_b32_e32 v217, 0xffff0000, v249
	v_pk_add_f32 v[108:109], v[108:109], v[216:217]
	v_lshlrev_b32_e32 v216, 16, v250
	v_and_b32_e32 v217, 0xffff0000, v250
	v_pk_add_f32 v[218:219], v[218:219], v[216:217]
	v_lshlrev_b32_e32 v216, 16, v251
	v_and_b32_e32 v217, 0xffff0000, v251
	v_pk_add_f32 v[220:221], v[220:221], v[216:217]
	ds_read_b128 v[248:251], v163 offset:3664
	s_waitcnt lgkmcnt(3)
	v_lshlrev_b32_e32 v216, 16, v252
	v_and_b32_e32 v217, 0xffff0000, v252
	v_pk_add_f32 v[106:107], v[106:107], v[216:217]
	v_lshlrev_b32_e32 v216, 16, v253
	v_and_b32_e32 v217, 0xffff0000, v253
	v_pk_add_f32 v[108:109], v[108:109], v[216:217]
	v_lshlrev_b32_e32 v216, 16, v254
	v_and_b32_e32 v217, 0xffff0000, v254
	v_pk_add_f32 v[218:219], v[218:219], v[216:217]
	v_lshlrev_b32_e32 v216, 16, v255
	v_and_b32_e32 v217, 0xffff0000, v255
	v_pk_add_f32 v[220:221], v[220:221], v[216:217]
	ds_read_b128 v[252:255], v163 offset:3392
	v_fma_f32 v106, v159, v106, -v98
	v_fma_f32 v107, v159, v107, -v99
	v_fma_f32 v108, v159, v108, -v100
	v_fma_f32 v109, v159, v109, -v101
	v_fma_f32 v218, v159, v218, -v102
	v_fma_f32 v219, v159, v219, -v103
	v_fma_f32 v220, v159, v220, -v104
	v_fma_f32 v221, v159, v221, -v105
	v_cvt_pk_bf16_f32 v106, v106, v107
	v_cvt_pk_bf16_f32 v107, v108, v109
	v_cvt_pk_bf16_f32 v108, v218, v219
	v_cvt_pk_bf16_f32 v109, v220, v221
	s_and_saveexec_b64 s[28:29], s[6:7]
	s_cbranch_execz .Lpu1_3
	global_store_dwordx4 v[192:193], v[98:101], off offset:192
	global_store_dwordx4 v[192:193], v[102:105], off offset:208
.Lpu1_3:
	s_or_b64 exec, exec, s[28:29]
	s_waitcnt vmcnt(8)
	v_mfma_f32_32x32x16_bf16 v[2:17], v[106:109], v[70:73], v[2:17]
	v_mfma_f32_32x32x16_bf16 v[18:33], v[106:109], v[74:77], v[18:33]
	v_mfma_f32_32x32x16_bf16 v[34:49], v[106:109], v[78:81], v[34:49]
	v_mfma_f32_32x32x16_bf16 v[50:65], v[106:109], v[66:69], v[50:65]
	global_load_dwordx4 v[70:73], v[112:113], off offset:3072
	global_load_dwordx4 v[74:77], v[114:115], off offset:3072
	global_load_dwordx4 v[78:81], v[116:117], off offset:3072
	global_load_dwordx4 v[66:69], v[118:119], off offset:3072
	s_waitcnt lgkmcnt(3)
	v_lshlrev_b32_e32 v98, 16, v238
	v_and_b32_e32 v99, 0xffff0000, v238
	v_lshlrev_b32_e32 v100, 16, v239
	v_and_b32_e32 v101, 0xffff0000, v239
	v_lshlrev_b32_e32 v102, 16, v240
	v_and_b32_e32 v103, 0xffff0000, v240
	v_lshlrev_b32_e32 v104, 16, v241
	v_and_b32_e32 v105, 0xffff0000, v241
	ds_read_b128 v[238:241], v163 offset:3120
	s_waitcnt lgkmcnt(3)
	v_lshlrev_b32_e32 v216, 16, v242
	v_and_b32_e32 v217, 0xffff0000, v242
	v_pk_add_f32 v[106:107], v[98:99], v[216:217]
	v_lshlrev_b32_e32 v216, 16, v243
	v_and_b32_e32 v217, 0xffff0000, v243
	v_pk_add_f32 v[108:109], v[100:101], v[216:217]
	v_lshlrev_b32_e32 v216, 16, v244
	v_and_b32_e32 v217, 0xffff0000, v244
	v_pk_add_f32 v[218:219], v[102:103], v[216:217]
	v_lshlrev_b32_e32 v216, 16, v245
	v_and_b32_e32 v217, 0xffff0000, v245
	v_pk_add_f32 v[220:221], v[104:105], v[216:217]
	ds_read_b128 v[242:245], v163 offset:2848
	s_waitcnt lgkmcnt(3)
	v_lshlrev_b32_e32 v216, 16, v248
	v_and_b32_e32 v217, 0xffff0000, v248
	v_pk_add_f32 v[106:107], v[106:107], v[216:217]
	v_lshlrev_b32_e32 v216, 16, v249
	v_and_b32_e32 v217, 0xffff0000, v249
	v_pk_add_f32 v[108:109], v[108:109], v[216:217]
	v_lshlrev_b32_e32 v216, 16, v250
	v_and_b32_e32 v217, 0xffff0000, v250
	v_pk_add_f32 v[218:219], v[218:219], v[216:217]
	v_lshlrev_b32_e32 v216, 16, v251
	v_and_b32_e32 v217, 0xffff0000, v251
	v_pk_add_f32 v[220:221], v[220:221], v[216:217]
	ds_read_b128 v[248:251], v163 offset:2576
	s_waitcnt lgkmcnt(3)
	v_lshlrev_b32_e32 v216, 16, v252
	v_and_b32_e32 v217, 0xffff0000, v252
	v_pk_add_f32 v[106:107], v[106:107], v[216:217]
	v_lshlrev_b32_e32 v216, 16, v253
	v_and_b32_e32 v217, 0xffff0000, v253
	v_pk_add_f32 v[108:109], v[108:109], v[216:217]
	v_lshlrev_b32_e32 v216, 16, v254
	v_and_b32_e32 v217, 0xffff0000, v254
	v_pk_add_f32 v[218:219], v[218:219], v[216:217]
	v_lshlrev_b32_e32 v216, 16, v255
	v_and_b32_e32 v217, 0xffff0000, v255
	v_pk_add_f32 v[220:221], v[220:221], v[216:217]
	ds_read_b128 v[252:255], v163 offset:2304
	s_waitcnt lgkmcnt(3)
	v_lshlrev_b32_e32 v216, 16, v238
	v_and_b32_e32 v217, 0xffff0000, v238
	v_pk_add_f32 v[106:107], v[106:107], v[216:217]
	v_lshlrev_b32_e32 v216, 16, v239
	v_and_b32_e32 v217, 0xffff0000, v239
	v_pk_add_f32 v[108:109], v[108:109], v[216:217]
	v_lshlrev_b32_e32 v216, 16, v240
	v_and_b32_e32 v217, 0xffff0000, v240
	v_pk_add_f32 v[218:219], v[218:219], v[216:217]
	v_lshlrev_b32_e32 v216, 16, v241
	v_and_b32_e32 v217, 0xffff0000, v241
	v_pk_add_f32 v[220:221], v[220:221], v[216:217]
	ds_read_b128 v[238:241], v163 offset:4240
	s_waitcnt lgkmcnt(3)
	v_lshlrev_b32_e32 v216, 16, v242
	v_and_b32_e32 v217, 0xffff0000, v242
	v_pk_add_f32 v[106:107], v[106:107], v[216:217]
	v_lshlrev_b32_e32 v216, 16, v243
	v_and_b32_e32 v217, 0xffff0000, v243
	v_pk_add_f32 v[108:109], v[108:109], v[216:217]
	v_lshlrev_b32_e32 v216, 16, v244
	v_and_b32_e32 v217, 0xffff0000, v244
	v_pk_add_f32 v[218:219], v[218:219], v[216:217]
	v_lshlrev_b32_e32 v216, 16, v245
	v_and_b32_e32 v217, 0xffff0000, v245
	v_pk_add_f32 v[220:221], v[220:221], v[216:217]
	ds_read_b128 v[242:245], v163 offset:3968
	s_waitcnt lgkmcnt(3)
	v_lshlrev_b32_e32 v216, 16, v248
	v_and_b32_e32 v217, 0xffff0000, v248
	v_pk_add_f32 v[106:107], v[106:107], v[216:217]
	v_lshlrev_b32_e32 v216, 16, v249
	v_and_b32_e32 v217, 0xffff0000, v249
	v_pk_add_f32 v[108:109], v[108:109], v[216:217]
	v_lshlrev_b32_e32 v216, 16, v250
	v_and_b32_e32 v217, 0xffff0000, v250
	v_pk_add_f32 v[218:219], v[218:219], v[216:217]
	v_lshlrev_b32_e32 v216, 16, v251
	v_and_b32_e32 v217, 0xffff0000, v251
	v_pk_add_f32 v[220:221], v[220:221], v[216:217]
	ds_read_b128 v[248:251], v163 offset:3696
	s_waitcnt lgkmcnt(3)
	v_lshlrev_b32_e32 v216, 16, v252
	v_and_b32_e32 v217, 0xffff0000, v252
	v_pk_add_f32 v[106:107], v[106:107], v[216:217]
	v_lshlrev_b32_e32 v216, 16, v253
	v_and_b32_e32 v217, 0xffff0000, v253
	v_pk_add_f32 v[108:109], v[108:109], v[216:217]
	v_lshlrev_b32_e32 v216, 16, v254
	v_and_b32_e32 v217, 0xffff0000, v254
	v_pk_add_f32 v[218:219], v[218:219], v[216:217]
	v_lshlrev_b32_e32 v216, 16, v255
	v_and_b32_e32 v217, 0xffff0000, v255
	v_pk_add_f32 v[220:221], v[220:221], v[216:217]
	ds_read_b128 v[252:255], v163 offset:3424
	v_fma_f32 v106, v159, v106, -v98
	v_fma_f32 v107, v159, v107, -v99
	v_fma_f32 v108, v159, v108, -v100
	v_fma_f32 v109, v159, v109, -v101
	v_fma_f32 v218, v159, v218, -v102
	v_fma_f32 v219, v159, v219, -v103
	v_fma_f32 v220, v159, v220, -v104
	v_fma_f32 v221, v159, v221, -v105
	v_cvt_pk_bf16_f32 v106, v106, v107
	v_cvt_pk_bf16_f32 v107, v108, v109
	v_cvt_pk_bf16_f32 v108, v218, v219
	v_cvt_pk_bf16_f32 v109, v220, v221
	s_and_saveexec_b64 s[28:29], s[6:7]
	s_cbranch_execz .Lpu1_4
	global_store_dwordx4 v[192:193], v[98:101], off offset:256
	global_store_dwordx4 v[192:193], v[102:105], off offset:272
.Lpu1_4:
	s_or_b64 exec, exec, s[28:29]
	s_waitcnt vmcnt(8)
	v_mfma_f32_32x32x16_bf16 v[2:17], v[106:109], v[82:85], v[2:17]
	v_mfma_f32_32x32x16_bf16 v[18:33], v[106:109], v[86:89], v[18:33]
	v_mfma_f32_32x32x16_bf16 v[34:49], v[106:109], v[90:93], v[34:49]
	v_mfma_f32_32x32x16_bf16 v[50:65], v[106:109], v[94:97], v[50:65]
	global_load_dwordx4 v[82:85], v[112:113], off offset:3584
	global_load_dwordx4 v[86:89], v[114:115], off offset:3584
	global_load_dwordx4 v[90:93], v[116:117], off offset:3584
	global_load_dwordx4 v[94:97], v[118:119], off offset:3584
	s_waitcnt lgkmcnt(3)
	v_lshlrev_b32_e32 v98, 16, v238
	v_and_b32_e32 v99, 0xffff0000, v238
	v_lshlrev_b32_e32 v100, 16, v239
	v_and_b32_e32 v101, 0xffff0000, v239
	v_lshlrev_b32_e32 v102, 16, v240
	v_and_b32_e32 v103, 0xffff0000, v240
	v_lshlrev_b32_e32 v104, 16, v241
	v_and_b32_e32 v105, 0xffff0000, v241
	ds_read_b128 v[238:241], v163 offset:3152
	s_waitcnt lgkmcnt(3)
	v_lshlrev_b32_e32 v216, 16, v242
	v_and_b32_e32 v217, 0xffff0000, v242
	v_pk_add_f32 v[106:107], v[98:99], v[216:217]
	v_lshlrev_b32_e32 v216, 16, v243
	v_and_b32_e32 v217, 0xffff0000, v243
	v_pk_add_f32 v[108:109], v[100:101], v[216:217]
	v_lshlrev_b32_e32 v216, 16, v244
	v_and_b32_e32 v217, 0xffff0000, v244
	v_pk_add_f32 v[218:219], v[102:103], v[216:217]
	v_lshlrev_b32_e32 v216, 16, v245
	v_and_b32_e32 v217, 0xffff0000, v245
	v_pk_add_f32 v[220:221], v[104:105], v[216:217]
	ds_read_b128 v[242:245], v163 offset:2880
	s_waitcnt lgkmcnt(3)
	v_lshlrev_b32_e32 v216, 16, v248
	v_and_b32_e32 v217, 0xffff0000, v248
	v_pk_add_f32 v[106:107], v[106:107], v[216:217]
	v_lshlrev_b32_e32 v216, 16, v249
	v_and_b32_e32 v217, 0xffff0000, v249
	v_pk_add_f32 v[108:109], v[108:109], v[216:217]
	v_lshlrev_b32_e32 v216, 16, v250
	v_and_b32_e32 v217, 0xffff0000, v250
	v_pk_add_f32 v[218:219], v[218:219], v[216:217]
	v_lshlrev_b32_e32 v216, 16, v251
	v_and_b32_e32 v217, 0xffff0000, v251
	v_pk_add_f32 v[220:221], v[220:221], v[216:217]
	ds_read_b128 v[248:251], v163 offset:2608
	s_waitcnt lgkmcnt(3)
	v_lshlrev_b32_e32 v216, 16, v252
	v_and_b32_e32 v217, 0xffff0000, v252
	v_pk_add_f32 v[106:107], v[106:107], v[216:217]
	v_lshlrev_b32_e32 v216, 16, v253
	v_and_b32_e32 v217, 0xffff0000, v253
	v_pk_add_f32 v[108:109], v[108:109], v[216:217]
	v_lshlrev_b32_e32 v216, 16, v254
	v_and_b32_e32 v217, 0xffff0000, v254
	v_pk_add_f32 v[218:219], v[218:219], v[216:217]
	v_lshlrev_b32_e32 v216, 16, v255
	v_and_b32_e32 v217, 0xffff0000, v255
	v_pk_add_f32 v[220:221], v[220:221], v[216:217]
	ds_read_b128 v[252:255], v163 offset:2336
	s_waitcnt lgkmcnt(3)
	v_lshlrev_b32_e32 v216, 16, v238
	v_and_b32_e32 v217, 0xffff0000, v238
	v_pk_add_f32 v[106:107], v[106:107], v[216:217]
	v_lshlrev_b32_e32 v216, 16, v239
	v_and_b32_e32 v217, 0xffff0000, v239
	v_pk_add_f32 v[108:109], v[108:109], v[216:217]
	v_lshlrev_b32_e32 v216, 16, v240
	v_and_b32_e32 v217, 0xffff0000, v240
	v_pk_add_f32 v[218:219], v[218:219], v[216:217]
	v_lshlrev_b32_e32 v216, 16, v241
	v_and_b32_e32 v217, 0xffff0000, v241
	v_pk_add_f32 v[220:221], v[220:221], v[216:217]
	ds_read_b128 v[238:241], v163 offset:4272
	s_waitcnt lgkmcnt(3)
	v_lshlrev_b32_e32 v216, 16, v242
	v_and_b32_e32 v217, 0xffff0000, v242
	v_pk_add_f32 v[106:107], v[106:107], v[216:217]
	v_lshlrev_b32_e32 v216, 16, v243
	v_and_b32_e32 v217, 0xffff0000, v243
	v_pk_add_f32 v[108:109], v[108:109], v[216:217]
	v_lshlrev_b32_e32 v216, 16, v244
	v_and_b32_e32 v217, 0xffff0000, v244
	v_pk_add_f32 v[218:219], v[218:219], v[216:217]
	v_lshlrev_b32_e32 v216, 16, v245
	v_and_b32_e32 v217, 0xffff0000, v245
	v_pk_add_f32 v[220:221], v[220:221], v[216:217]
	ds_read_b128 v[242:245], v163 offset:4000
	s_waitcnt lgkmcnt(3)
	v_lshlrev_b32_e32 v216, 16, v248
	v_and_b32_e32 v217, 0xffff0000, v248
	v_pk_add_f32 v[106:107], v[106:107], v[216:217]
	v_lshlrev_b32_e32 v216, 16, v249
	v_and_b32_e32 v217, 0xffff0000, v249
	v_pk_add_f32 v[108:109], v[108:109], v[216:217]
	v_lshlrev_b32_e32 v216, 16, v250
	v_and_b32_e32 v217, 0xffff0000, v250
	v_pk_add_f32 v[218:219], v[218:219], v[216:217]
	v_lshlrev_b32_e32 v216, 16, v251
	v_and_b32_e32 v217, 0xffff0000, v251
	v_pk_add_f32 v[220:221], v[220:221], v[216:217]
	ds_read_b128 v[248:251], v163 offset:3728
	s_waitcnt lgkmcnt(3)
	v_lshlrev_b32_e32 v216, 16, v252
	v_and_b32_e32 v217, 0xffff0000, v252
	v_pk_add_f32 v[106:107], v[106:107], v[216:217]
	v_lshlrev_b32_e32 v216, 16, v253
	v_and_b32_e32 v217, 0xffff0000, v253
	v_pk_add_f32 v[108:109], v[108:109], v[216:217]
	v_lshlrev_b32_e32 v216, 16, v254
	v_and_b32_e32 v217, 0xffff0000, v254
	v_pk_add_f32 v[218:219], v[218:219], v[216:217]
	v_lshlrev_b32_e32 v216, 16, v255
	v_and_b32_e32 v217, 0xffff0000, v255
	v_pk_add_f32 v[220:221], v[220:221], v[216:217]
	ds_read_b128 v[252:255], v163 offset:3456
	v_fma_f32 v106, v159, v106, -v98
	v_fma_f32 v107, v159, v107, -v99
	v_fma_f32 v108, v159, v108, -v100
	v_fma_f32 v109, v159, v109, -v101
	v_fma_f32 v218, v159, v218, -v102
	v_fma_f32 v219, v159, v219, -v103
	v_fma_f32 v220, v159, v220, -v104
	v_fma_f32 v221, v159, v221, -v105
	v_cvt_pk_bf16_f32 v106, v106, v107
	v_cvt_pk_bf16_f32 v107, v108, v109
	v_cvt_pk_bf16_f32 v108, v218, v219
	v_cvt_pk_bf16_f32 v109, v220, v221
	s_and_saveexec_b64 s[28:29], s[6:7]
	s_cbranch_execz .Lpu1_5
	global_store_dwordx4 v[192:193], v[98:101], off offset:320
	global_store_dwordx4 v[192:193], v[102:105], off offset:336
.Lpu1_5:
	s_or_b64 exec, exec, s[28:29]
	s_waitcnt vmcnt(8)
	v_mfma_f32_32x32x16_bf16 v[2:17], v[106:109], v[222:225], v[2:17]
	v_mfma_f32_32x32x16_bf16 v[18:33], v[106:109], v[226:229], v[18:33]
	v_mfma_f32_32x32x16_bf16 v[34:49], v[106:109], v[230:233], v[34:49]
	v_mfma_f32_32x32x16_bf16 v[50:65], v[106:109], v[234:237], v[50:65]
	s_waitcnt lgkmcnt(3)
	v_lshlrev_b32_e32 v98, 16, v238
	v_and_b32_e32 v99, 0xffff0000, v238
	v_lshlrev_b32_e32 v100, 16, v239
	v_and_b32_e32 v101, 0xffff0000, v239
	v_lshlrev_b32_e32 v102, 16, v240
	v_and_b32_e32 v103, 0xffff0000, v240
	v_lshlrev_b32_e32 v104, 16, v241
	v_and_b32_e32 v105, 0xffff0000, v241
	ds_read_b128 v[238:241], v163 offset:3184
	s_waitcnt lgkmcnt(3)
	v_lshlrev_b32_e32 v216, 16, v242
	v_and_b32_e32 v217, 0xffff0000, v242
	v_pk_add_f32 v[106:107], v[98:99], v[216:217]
	v_lshlrev_b32_e32 v216, 16, v243
	v_and_b32_e32 v217, 0xffff0000, v243
	v_pk_add_f32 v[108:109], v[100:101], v[216:217]
	v_lshlrev_b32_e32 v216, 16, v244
	v_and_b32_e32 v217, 0xffff0000, v244
	v_pk_add_f32 v[218:219], v[102:103], v[216:217]
	v_lshlrev_b32_e32 v216, 16, v245
	v_and_b32_e32 v217, 0xffff0000, v245
	v_pk_add_f32 v[220:221], v[104:105], v[216:217]
	ds_read_b128 v[242:245], v163 offset:2912
	s_waitcnt lgkmcnt(3)
	v_lshlrev_b32_e32 v216, 16, v248
	v_and_b32_e32 v217, 0xffff0000, v248
	v_pk_add_f32 v[106:107], v[106:107], v[216:217]
	v_lshlrev_b32_e32 v216, 16, v249
	v_and_b32_e32 v217, 0xffff0000, v249
	v_pk_add_f32 v[108:109], v[108:109], v[216:217]
	v_lshlrev_b32_e32 v216, 16, v250
	v_and_b32_e32 v217, 0xffff0000, v250
	v_pk_add_f32 v[218:219], v[218:219], v[216:217]
	v_lshlrev_b32_e32 v216, 16, v251
	v_and_b32_e32 v217, 0xffff0000, v251
	v_pk_add_f32 v[220:221], v[220:221], v[216:217]
	ds_read_b128 v[248:251], v163 offset:2640
	s_waitcnt lgkmcnt(3)
	v_lshlrev_b32_e32 v216, 16, v252
	v_and_b32_e32 v217, 0xffff0000, v252
	v_pk_add_f32 v[106:107], v[106:107], v[216:217]
	v_lshlrev_b32_e32 v216, 16, v253
	v_and_b32_e32 v217, 0xffff0000, v253
	v_pk_add_f32 v[108:109], v[108:109], v[216:217]
	v_lshlrev_b32_e32 v216, 16, v254
	v_and_b32_e32 v217, 0xffff0000, v254
	v_pk_add_f32 v[218:219], v[218:219], v[216:217]
	v_lshlrev_b32_e32 v216, 16, v255
	v_and_b32_e32 v217, 0xffff0000, v255
	v_pk_add_f32 v[220:221], v[220:221], v[216:217]
	ds_read_b128 v[252:255], v163 offset:2368
	s_waitcnt lgkmcnt(3)
	v_lshlrev_b32_e32 v216, 16, v238
	v_and_b32_e32 v217, 0xffff0000, v238
	v_pk_add_f32 v[106:107], v[106:107], v[216:217]
	v_lshlrev_b32_e32 v216, 16, v239
	v_and_b32_e32 v217, 0xffff0000, v239
	v_pk_add_f32 v[108:109], v[108:109], v[216:217]
	v_lshlrev_b32_e32 v216, 16, v240
	v_and_b32_e32 v217, 0xffff0000, v240
	v_pk_add_f32 v[218:219], v[218:219], v[216:217]
	v_lshlrev_b32_e32 v216, 16, v241
	v_and_b32_e32 v217, 0xffff0000, v241
	v_pk_add_f32 v[220:221], v[220:221], v[216:217]
	ds_read_b128 v[238:241], v163 offset:4304
	s_waitcnt lgkmcnt(3)
	v_lshlrev_b32_e32 v216, 16, v242
	v_and_b32_e32 v217, 0xffff0000, v242
	v_pk_add_f32 v[106:107], v[106:107], v[216:217]
	v_lshlrev_b32_e32 v216, 16, v243
	v_and_b32_e32 v217, 0xffff0000, v243
	v_pk_add_f32 v[108:109], v[108:109], v[216:217]
	v_lshlrev_b32_e32 v216, 16, v244
	v_and_b32_e32 v217, 0xffff0000, v244
	v_pk_add_f32 v[218:219], v[218:219], v[216:217]
	v_lshlrev_b32_e32 v216, 16, v245
	v_and_b32_e32 v217, 0xffff0000, v245
	v_pk_add_f32 v[220:221], v[220:221], v[216:217]
	ds_read_b128 v[242:245], v163 offset:4032
	s_waitcnt lgkmcnt(3)
	v_lshlrev_b32_e32 v216, 16, v248
	v_and_b32_e32 v217, 0xffff0000, v248
	v_pk_add_f32 v[106:107], v[106:107], v[216:217]
	v_lshlrev_b32_e32 v216, 16, v249
	v_and_b32_e32 v217, 0xffff0000, v249
	v_pk_add_f32 v[108:109], v[108:109], v[216:217]
	v_lshlrev_b32_e32 v216, 16, v250
	v_and_b32_e32 v217, 0xffff0000, v250
	v_pk_add_f32 v[218:219], v[218:219], v[216:217]
	v_lshlrev_b32_e32 v216, 16, v251
	v_and_b32_e32 v217, 0xffff0000, v251
	v_pk_add_f32 v[220:221], v[220:221], v[216:217]
	ds_read_b128 v[248:251], v163 offset:3760
	s_waitcnt lgkmcnt(3)
	v_lshlrev_b32_e32 v216, 16, v252
	v_and_b32_e32 v217, 0xffff0000, v252
	v_pk_add_f32 v[106:107], v[106:107], v[216:217]
	v_lshlrev_b32_e32 v216, 16, v253
	v_and_b32_e32 v217, 0xffff0000, v253
	v_pk_add_f32 v[108:109], v[108:109], v[216:217]
	v_lshlrev_b32_e32 v216, 16, v254
	v_and_b32_e32 v217, 0xffff0000, v254
	v_pk_add_f32 v[218:219], v[218:219], v[216:217]
	v_lshlrev_b32_e32 v216, 16, v255
	v_and_b32_e32 v217, 0xffff0000, v255
	v_pk_add_f32 v[220:221], v[220:221], v[216:217]
	ds_read_b128 v[252:255], v163 offset:3488
	v_fma_f32 v106, v159, v106, -v98
	v_fma_f32 v107, v159, v107, -v99
	v_fma_f32 v108, v159, v108, -v100
	v_fma_f32 v109, v159, v109, -v101
	v_fma_f32 v218, v159, v218, -v102
	v_fma_f32 v219, v159, v219, -v103
	v_fma_f32 v220, v159, v220, -v104
	v_fma_f32 v221, v159, v221, -v105
	v_cvt_pk_bf16_f32 v106, v106, v107
	v_cvt_pk_bf16_f32 v107, v108, v109
	v_cvt_pk_bf16_f32 v108, v218, v219
	v_cvt_pk_bf16_f32 v109, v220, v221
	s_and_saveexec_b64 s[28:29], s[6:7]
	s_cbranch_execz .Lpu1_6
	global_store_dwordx4 v[192:193], v[98:101], off offset:384
	global_store_dwordx4 v[192:193], v[102:105], off offset:400
.Lpu1_6:
	s_or_b64 exec, exec, s[28:29]
	s_waitcnt vmcnt(4)
	v_mfma_f32_32x32x16_bf16 v[2:17], v[106:109], v[70:73], v[2:17]
	v_mfma_f32_32x32x16_bf16 v[18:33], v[106:109], v[74:77], v[18:33]
	v_mfma_f32_32x32x16_bf16 v[34:49], v[106:109], v[78:81], v[34:49]
	v_mfma_f32_32x32x16_bf16 v[50:65], v[106:109], v[66:69], v[50:65]
	s_waitcnt lgkmcnt(3)
	v_lshlrev_b32_e32 v98, 16, v238
	v_and_b32_e32 v99, 0xffff0000, v238
	v_lshlrev_b32_e32 v100, 16, v239
	v_and_b32_e32 v101, 0xffff0000, v239
	v_lshlrev_b32_e32 v102, 16, v240
	v_and_b32_e32 v103, 0xffff0000, v240
	v_lshlrev_b32_e32 v104, 16, v241
	v_and_b32_e32 v105, 0xffff0000, v241
	ds_read_b128 v[238:241], v163 offset:3216
	s_waitcnt lgkmcnt(3)
	v_lshlrev_b32_e32 v216, 16, v242
	v_and_b32_e32 v217, 0xffff0000, v242
	v_pk_add_f32 v[106:107], v[98:99], v[216:217]
	v_lshlrev_b32_e32 v216, 16, v243
	v_and_b32_e32 v217, 0xffff0000, v243
	v_pk_add_f32 v[108:109], v[100:101], v[216:217]
	v_lshlrev_b32_e32 v216, 16, v244
	v_and_b32_e32 v217, 0xffff0000, v244
	v_pk_add_f32 v[218:219], v[102:103], v[216:217]
	v_lshlrev_b32_e32 v216, 16, v245
	v_and_b32_e32 v217, 0xffff0000, v245
	v_pk_add_f32 v[220:221], v[104:105], v[216:217]
	ds_read_b128 v[242:245], v163 offset:2944
	s_waitcnt lgkmcnt(3)
	v_lshlrev_b32_e32 v216, 16, v248
	v_and_b32_e32 v217, 0xffff0000, v248
	v_pk_add_f32 v[106:107], v[106:107], v[216:217]
	v_lshlrev_b32_e32 v216, 16, v249
	v_and_b32_e32 v217, 0xffff0000, v249
	v_pk_add_f32 v[108:109], v[108:109], v[216:217]
	v_lshlrev_b32_e32 v216, 16, v250
	v_and_b32_e32 v217, 0xffff0000, v250
	v_pk_add_f32 v[218:219], v[218:219], v[216:217]
	v_lshlrev_b32_e32 v216, 16, v251
	v_and_b32_e32 v217, 0xffff0000, v251
	v_pk_add_f32 v[220:221], v[220:221], v[216:217]
	ds_read_b128 v[248:251], v163 offset:2672
	s_waitcnt lgkmcnt(3)
	v_lshlrev_b32_e32 v216, 16, v252
	v_and_b32_e32 v217, 0xffff0000, v252
	v_pk_add_f32 v[106:107], v[106:107], v[216:217]
	v_lshlrev_b32_e32 v216, 16, v253
	v_and_b32_e32 v217, 0xffff0000, v253
	v_pk_add_f32 v[108:109], v[108:109], v[216:217]
	v_lshlrev_b32_e32 v216, 16, v254
	v_and_b32_e32 v217, 0xffff0000, v254
	v_pk_add_f32 v[218:219], v[218:219], v[216:217]
	v_lshlrev_b32_e32 v216, 16, v255
	v_and_b32_e32 v217, 0xffff0000, v255
	v_pk_add_f32 v[220:221], v[220:221], v[216:217]
	ds_read_b128 v[252:255], v163 offset:2400
	s_waitcnt lgkmcnt(3)
	v_lshlrev_b32_e32 v216, 16, v238
	v_and_b32_e32 v217, 0xffff0000, v238
	v_pk_add_f32 v[106:107], v[106:107], v[216:217]
	v_lshlrev_b32_e32 v216, 16, v239
	v_and_b32_e32 v217, 0xffff0000, v239
	v_pk_add_f32 v[108:109], v[108:109], v[216:217]
	v_lshlrev_b32_e32 v216, 16, v240
	v_and_b32_e32 v217, 0xffff0000, v240
	v_pk_add_f32 v[218:219], v[218:219], v[216:217]
	v_lshlrev_b32_e32 v216, 16, v241
	v_and_b32_e32 v217, 0xffff0000, v241
	v_pk_add_f32 v[220:221], v[220:221], v[216:217]
	s_waitcnt lgkmcnt(2)
	v_lshlrev_b32_e32 v216, 16, v242
	v_and_b32_e32 v217, 0xffff0000, v242
	v_pk_add_f32 v[106:107], v[106:107], v[216:217]
	v_lshlrev_b32_e32 v216, 16, v243
	v_and_b32_e32 v217, 0xffff0000, v243
	v_pk_add_f32 v[108:109], v[108:109], v[216:217]
	v_lshlrev_b32_e32 v216, 16, v244
	v_and_b32_e32 v217, 0xffff0000, v244
	v_pk_add_f32 v[218:219], v[218:219], v[216:217]
	v_lshlrev_b32_e32 v216, 16, v245
	v_and_b32_e32 v217, 0xffff0000, v245
	v_pk_add_f32 v[220:221], v[220:221], v[216:217]
	s_waitcnt lgkmcnt(1)
	v_lshlrev_b32_e32 v216, 16, v248
	v_and_b32_e32 v217, 0xffff0000, v248
	v_pk_add_f32 v[106:107], v[106:107], v[216:217]
	v_lshlrev_b32_e32 v216, 16, v249
	v_and_b32_e32 v217, 0xffff0000, v249
	v_pk_add_f32 v[108:109], v[108:109], v[216:217]
	v_lshlrev_b32_e32 v216, 16, v250
	v_and_b32_e32 v217, 0xffff0000, v250
	v_pk_add_f32 v[218:219], v[218:219], v[216:217]
	v_lshlrev_b32_e32 v216, 16, v251
	v_and_b32_e32 v217, 0xffff0000, v251
	v_pk_add_f32 v[220:221], v[220:221], v[216:217]
	s_waitcnt lgkmcnt(0)
	v_lshlrev_b32_e32 v216, 16, v252
	v_and_b32_e32 v217, 0xffff0000, v252
	v_pk_add_f32 v[106:107], v[106:107], v[216:217]
	v_lshlrev_b32_e32 v216, 16, v253
	v_and_b32_e32 v217, 0xffff0000, v253
	v_pk_add_f32 v[108:109], v[108:109], v[216:217]
	v_lshlrev_b32_e32 v216, 16, v254
	v_and_b32_e32 v217, 0xffff0000, v254
	v_pk_add_f32 v[218:219], v[218:219], v[216:217]
	v_lshlrev_b32_e32 v216, 16, v255
	v_and_b32_e32 v217, 0xffff0000, v255
	v_pk_add_f32 v[220:221], v[220:221], v[216:217]
	v_fma_f32 v106, v159, v106, -v98
	v_fma_f32 v107, v159, v107, -v99
	v_fma_f32 v108, v159, v108, -v100
	v_fma_f32 v109, v159, v109, -v101
	v_fma_f32 v218, v159, v218, -v102
	v_fma_f32 v219, v159, v219, -v103
	v_fma_f32 v220, v159, v220, -v104
	v_fma_f32 v221, v159, v221, -v105
	v_cvt_pk_bf16_f32 v106, v106, v107
	v_cvt_pk_bf16_f32 v107, v108, v109
	v_cvt_pk_bf16_f32 v108, v218, v219
	v_cvt_pk_bf16_f32 v109, v220, v221
	s_and_saveexec_b64 s[28:29], s[6:7]
	s_cbranch_execz .Lpu1_7
	global_store_dwordx4 v[192:193], v[98:101], off offset:448
	global_store_dwordx4 v[192:193], v[102:105], off offset:464

.LBB0_379:
	s_or_b64 exec, exec, s[6:7]
	s_waitcnt lgkmcnt(0)
	global_load_dwordx4 v[82:85], v[122:123], off offset:512
	global_load_dwordx4 v[86:89], v[124:125], off offset:512
	global_load_dwordx4 v[90:93], v[126:127], off offset:512
	global_load_dwordx4 v[94:97], v[128:129], off offset:512
	global_load_dwordx4 v[222:225], v[122:123], off offset:1024
	global_load_dwordx4 v[226:229], v[124:125], off offset:1024
	global_load_dwordx4 v[230:233], v[126:127], off offset:1024
	global_load_dwordx4 v[234:237], v[128:129], off offset:1024
	v_or_b32_e32 v2, s28, v1
	v_min_u32_e32 v3, 3, v2
	v_add_u32_e32 v3, 1, v3
	v_cvt_f32_ubyte0_e32 v3, v3
	v_div_scale_f32 v4, s[6:7], v3, v3, 1.0
	v_rcp_f32_e32 v5, v4
	s_ashr_i32 s8, s30, 6
	s_mul_i32 s10, s8, 15
	v_cmp_lt_u32_e64 s[6:7], s41, v2
	v_fma_f32 v6, -v4, v5, 1.0
	v_fmac_f32_e32 v5, v6, v5
	v_div_scale_f32 v6, vcc, 1.0, v3, 1.0
	v_mul_f32_e32 v7, v6, v5
	v_fma_f32 v8, -v4, v7, v6
	v_fmac_f32_e32 v7, v8, v5
	v_fma_f32 v4, -v4, v7, v6
	v_div_fmas_f32 v4, v4, v5, v7
	v_div_fixup_f32 v159, v4, v3, 1.0
	s_ashr_i32 s11, s10, 31
	v_add_u32_e32 v2, 0xfffff80f, v2
	v_mov_b32_e32 v3, v155
	v_lshl_add_u64 v[2:3], v[2:3], 0, s[10:11]
	v_lshlrev_b64 v[2:3], 11, v[2:3]
	v_lshl_add_u64 v[2:3], s[70:71], 0, v[2:3]
	v_mov_b32_e32 v163, v155
	v_lshl_add_u64 v[2:3], v[2:3], 0, v[162:163]
	v_lshl_add_u64 v[190:191], v[2:3], 0, s[24:25]
	v_mov_b32_e32 v2, 0
	s_mov_b32 s49, 0
	s_mov_b64 s[10:11], 0
	v_mov_b32_e32 v3, v2
	v_mov_b32_e32 v4, v2
	v_mov_b32_e32 v5, v2
	v_mov_b32_e32 v6, v2
	v_mov_b32_e32 v7, v2
	v_mov_b32_e32 v8, v2
	v_mov_b32_e32 v9, v2
	v_mov_b32_e32 v10, v2
	v_mov_b32_e32 v11, v2
	v_mov_b32_e32 v12, v2
	v_mov_b32_e32 v13, v2
	v_mov_b32_e32 v14, v2
	v_mov_b32_e32 v15, v2
	v_mov_b32_e32 v16, v2
	v_mov_b32_e32 v17, v2
	v_mov_b32_e32 v18, v2
	v_mov_b32_e32 v19, v2
	v_mov_b32_e32 v20, v2
	v_mov_b32_e32 v21, v2
	v_mov_b32_e32 v22, v2
	v_mov_b32_e32 v23, v2
	v_mov_b32_e32 v24, v2
	v_mov_b32_e32 v25, v2
	v_mov_b32_e32 v26, v2
	v_mov_b32_e32 v27, v2
	v_mov_b32_e32 v28, v2
	v_mov_b32_e32 v29, v2
	v_mov_b32_e32 v30, v2
	v_mov_b32_e32 v31, v2
	v_mov_b32_e32 v32, v2
	v_mov_b32_e32 v33, v2
	v_mov_b32_e32 v34, v2
	v_mov_b32_e32 v35, v2
	v_mov_b32_e32 v36, v2
	v_mov_b32_e32 v37, v2
	v_mov_b32_e32 v38, v2
	v_mov_b32_e32 v39, v2
	v_mov_b32_e32 v40, v2
	v_mov_b32_e32 v41, v2
	v_mov_b32_e32 v42, v2
	v_mov_b32_e32 v43, v2
	v_mov_b32_e32 v44, v2
	v_mov_b32_e32 v45, v2
	v_mov_b32_e32 v46, v2
	v_mov_b32_e32 v47, v2
	v_mov_b32_e32 v48, v2
	v_mov_b32_e32 v49, v2
	v_mov_b32_e32 v50, v2
	v_mov_b32_e32 v51, v2
	v_mov_b32_e32 v52, v2
	v_mov_b32_e32 v53, v2
	v_mov_b32_e32 v54, v2
	v_mov_b32_e32 v55, v2
	v_mov_b32_e32 v56, v2
	v_mov_b32_e32 v57, v2
	v_mov_b32_e32 v58, v2
	v_mov_b32_e32 v59, v2
	v_mov_b32_e32 v60, v2
	v_mov_b32_e32 v61, v2
	v_mov_b32_e32 v62, v2
	v_mov_b32_e32 v63, v2
	v_mov_b32_e32 v64, v2
	v_mov_b32_e32 v65, v2
	v_lshl_add_u32 v163, v197, 1, v214
	ds_read_b128 v[238:241], v163 offset:4080
	ds_read_b128 v[242:245], v163 offset:3808
	ds_read_b128 v[248:251], v163 offset:3536
	ds_read_b128 v[252:255], v163 offset:3264
	s_waitcnt lgkmcnt(3)
	v_lshlrev_b32_e32 v98, 16, v238
	v_and_b32_e32 v99, 0xffff0000, v238
	v_lshlrev_b32_e32 v100, 16, v239
	v_and_b32_e32 v101, 0xffff0000, v239
	v_lshlrev_b32_e32 v102, 16, v240
	v_and_b32_e32 v103, 0xffff0000, v240
	v_lshlrev_b32_e32 v104, 16, v241
	v_and_b32_e32 v105, 0xffff0000, v241
	ds_read_b128 v[238:241], v163 offset:4112
	s_waitcnt lgkmcnt(3)
	v_lshlrev_b32_e32 v216, 16, v242
	v_and_b32_e32 v217, 0xffff0000, v242
	v_pk_add_f32 v[106:107], v[98:99], v[216:217]
	v_lshlrev_b32_e32 v216, 16, v243
	v_and_b32_e32 v217, 0xffff0000, v243
	v_pk_add_f32 v[108:109], v[100:101], v[216:217]
	v_lshlrev_b32_e32 v216, 16, v244
	v_and_b32_e32 v217, 0xffff0000, v244
	v_pk_add_f32 v[218:219], v[102:103], v[216:217]
	v_lshlrev_b32_e32 v216, 16, v245
	v_and_b32_e32 v217, 0xffff0000, v245
	v_pk_add_f32 v[220:221], v[104:105], v[216:217]
	ds_read_b128 v[242:245], v163 offset:3840
	s_waitcnt lgkmcnt(3)
	v_lshlrev_b32_e32 v216, 16, v248
	v_and_b32_e32 v217, 0xffff0000, v248
	v_pk_add_f32 v[106:107], v[106:107], v[216:217]
	v_lshlrev_b32_e32 v216, 16, v249
	v_and_b32_e32 v217, 0xffff0000, v249
	v_pk_add_f32 v[108:109], v[108:109], v[216:217]
	v_lshlrev_b32_e32 v216, 16, v250
	v_and_b32_e32 v217, 0xffff0000, v250
	v_pk_add_f32 v[218:219], v[218:219], v[216:217]
	v_lshlrev_b32_e32 v216, 16, v251
	v_and_b32_e32 v217, 0xffff0000, v251
	v_pk_add_f32 v[220:221], v[220:221], v[216:217]
	ds_read_b128 v[248:251], v163 offset:3568
	s_waitcnt lgkmcnt(3)
	v_lshlrev_b32_e32 v216, 16, v252
	v_and_b32_e32 v217, 0xffff0000, v252
	v_pk_add_f32 v[106:107], v[106:107], v[216:217]
	v_lshlrev_b32_e32 v216, 16, v253
	v_and_b32_e32 v217, 0xffff0000, v253
	v_pk_add_f32 v[108:109], v[108:109], v[216:217]
	v_lshlrev_b32_e32 v216, 16, v254
	v_and_b32_e32 v217, 0xffff0000, v254
	v_pk_add_f32 v[218:219], v[218:219], v[216:217]
	v_lshlrev_b32_e32 v216, 16, v255
	v_and_b32_e32 v217, 0xffff0000, v255
	v_pk_add_f32 v[220:221], v[220:221], v[216:217]
	ds_read_b128 v[252:255], v163 offset:3296
	v_fma_f32 v106, v159, v106, -v98
	v_fma_f32 v107, v159, v107, -v99
	v_fma_f32 v108, v159, v108, -v100
	v_fma_f32 v109, v159, v109, -v101
	v_fma_f32 v218, v159, v218, -v102
	v_fma_f32 v219, v159, v219, -v103
	v_fma_f32 v220, v159, v220, -v104
	v_fma_f32 v221, v159, v221, -v105
	v_cvt_pk_bf16_f32 v106, v106, v107
	v_cvt_pk_bf16_f32 v107, v108, v109
	v_cvt_pk_bf16_f32 v108, v218, v219
	v_cvt_pk_bf16_f32 v109, v220, v221
	s_and_saveexec_b64 s[28:29], s[6:7]
	s_cbranch_execz .Lpu2_0
	global_store_dwordx4 v[190:191], v[98:101], off offset:0
	global_store_dwordx4 v[190:191], v[102:105], off offset:16
.Lpu2_0:
	s_or_b64 exec, exec, s[28:29]
	s_waitcnt vmcnt(8)
	v_mfma_f32_32x32x16_bf16 v[2:17], v[106:109], v[70:73], v[2:17]
	v_mfma_f32_32x32x16_bf16 v[18:33], v[106:109], v[74:77], v[18:33]
	v_mfma_f32_32x32x16_bf16 v[34:49], v[106:109], v[78:81], v[34:49]
	v_mfma_f32_32x32x16_bf16 v[50:65], v[106:109], v[66:69], v[50:65]
	global_load_dwordx4 v[70:73], v[122:123], off offset:1536
	global_load_dwordx4 v[74:77], v[124:125], off offset:1536
	global_load_dwordx4 v[78:81], v[126:127], off offset:1536
	global_load_dwordx4 v[66:69], v[128:129], off offset:1536
	s_waitcnt lgkmcnt(3)
	v_lshlrev_b32_e32 v98, 16, v238
	v_and_b32_e32 v99, 0xffff0000, v238
	v_lshlrev_b32_e32 v100, 16, v239
	v_and_b32_e32 v101, 0xffff0000, v239
	v_lshlrev_b32_e32 v102, 16, v240
	v_and_b32_e32 v103, 0xffff0000, v240
	v_lshlrev_b32_e32 v104, 16, v241
	v_and_b32_e32 v105, 0xffff0000, v241
	ds_read_b128 v[238:241], v163 offset:4144
	s_waitcnt lgkmcnt(3)
	v_lshlrev_b32_e32 v216, 16, v242
	v_and_b32_e32 v217, 0xffff0000, v242
	v_pk_add_f32 v[106:107], v[98:99], v[216:217]
	v_lshlrev_b32_e32 v216, 16, v243
	v_and_b32_e32 v217, 0xffff0000, v243
	v_pk_add_f32 v[108:109], v[100:101], v[216:217]
	v_lshlrev_b32_e32 v216, 16, v244
	v_and_b32_e32 v217, 0xffff0000, v244
	v_pk_add_f32 v[218:219], v[102:103], v[216:217]
	v_lshlrev_b32_e32 v216, 16, v245
	v_and_b32_e32 v217, 0xffff0000, v245
	v_pk_add_f32 v[220:221], v[104:105], v[216:217]
	ds_read_b128 v[242:245], v163 offset:3872
	s_waitcnt lgkmcnt(3)
	v_lshlrev_b32_e32 v216, 16, v248
	v_and_b32_e32 v217, 0xffff0000, v248
	v_pk_add_f32 v[106:107], v[106:107], v[216:217]
	v_lshlrev_b32_e32 v216, 16, v249
	v_and_b32_e32 v217, 0xffff0000, v249
	v_pk_add_f32 v[108:109], v[108:109], v[216:217]
	v_lshlrev_b32_e32 v216, 16, v250
	v_and_b32_e32 v217, 0xffff0000, v250
	v_pk_add_f32 v[218:219], v[218:219], v[216:217]
	v_lshlrev_b32_e32 v216, 16, v251
	v_and_b32_e32 v217, 0xffff0000, v251
	v_pk_add_f32 v[220:221], v[220:221], v[216:217]
	ds_read_b128 v[248:251], v163 offset:3600
	s_waitcnt lgkmcnt(3)
	v_lshlrev_b32_e32 v216, 16, v252
	v_and_b32_e32 v217, 0xffff0000, v252
	v_pk_add_f32 v[106:107], v[106:107], v[216:217]
	v_lshlrev_b32_e32 v216, 16, v253
	v_and_b32_e32 v217, 0xffff0000, v253
	v_pk_add_f32 v[108:109], v[108:109], v[216:217]
	v_lshlrev_b32_e32 v216, 16, v254
	v_and_b32_e32 v217, 0xffff0000, v254
	v_pk_add_f32 v[218:219], v[218:219], v[216:217]
	v_lshlrev_b32_e32 v216, 16, v255
	v_and_b32_e32 v217, 0xffff0000, v255
	v_pk_add_f32 v[220:221], v[220:221], v[216:217]
	ds_read_b128 v[252:255], v163 offset:3328
	v_fma_f32 v106, v159, v106, -v98
	v_fma_f32 v107, v159, v107, -v99
	v_fma_f32 v108, v159, v108, -v100
	v_fma_f32 v109, v159, v109, -v101
	v_fma_f32 v218, v159, v218, -v102
	v_fma_f32 v219, v159, v219, -v103
	v_fma_f32 v220, v159, v220, -v104
	v_fma_f32 v221, v159, v221, -v105
	v_cvt_pk_bf16_f32 v106, v106, v107
	v_cvt_pk_bf16_f32 v107, v108, v109
	v_cvt_pk_bf16_f32 v108, v218, v219
	v_cvt_pk_bf16_f32 v109, v220, v221
	s_and_saveexec_b64 s[28:29], s[6:7]
	s_cbranch_execz .Lpu2_1
	global_store_dwordx4 v[190:191], v[98:101], off offset:64
	global_store_dwordx4 v[190:191], v[102:105], off offset:80
.Lpu2_1:
	s_or_b64 exec, exec, s[28:29]
	s_waitcnt vmcnt(8)
	v_mfma_f32_32x32x16_bf16 v[2:17], v[106:109], v[82:85], v[2:17]
	v_mfma_f32_32x32x16_bf16 v[18:33], v[106:109], v[86:89], v[18:33]
	v_mfma_f32_32x32x16_bf16 v[34:49], v[106:109], v[90:93], v[34:49]
	v_mfma_f32_32x32x16_bf16 v[50:65], v[106:109], v[94:97], v[50:65]
	global_load_dwordx4 v[82:85], v[122:123], off offset:2048
	global_load_dwordx4 v[86:89], v[124:125], off offset:2048
	global_load_dwordx4 v[90:93], v[126:127], off offset:2048
	global_load_dwordx4 v[94:97], v[128:129], off offset:2048
	s_waitcnt lgkmcnt(3)
	v_lshlrev_b32_e32 v98, 16, v238
	v_and_b32_e32 v99, 0xffff0000, v238
	v_lshlrev_b32_e32 v100, 16, v239
	v_and_b32_e32 v101, 0xffff0000, v239
	v_lshlrev_b32_e32 v102, 16, v240
	v_and_b32_e32 v103, 0xffff0000, v240
	v_lshlrev_b32_e32 v104, 16, v241
	v_and_b32_e32 v105, 0xffff0000, v241
	ds_read_b128 v[238:241], v163 offset:4176
	s_waitcnt lgkmcnt(3)
	v_lshlrev_b32_e32 v216, 16, v242
	v_and_b32_e32 v217, 0xffff0000, v242
	v_pk_add_f32 v[106:107], v[98:99], v[216:217]
	v_lshlrev_b32_e32 v216, 16, v243
	v_and_b32_e32 v217, 0xffff0000, v243
	v_pk_add_f32 v[108:109], v[100:101], v[216:217]
	v_lshlrev_b32_e32 v216, 16, v244
	v_and_b32_e32 v217, 0xffff0000, v244
	v_pk_add_f32 v[218:219], v[102:103], v[216:217]
	v_lshlrev_b32_e32 v216, 16, v245
	v_and_b32_e32 v217, 0xffff0000, v245
	v_pk_add_f32 v[220:221], v[104:105], v[216:217]
	ds_read_b128 v[242:245], v163 offset:3904
	s_waitcnt lgkmcnt(3)
	v_lshlrev_b32_e32 v216, 16, v248
	v_and_b32_e32 v217, 0xffff0000, v248
	v_pk_add_f32 v[106:107], v[106:107], v[216:217]
	v_lshlrev_b32_e32 v216, 16, v249
	v_and_b32_e32 v217, 0xffff0000, v249
	v_pk_add_f32 v[108:109], v[108:109], v[216:217]
	v_lshlrev_b32_e32 v216, 16, v250
	v_and_b32_e32 v217, 0xffff0000, v250
	v_pk_add_f32 v[218:219], v[218:219], v[216:217]
	v_lshlrev_b32_e32 v216, 16, v251
	v_and_b32_e32 v217, 0xffff0000, v251
	v_pk_add_f32 v[220:221], v[220:221], v[216:217]
	ds_read_b128 v[248:251], v163 offset:3632
	s_waitcnt lgkmcnt(3)
	v_lshlrev_b32_e32 v216, 16, v252
	v_and_b32_e32 v217, 0xffff0000, v252
	v_pk_add_f32 v[106:107], v[106:107], v[216:217]
	v_lshlrev_b32_e32 v216, 16, v253
	v_and_b32_e32 v217, 0xffff0000, v253
	v_pk_add_f32 v[108:109], v[108:109], v[216:217]
	v_lshlrev_b32_e32 v216, 16, v254
	v_and_b32_e32 v217, 0xffff0000, v254
	v_pk_add_f32 v[218:219], v[218:219], v[216:217]
	v_lshlrev_b32_e32 v216, 16, v255
	v_and_b32_e32 v217, 0xffff0000, v255
	v_pk_add_f32 v[220:221], v[220:221], v[216:217]
	ds_read_b128 v[252:255], v163 offset:3360
	v_fma_f32 v106, v159, v106, -v98
	v_fma_f32 v107, v159, v107, -v99
	v_fma_f32 v108, v159, v108, -v100
	v_fma_f32 v109, v159, v109, -v101
	v_fma_f32 v218, v159, v218, -v102
	v_fma_f32 v219, v159, v219, -v103
	v_fma_f32 v220, v159, v220, -v104
	v_fma_f32 v221, v159, v221, -v105
	v_cvt_pk_bf16_f32 v106, v106, v107
	v_cvt_pk_bf16_f32 v107, v108, v109
	v_cvt_pk_bf16_f32 v108, v218, v219
	v_cvt_pk_bf16_f32 v109, v220, v221
	s_and_saveexec_b64 s[28:29], s[6:7]
	s_cbranch_execz .Lpu2_2
	global_store_dwordx4 v[190:191], v[98:101], off offset:128
	global_store_dwordx4 v[190:191], v[102:105], off offset:144
.Lpu2_2:
	s_or_b64 exec, exec, s[28:29]
	s_waitcnt vmcnt(8)
	v_mfma_f32_32x32x16_bf16 v[2:17], v[106:109], v[222:225], v[2:17]
	v_mfma_f32_32x32x16_bf16 v[18:33], v[106:109], v[226:229], v[18:33]
	v_mfma_f32_32x32x16_bf16 v[34:49], v[106:109], v[230:233], v[34:49]
	v_mfma_f32_32x32x16_bf16 v[50:65], v[106:109], v[234:237], v[50:65]
	global_load_dwordx4 v[222:225], v[122:123], off offset:2560
	global_load_dwordx4 v[226:229], v[124:125], off offset:2560
	global_load_dwordx4 v[230:233], v[126:127], off offset:2560
	global_load_dwordx4 v[234:237], v[128:129], off offset:2560
	s_waitcnt lgkmcnt(3)
	v_lshlrev_b32_e32 v98, 16, v238
	v_and_b32_e32 v99, 0xffff0000, v238
	v_lshlrev_b32_e32 v100, 16, v239
	v_and_b32_e32 v101, 0xffff0000, v239
	v_lshlrev_b32_e32 v102, 16, v240
	v_and_b32_e32 v103, 0xffff0000, v240
	v_lshlrev_b32_e32 v104, 16, v241
	v_and_b32_e32 v105, 0xffff0000, v241
	ds_read_b128 v[238:241], v163 offset:4208
	s_waitcnt lgkmcnt(3)
	v_lshlrev_b32_e32 v216, 16, v242
	v_and_b32_e32 v217, 0xffff0000, v242
	v_pk_add_f32 v[106:107], v[98:99], v[216:217]
	v_lshlrev_b32_e32 v216, 16, v243
	v_and_b32_e32 v217, 0xffff0000, v243
	v_pk_add_f32 v[108:109], v[100:101], v[216:217]
	v_lshlrev_b32_e32 v216, 16, v244
	v_and_b32_e32 v217, 0xffff0000, v244
	v_pk_add_f32 v[218:219], v[102:103], v[216:217]
	v_lshlrev_b32_e32 v216, 16, v245
	v_and_b32_e32 v217, 0xffff0000, v245
	v_pk_add_f32 v[220:221], v[104:105], v[216:217]
	ds_read_b128 v[242:245], v163 offset:3936
	s_waitcnt lgkmcnt(3)
	v_lshlrev_b32_e32 v216, 16, v248
	v_and_b32_e32 v217, 0xffff0000, v248
	v_pk_add_f32 v[106:107], v[106:107], v[216:217]
	v_lshlrev_b32_e32 v216, 16, v249
	v_and_b32_e32 v217, 0xffff0000, v249
	v_pk_add_f32 v[108:109], v[108:109], v[216:217]
	v_lshlrev_b32_e32 v216, 16, v250
	v_and_b32_e32 v217, 0xffff0000, v250
	v_pk_add_f32 v[218:219], v[218:219], v[216:217]
	v_lshlrev_b32_e32 v216, 16, v251
	v_and_b32_e32 v217, 0xffff0000, v251
	v_pk_add_f32 v[220:221], v[220:221], v[216:217]
	ds_read_b128 v[248:251], v163 offset:3664
	s_waitcnt lgkmcnt(3)
	v_lshlrev_b32_e32 v216, 16, v252
	v_and_b32_e32 v217, 0xffff0000, v252
	v_pk_add_f32 v[106:107], v[106:107], v[216:217]
	v_lshlrev_b32_e32 v216, 16, v253
	v_and_b32_e32 v217, 0xffff0000, v253
	v_pk_add_f32 v[108:109], v[108:109], v[216:217]
	v_lshlrev_b32_e32 v216, 16, v254
	v_and_b32_e32 v217, 0xffff0000, v254
	v_pk_add_f32 v[218:219], v[218:219], v[216:217]
	v_lshlrev_b32_e32 v216, 16, v255
	v_and_b32_e32 v217, 0xffff0000, v255
	v_pk_add_f32 v[220:221], v[220:221], v[216:217]
	ds_read_b128 v[252:255], v163 offset:3392
	v_fma_f32 v106, v159, v106, -v98
	v_fma_f32 v107, v159, v107, -v99
	v_fma_f32 v108, v159, v108, -v100
	v_fma_f32 v109, v159, v109, -v101
	v_fma_f32 v218, v159, v218, -v102
	v_fma_f32 v219, v159, v219, -v103
	v_fma_f32 v220, v159, v220, -v104
	v_fma_f32 v221, v159, v221, -v105
	v_cvt_pk_bf16_f32 v106, v106, v107
	v_cvt_pk_bf16_f32 v107, v108, v109
	v_cvt_pk_bf16_f32 v108, v218, v219
	v_cvt_pk_bf16_f32 v109, v220, v221
	s_and_saveexec_b64 s[28:29], s[6:7]
	s_cbranch_execz .Lpu2_3
	global_store_dwordx4 v[190:191], v[98:101], off offset:192
	global_store_dwordx4 v[190:191], v[102:105], off offset:208
.Lpu2_3:
	s_or_b64 exec, exec, s[28:29]
	s_waitcnt vmcnt(8)
	v_mfma_f32_32x32x16_bf16 v[2:17], v[106:109], v[70:73], v[2:17]
	v_mfma_f32_32x32x16_bf16 v[18:33], v[106:109], v[74:77], v[18:33]
	v_mfma_f32_32x32x16_bf16 v[34:49], v[106:109], v[78:81], v[34:49]
	v_mfma_f32_32x32x16_bf16 v[50:65], v[106:109], v[66:69], v[50:65]
	global_load_dwordx4 v[70:73], v[122:123], off offset:3072
	global_load_dwordx4 v[74:77], v[124:125], off offset:3072
	global_load_dwordx4 v[78:81], v[126:127], off offset:3072
	global_load_dwordx4 v[66:69], v[128:129], off offset:3072
	s_waitcnt lgkmcnt(3)
	v_lshlrev_b32_e32 v98, 16, v238
	v_and_b32_e32 v99, 0xffff0000, v238
	v_lshlrev_b32_e32 v100, 16, v239
	v_and_b32_e32 v101, 0xffff0000, v239
	v_lshlrev_b32_e32 v102, 16, v240
	v_and_b32_e32 v103, 0xffff0000, v240
	v_lshlrev_b32_e32 v104, 16, v241
	v_and_b32_e32 v105, 0xffff0000, v241
	ds_read_b128 v[238:241], v163 offset:4240
	s_waitcnt lgkmcnt(3)
	v_lshlrev_b32_e32 v216, 16, v242
	v_and_b32_e32 v217, 0xffff0000, v242
	v_pk_add_f32 v[106:107], v[98:99], v[216:217]
	v_lshlrev_b32_e32 v216, 16, v243
	v_and_b32_e32 v217, 0xffff0000, v243
	v_pk_add_f32 v[108:109], v[100:101], v[216:217]
	v_lshlrev_b32_e32 v216, 16, v244
	v_and_b32_e32 v217, 0xffff0000, v244
	v_pk_add_f32 v[218:219], v[102:103], v[216:217]
	v_lshlrev_b32_e32 v216, 16, v245
	v_and_b32_e32 v217, 0xffff0000, v245
	v_pk_add_f32 v[220:221], v[104:105], v[216:217]
	ds_read_b128 v[242:245], v163 offset:3968
	s_waitcnt lgkmcnt(3)
	v_lshlrev_b32_e32 v216, 16, v248
	v_and_b32_e32 v217, 0xffff0000, v248
	v_pk_add_f32 v[106:107], v[106:107], v[216:217]
	v_lshlrev_b32_e32 v216, 16, v249
	v_and_b32_e32 v217, 0xffff0000, v249
	v_pk_add_f32 v[108:109], v[108:109], v[216:217]
	v_lshlrev_b32_e32 v216, 16, v250
	v_and_b32_e32 v217, 0xffff0000, v250
	v_pk_add_f32 v[218:219], v[218:219], v[216:217]
	v_lshlrev_b32_e32 v216, 16, v251
	v_and_b32_e32 v217, 0xffff0000, v251
	v_pk_add_f32 v[220:221], v[220:221], v[216:217]
	ds_read_b128 v[248:251], v163 offset:3696
	s_waitcnt lgkmcnt(3)
	v_lshlrev_b32_e32 v216, 16, v252
	v_and_b32_e32 v217, 0xffff0000, v252
	v_pk_add_f32 v[106:107], v[106:107], v[216:217]
	v_lshlrev_b32_e32 v216, 16, v253
	v_and_b32_e32 v217, 0xffff0000, v253
	v_pk_add_f32 v[108:109], v[108:109], v[216:217]
	v_lshlrev_b32_e32 v216, 16, v254
	v_and_b32_e32 v217, 0xffff0000, v254
	v_pk_add_f32 v[218:219], v[218:219], v[216:217]
	v_lshlrev_b32_e32 v216, 16, v255
	v_and_b32_e32 v217, 0xffff0000, v255
	v_pk_add_f32 v[220:221], v[220:221], v[216:217]
	ds_read_b128 v[252:255], v163 offset:3424
	v_fma_f32 v106, v159, v106, -v98
	v_fma_f32 v107, v159, v107, -v99
	v_fma_f32 v108, v159, v108, -v100
	v_fma_f32 v109, v159, v109, -v101
	v_fma_f32 v218, v159, v218, -v102
	v_fma_f32 v219, v159, v219, -v103
	v_fma_f32 v220, v159, v220, -v104
	v_fma_f32 v221, v159, v221, -v105
	v_cvt_pk_bf16_f32 v106, v106, v107
	v_cvt_pk_bf16_f32 v107, v108, v109
	v_cvt_pk_bf16_f32 v108, v218, v219
	v_cvt_pk_bf16_f32 v109, v220, v221
	s_and_saveexec_b64 s[28:29], s[6:7]
	s_cbranch_execz .Lpu2_4
	global_store_dwordx4 v[190:191], v[98:101], off offset:256
	global_store_dwordx4 v[190:191], v[102:105], off offset:272
.Lpu2_4:
	s_or_b64 exec, exec, s[28:29]
	s_waitcnt vmcnt(8)
	v_mfma_f32_32x32x16_bf16 v[2:17], v[106:109], v[82:85], v[2:17]
	v_mfma_f32_32x32x16_bf16 v[18:33], v[106:109], v[86:89], v[18:33]
	v_mfma_f32_32x32x16_bf16 v[34:49], v[106:109], v[90:93], v[34:49]
	v_mfma_f32_32x32x16_bf16 v[50:65], v[106:109], v[94:97], v[50:65]
	global_load_dwordx4 v[82:85], v[122:123], off offset:3584
	global_load_dwordx4 v[86:89], v[124:125], off offset:3584
	global_load_dwordx4 v[90:93], v[126:127], off offset:3584
	global_load_dwordx4 v[94:97], v[128:129], off offset:3584
	s_waitcnt lgkmcnt(3)
	v_lshlrev_b32_e32 v98, 16, v238
	v_and_b32_e32 v99, 0xffff0000, v238
	v_lshlrev_b32_e32 v100, 16, v239
	v_and_b32_e32 v101, 0xffff0000, v239
	v_lshlrev_b32_e32 v102, 16, v240
	v_and_b32_e32 v103, 0xffff0000, v240
	v_lshlrev_b32_e32 v104, 16, v241
	v_and_b32_e32 v105, 0xffff0000, v241
	ds_read_b128 v[238:241], v163 offset:4272
	s_waitcnt lgkmcnt(3)
	v_lshlrev_b32_e32 v216, 16, v242
	v_and_b32_e32 v217, 0xffff0000, v242
	v_pk_add_f32 v[106:107], v[98:99], v[216:217]
	v_lshlrev_b32_e32 v216, 16, v243
	v_and_b32_e32 v217, 0xffff0000, v243
	v_pk_add_f32 v[108:109], v[100:101], v[216:217]
	v_lshlrev_b32_e32 v216, 16, v244
	v_and_b32_e32 v217, 0xffff0000, v244
	v_pk_add_f32 v[218:219], v[102:103], v[216:217]
	v_lshlrev_b32_e32 v216, 16, v245
	v_and_b32_e32 v217, 0xffff0000, v245
	v_pk_add_f32 v[220:221], v[104:105], v[216:217]
	ds_read_b128 v[242:245], v163 offset:4000
	s_waitcnt lgkmcnt(3)
	v_lshlrev_b32_e32 v216, 16, v248
	v_and_b32_e32 v217, 0xffff0000, v248
	v_pk_add_f32 v[106:107], v[106:107], v[216:217]
	v_lshlrev_b32_e32 v216, 16, v249
	v_and_b32_e32 v217, 0xffff0000, v249
	v_pk_add_f32 v[108:109], v[108:109], v[216:217]
	v_lshlrev_b32_e32 v216, 16, v250
	v_and_b32_e32 v217, 0xffff0000, v250
	v_pk_add_f32 v[218:219], v[218:219], v[216:217]
	v_lshlrev_b32_e32 v216, 16, v251
	v_and_b32_e32 v217, 0xffff0000, v251
	v_pk_add_f32 v[220:221], v[220:221], v[216:217]
	ds_read_b128 v[248:251], v163 offset:3728
	s_waitcnt lgkmcnt(3)
	v_lshlrev_b32_e32 v216, 16, v252
	v_and_b32_e32 v217, 0xffff0000, v252
	v_pk_add_f32 v[106:107], v[106:107], v[216:217]
	v_lshlrev_b32_e32 v216, 16, v253
	v_and_b32_e32 v217, 0xffff0000, v253
	v_pk_add_f32 v[108:109], v[108:109], v[216:217]
	v_lshlrev_b32_e32 v216, 16, v254
	v_and_b32_e32 v217, 0xffff0000, v254
	v_pk_add_f32 v[218:219], v[218:219], v[216:217]
	v_lshlrev_b32_e32 v216, 16, v255
	v_and_b32_e32 v217, 0xffff0000, v255
	v_pk_add_f32 v[220:221], v[220:221], v[216:217]
	ds_read_b128 v[252:255], v163 offset:3456
	v_fma_f32 v106, v159, v106, -v98
	v_fma_f32 v107, v159, v107, -v99
	v_fma_f32 v108, v159, v108, -v100
	v_fma_f32 v109, v159, v109, -v101
	v_fma_f32 v218, v159, v218, -v102
	v_fma_f32 v219, v159, v219, -v103
	v_fma_f32 v220, v159, v220, -v104
	v_fma_f32 v221, v159, v221, -v105
	v_cvt_pk_bf16_f32 v106, v106, v107
	v_cvt_pk_bf16_f32 v107, v108, v109
	v_cvt_pk_bf16_f32 v108, v218, v219
	v_cvt_pk_bf16_f32 v109, v220, v221
	s_and_saveexec_b64 s[28:29], s[6:7]
	s_cbranch_execz .Lpu2_5
	global_store_dwordx4 v[190:191], v[98:101], off offset:320
	global_store_dwordx4 v[190:191], v[102:105], off offset:336
.Lpu2_5:
	s_or_b64 exec, exec, s[28:29]
	s_waitcnt vmcnt(8)
	v_mfma_f32_32x32x16_bf16 v[2:17], v[106:109], v[222:225], v[2:17]
	v_mfma_f32_32x32x16_bf16 v[18:33], v[106:109], v[226:229], v[18:33]
	v_mfma_f32_32x32x16_bf16 v[34:49], v[106:109], v[230:233], v[34:49]
	v_mfma_f32_32x32x16_bf16 v[50:65], v[106:109], v[234:237], v[50:65]
	s_waitcnt lgkmcnt(3)
	v_lshlrev_b32_e32 v98, 16, v238
	v_and_b32_e32 v99, 0xffff0000, v238
	v_lshlrev_b32_e32 v100, 16, v239
	v_and_b32_e32 v101, 0xffff0000, v239
	v_lshlrev_b32_e32 v102, 16, v240
	v_and_b32_e32 v103, 0xffff0000, v240
	v_lshlrev_b32_e32 v104, 16, v241
	v_and_b32_e32 v105, 0xffff0000, v241
	ds_read_b128 v[238:241], v163 offset:4304
	s_waitcnt lgkmcnt(3)
	v_lshlrev_b32_e32 v216, 16, v242
	v_and_b32_e32 v217, 0xffff0000, v242
	v_pk_add_f32 v[106:107], v[98:99], v[216:217]
	v_lshlrev_b32_e32 v216, 16, v243
	v_and_b32_e32 v217, 0xffff0000, v243
	v_pk_add_f32 v[108:109], v[100:101], v[216:217]
	v_lshlrev_b32_e32 v216, 16, v244
	v_and_b32_e32 v217, 0xffff0000, v244
	v_pk_add_f32 v[218:219], v[102:103], v[216:217]
	v_lshlrev_b32_e32 v216, 16, v245
	v_and_b32_e32 v217, 0xffff0000, v245
	v_pk_add_f32 v[220:221], v[104:105], v[216:217]
	ds_read_b128 v[242:245], v163 offset:4032
	s_waitcnt lgkmcnt(3)
	v_lshlrev_b32_e32 v216, 16, v248
	v_and_b32_e32 v217, 0xffff0000, v248
	v_pk_add_f32 v[106:107], v[106:107], v[216:217]
	v_lshlrev_b32_e32 v216, 16, v249
	v_and_b32_e32 v217, 0xffff0000, v249
	v_pk_add_f32 v[108:109], v[108:109], v[216:217]
	v_lshlrev_b32_e32 v216, 16, v250
	v_and_b32_e32 v217, 0xffff0000, v250
	v_pk_add_f32 v[218:219], v[218:219], v[216:217]
	v_lshlrev_b32_e32 v216, 16, v251
	v_and_b32_e32 v217, 0xffff0000, v251
	v_pk_add_f32 v[220:221], v[220:221], v[216:217]
	ds_read_b128 v[248:251], v163 offset:3760
	s_waitcnt lgkmcnt(3)
	v_lshlrev_b32_e32 v216, 16, v252
	v_and_b32_e32 v217, 0xffff0000, v252
	v_pk_add_f32 v[106:107], v[106:107], v[216:217]
	v_lshlrev_b32_e32 v216, 16, v253
	v_and_b32_e32 v217, 0xffff0000, v253
	v_pk_add_f32 v[108:109], v[108:109], v[216:217]
	v_lshlrev_b32_e32 v216, 16, v254
	v_and_b32_e32 v217, 0xffff0000, v254
	v_pk_add_f32 v[218:219], v[218:219], v[216:217]
	v_lshlrev_b32_e32 v216, 16, v255
	v_and_b32_e32 v217, 0xffff0000, v255
	v_pk_add_f32 v[220:221], v[220:221], v[216:217]
	ds_read_b128 v[252:255], v163 offset:3488
	v_fma_f32 v106, v159, v106, -v98
	v_fma_f32 v107, v159, v107, -v99
	v_fma_f32 v108, v159, v108, -v100
	v_fma_f32 v109, v159, v109, -v101
	v_fma_f32 v218, v159, v218, -v102
	v_fma_f32 v219, v159, v219, -v103
	v_fma_f32 v220, v159, v220, -v104
	v_fma_f32 v221, v159, v221, -v105
	v_cvt_pk_bf16_f32 v106, v106, v107
	v_cvt_pk_bf16_f32 v107, v108, v109
	v_cvt_pk_bf16_f32 v108, v218, v219
	v_cvt_pk_bf16_f32 v109, v220, v221
	s_and_saveexec_b64 s[28:29], s[6:7]
	s_cbranch_execz .Lpu2_6
	global_store_dwordx4 v[190:191], v[98:101], off offset:384
	global_store_dwordx4 v[190:191], v[102:105], off offset:400
.Lpu2_6:
	s_or_b64 exec, exec, s[28:29]
	s_waitcnt vmcnt(4)
	v_mfma_f32_32x32x16_bf16 v[2:17], v[106:109], v[70:73], v[2:17]
	v_mfma_f32_32x32x16_bf16 v[18:33], v[106:109], v[74:77], v[18:33]
	v_mfma_f32_32x32x16_bf16 v[34:49], v[106:109], v[78:81], v[34:49]
	v_mfma_f32_32x32x16_bf16 v[50:65], v[106:109], v[66:69], v[50:65]
	s_waitcnt lgkmcnt(3)
	v_lshlrev_b32_e32 v98, 16, v238
	v_and_b32_e32 v99, 0xffff0000, v238
	v_lshlrev_b32_e32 v100, 16, v239
	v_and_b32_e32 v101, 0xffff0000, v239
	v_lshlrev_b32_e32 v102, 16, v240
	v_and_b32_e32 v103, 0xffff0000, v240
	v_lshlrev_b32_e32 v104, 16, v241
	v_and_b32_e32 v105, 0xffff0000, v241
	s_waitcnt lgkmcnt(2)
	v_lshlrev_b32_e32 v216, 16, v242
	v_and_b32_e32 v217, 0xffff0000, v242
	v_pk_add_f32 v[106:107], v[98:99], v[216:217]
	v_lshlrev_b32_e32 v216, 16, v243
	v_and_b32_e32 v217, 0xffff0000, v243
	v_pk_add_f32 v[108:109], v[100:101], v[216:217]
	v_lshlrev_b32_e32 v216, 16, v244
	v_and_b32_e32 v217, 0xffff0000, v244
	v_pk_add_f32 v[218:219], v[102:103], v[216:217]
	v_lshlrev_b32_e32 v216, 16, v245
	v_and_b32_e32 v217, 0xffff0000, v245
	v_pk_add_f32 v[220:221], v[104:105], v[216:217]
	s_waitcnt lgkmcnt(1)
	v_lshlrev_b32_e32 v216, 16, v248
	v_and_b32_e32 v217, 0xffff0000, v248
	v_pk_add_f32 v[106:107], v[106:107], v[216:217]
	v_lshlrev_b32_e32 v216, 16, v249
	v_and_b32_e32 v217, 0xffff0000, v249
	v_pk_add_f32 v[108:109], v[108:109], v[216:217]
	v_lshlrev_b32_e32 v216, 16, v250
	v_and_b32_e32 v217, 0xffff0000, v250
	v_pk_add_f32 v[218:219], v[218:219], v[216:217]
	v_lshlrev_b32_e32 v216, 16, v251
	v_and_b32_e32 v217, 0xffff0000, v251
	v_pk_add_f32 v[220:221], v[220:221], v[216:217]
	s_waitcnt lgkmcnt(0)
	v_lshlrev_b32_e32 v216, 16, v252
	v_and_b32_e32 v217, 0xffff0000, v252
	v_pk_add_f32 v[106:107], v[106:107], v[216:217]
	v_lshlrev_b32_e32 v216, 16, v253
	v_and_b32_e32 v217, 0xffff0000, v253
	v_pk_add_f32 v[108:109], v[108:109], v[216:217]
	v_lshlrev_b32_e32 v216, 16, v254
	v_and_b32_e32 v217, 0xffff0000, v254
	v_pk_add_f32 v[218:219], v[218:219], v[216:217]
	v_lshlrev_b32_e32 v216, 16, v255
	v_and_b32_e32 v217, 0xffff0000, v255
	v_pk_add_f32 v[220:221], v[220:221], v[216:217]
	v_fma_f32 v106, v159, v106, -v98
	v_fma_f32 v107, v159, v107, -v99
	v_fma_f32 v108, v159, v108, -v100
	v_fma_f32 v109, v159, v109, -v101
	v_fma_f32 v218, v159, v218, -v102
	v_fma_f32 v219, v159, v219, -v103
	v_fma_f32 v220, v159, v220, -v104
	v_fma_f32 v221, v159, v221, -v105
	v_cvt_pk_bf16_f32 v106, v106, v107
	v_cvt_pk_bf16_f32 v107, v108, v109
	v_cvt_pk_bf16_f32 v108, v218, v219
	v_cvt_pk_bf16_f32 v109, v220, v221
	s_and_saveexec_b64 s[28:29], s[6:7]
	s_cbranch_execz .Lpu2_7
	global_store_dwordx4 v[190:191], v[98:101], off offset:448
	global_store_dwordx4 v[190:191], v[102:105], off offset:464

.LBB0_403:
	s_or_b64 exec, exec, s[2:3]
	s_waitcnt lgkmcnt(0)
	global_load_dwordx4 v[82:85], v[110:111], off offset:512
	global_load_dwordx4 v[86:89], v[134:135], off offset:512
	global_load_dwordx4 v[90:93], v[136:137], off offset:512
	global_load_dwordx4 v[94:97], v[138:139], off offset:512
	global_load_dwordx4 v[222:225], v[110:111], off offset:1024
	global_load_dwordx4 v[226:229], v[134:135], off offset:1024
	global_load_dwordx4 v[230:233], v[136:137], off offset:1024
	global_load_dwordx4 v[234:237], v[138:139], off offset:1024
	s_ashr_i32 s2, s30, 6
	v_or_b32_e32 v2, s28, v1
	s_mul_i32 s2, s2, 15
	v_cmp_eq_u32_e32 vcc, 0, v2
	v_cmp_lt_u32_e64 s[6:7], s41, v2
	s_ashr_i32 s3, s2, 31
	v_add_u32_e32 v2, 0xfffff80f, v2
	v_mov_b32_e32 v3, v155
	v_lshl_add_u64 v[2:3], v[2:3], 0, s[2:3]
	v_lshlrev_b64 v[2:3], 11, v[2:3]
	v_lshl_add_u64 v[184:185], v[140:141], 0, v[2:3]
	v_mov_b32_e32 v2, 0
	s_mov_b32 s28, 0
	v_cndmask_b32_e64 v159, 0.5, 1.0, vcc
	s_mov_b64 s[2:3], 0
	v_mov_b32_e32 v3, v2
	v_mov_b32_e32 v4, v2
	v_mov_b32_e32 v5, v2
	v_mov_b32_e32 v6, v2
	v_mov_b32_e32 v7, v2
	v_mov_b32_e32 v8, v2
	v_mov_b32_e32 v9, v2
	v_mov_b32_e32 v10, v2
	v_mov_b32_e32 v11, v2
	v_mov_b32_e32 v12, v2
	v_mov_b32_e32 v13, v2
	v_mov_b32_e32 v14, v2
	v_mov_b32_e32 v15, v2
	v_mov_b32_e32 v16, v2
	v_mov_b32_e32 v17, v2
	v_mov_b32_e32 v18, v2
	v_mov_b32_e32 v19, v2
	v_mov_b32_e32 v20, v2
	v_mov_b32_e32 v21, v2
	v_mov_b32_e32 v22, v2
	v_mov_b32_e32 v23, v2
	v_mov_b32_e32 v24, v2
	v_mov_b32_e32 v25, v2
	v_mov_b32_e32 v26, v2
	v_mov_b32_e32 v27, v2
	v_mov_b32_e32 v28, v2
	v_mov_b32_e32 v29, v2
	v_mov_b32_e32 v30, v2
	v_mov_b32_e32 v31, v2
	v_mov_b32_e32 v32, v2
	v_mov_b32_e32 v33, v2
	v_mov_b32_e32 v34, v2
	v_mov_b32_e32 v35, v2
	v_mov_b32_e32 v36, v2
	v_mov_b32_e32 v37, v2
	v_mov_b32_e32 v38, v2
	v_mov_b32_e32 v39, v2
	v_mov_b32_e32 v40, v2
	v_mov_b32_e32 v41, v2
	v_mov_b32_e32 v42, v2
	v_mov_b32_e32 v43, v2
	v_mov_b32_e32 v44, v2
	v_mov_b32_e32 v45, v2
	v_mov_b32_e32 v46, v2
	v_mov_b32_e32 v47, v2
	v_mov_b32_e32 v48, v2
	v_mov_b32_e32 v49, v2
	v_mov_b32_e32 v50, v2
	v_mov_b32_e32 v51, v2
	v_mov_b32_e32 v52, v2
	v_mov_b32_e32 v53, v2
	v_mov_b32_e32 v54, v2
	v_mov_b32_e32 v55, v2
	v_mov_b32_e32 v56, v2
	v_mov_b32_e32 v57, v2
	v_mov_b32_e32 v58, v2
	v_mov_b32_e32 v59, v2
	v_mov_b32_e32 v60, v2
	v_mov_b32_e32 v61, v2
	v_mov_b32_e32 v62, v2
	v_mov_b32_e32 v63, v2
	v_mov_b32_e32 v64, v2
	v_mov_b32_e32 v65, v2
	v_lshl_add_u32 v163, v197, 1, v214
	ds_read_b128 v[238:241], v163 offset:4080
	ds_read_b128 v[242:245], v163 offset:3808
	ds_read_b128 v[248:251], v163 offset:4112
	ds_read_b128 v[252:255], v163 offset:3840
	s_waitcnt lgkmcnt(3)
	v_lshlrev_b32_e32 v98, 16, v238
	v_and_b32_e32 v99, 0xffff0000, v238
	v_lshlrev_b32_e32 v100, 16, v239
	v_and_b32_e32 v101, 0xffff0000, v239
	v_lshlrev_b32_e32 v102, 16, v240
	v_and_b32_e32 v103, 0xffff0000, v240
	v_lshlrev_b32_e32 v104, 16, v241
	v_and_b32_e32 v105, 0xffff0000, v241
	ds_read_b128 v[238:241], v163 offset:4144
	s_waitcnt lgkmcnt(3)
	v_lshlrev_b32_e32 v216, 16, v242
	v_and_b32_e32 v217, 0xffff0000, v242
	v_pk_add_f32 v[106:107], v[98:99], v[216:217]
	v_lshlrev_b32_e32 v216, 16, v243
	v_and_b32_e32 v217, 0xffff0000, v243
	v_pk_add_f32 v[108:109], v[100:101], v[216:217]
	v_lshlrev_b32_e32 v216, 16, v244
	v_and_b32_e32 v217, 0xffff0000, v244
	v_pk_add_f32 v[218:219], v[102:103], v[216:217]
	v_lshlrev_b32_e32 v216, 16, v245
	v_and_b32_e32 v217, 0xffff0000, v245
	v_pk_add_f32 v[220:221], v[104:105], v[216:217]
	ds_read_b128 v[242:245], v163 offset:3872
	v_fma_f32 v106, v159, v106, -v98
	v_fma_f32 v107, v159, v107, -v99
	v_fma_f32 v108, v159, v108, -v100
	v_fma_f32 v109, v159, v109, -v101
	v_fma_f32 v218, v159, v218, -v102
	v_fma_f32 v219, v159, v219, -v103
	v_fma_f32 v220, v159, v220, -v104
	v_fma_f32 v221, v159, v221, -v105
	v_cvt_pk_bf16_f32 v106, v106, v107
	v_cvt_pk_bf16_f32 v107, v108, v109
	v_cvt_pk_bf16_f32 v108, v218, v219
	v_cvt_pk_bf16_f32 v109, v220, v221
	s_and_saveexec_b64 s[10:11], s[6:7]
	s_cbranch_execz .Lpu3_0
	global_store_dwordx4 v[184:185], v[98:101], off offset:0
	global_store_dwordx4 v[184:185], v[102:105], off offset:16
.Lpu3_0:
	s_or_b64 exec, exec, s[10:11]
	s_waitcnt vmcnt(8)
	v_mfma_f32_32x32x16_bf16 v[2:17], v[106:109], v[70:73], v[2:17]
	v_mfma_f32_32x32x16_bf16 v[18:33], v[106:109], v[74:77], v[18:33]
	v_mfma_f32_32x32x16_bf16 v[34:49], v[106:109], v[78:81], v[34:49]
	v_mfma_f32_32x32x16_bf16 v[50:65], v[106:109], v[66:69], v[50:65]
	global_load_dwordx4 v[70:73], v[110:111], off offset:1536
	global_load_dwordx4 v[74:77], v[134:135], off offset:1536
	global_load_dwordx4 v[78:81], v[136:137], off offset:1536
	global_load_dwordx4 v[66:69], v[138:139], off offset:1536
	s_waitcnt lgkmcnt(3)
	v_lshlrev_b32_e32 v98, 16, v248
	v_and_b32_e32 v99, 0xffff0000, v248
	v_lshlrev_b32_e32 v100, 16, v249
	v_and_b32_e32 v101, 0xffff0000, v249
	v_lshlrev_b32_e32 v102, 16, v250
	v_and_b32_e32 v103, 0xffff0000, v250
	v_lshlrev_b32_e32 v104, 16, v251
	v_and_b32_e32 v105, 0xffff0000, v251
	ds_read_b128 v[248:251], v163 offset:4176
	s_waitcnt lgkmcnt(3)
	v_lshlrev_b32_e32 v216, 16, v252
	v_and_b32_e32 v217, 0xffff0000, v252
	v_pk_add_f32 v[106:107], v[98:99], v[216:217]
	v_lshlrev_b32_e32 v216, 16, v253
	v_and_b32_e32 v217, 0xffff0000, v253
	v_pk_add_f32 v[108:109], v[100:101], v[216:217]
	v_lshlrev_b32_e32 v216, 16, v254
	v_and_b32_e32 v217, 0xffff0000, v254
	v_pk_add_f32 v[218:219], v[102:103], v[216:217]
	v_lshlrev_b32_e32 v216, 16, v255
	v_and_b32_e32 v217, 0xffff0000, v255
	v_pk_add_f32 v[220:221], v[104:105], v[216:217]
	ds_read_b128 v[252:255], v163 offset:3904
	v_fma_f32 v106, v159, v106, -v98
	v_fma_f32 v107, v159, v107, -v99
	v_fma_f32 v108, v159, v108, -v100
	v_fma_f32 v109, v159, v109, -v101
	v_fma_f32 v218, v159, v218, -v102
	v_fma_f32 v219, v159, v219, -v103
	v_fma_f32 v220, v159, v220, -v104
	v_fma_f32 v221, v159, v221, -v105
	v_cvt_pk_bf16_f32 v106, v106, v107
	v_cvt_pk_bf16_f32 v107, v108, v109
	v_cvt_pk_bf16_f32 v108, v218, v219
	v_cvt_pk_bf16_f32 v109, v220, v221
	s_and_saveexec_b64 s[10:11], s[6:7]
	s_cbranch_execz .Lpu3_1
	global_store_dwordx4 v[184:185], v[98:101], off offset:64
	global_store_dwordx4 v[184:185], v[102:105], off offset:80
.Lpu3_1:
	s_or_b64 exec, exec, s[10:11]
	s_waitcnt vmcnt(8)
	v_mfma_f32_32x32x16_bf16 v[2:17], v[106:109], v[82:85], v[2:17]
	v_mfma_f32_32x32x16_bf16 v[18:33], v[106:109], v[86:89], v[18:33]
	v_mfma_f32_32x32x16_bf16 v[34:49], v[106:109], v[90:93], v[34:49]
	v_mfma_f32_32x32x16_bf16 v[50:65], v[106:109], v[94:97], v[50:65]
	global_load_dwordx4 v[82:85], v[110:111], off offset:2048
	global_load_dwordx4 v[86:89], v[134:135], off offset:2048
	global_load_dwordx4 v[90:93], v[136:137], off offset:2048
	global_load_dwordx4 v[94:97], v[138:139], off offset:2048
	s_waitcnt lgkmcnt(3)
	v_lshlrev_b32_e32 v98, 16, v238
	v_and_b32_e32 v99, 0xffff0000, v238
	v_lshlrev_b32_e32 v100, 16, v239
	v_and_b32_e32 v101, 0xffff0000, v239
	v_lshlrev_b32_e32 v102, 16, v240
	v_and_b32_e32 v103, 0xffff0000, v240
	v_lshlrev_b32_e32 v104, 16, v241
	v_and_b32_e32 v105, 0xffff0000, v241
	ds_read_b128 v[238:241], v163 offset:4208
	s_waitcnt lgkmcnt(3)
	v_lshlrev_b32_e32 v216, 16, v242
	v_and_b32_e32 v217, 0xffff0000, v242
	v_pk_add_f32 v[106:107], v[98:99], v[216:217]
	v_lshlrev_b32_e32 v216, 16, v243
	v_and_b32_e32 v217, 0xffff0000, v243
	v_pk_add_f32 v[108:109], v[100:101], v[216:217]
	v_lshlrev_b32_e32 v216, 16, v244
	v_and_b32_e32 v217, 0xffff0000, v244
	v_pk_add_f32 v[218:219], v[102:103], v[216:217]
	v_lshlrev_b32_e32 v216, 16, v245
	v_and_b32_e32 v217, 0xffff0000, v245
	v_pk_add_f32 v[220:221], v[104:105], v[216:217]
	ds_read_b128 v[242:245], v163 offset:3936
	v_fma_f32 v106, v159, v106, -v98
	v_fma_f32 v107, v159, v107, -v99
	v_fma_f32 v108, v159, v108, -v100
	v_fma_f32 v109, v159, v109, -v101
	v_fma_f32 v218, v159, v218, -v102
	v_fma_f32 v219, v159, v219, -v103
	v_fma_f32 v220, v159, v220, -v104
	v_fma_f32 v221, v159, v221, -v105
	v_cvt_pk_bf16_f32 v106, v106, v107
	v_cvt_pk_bf16_f32 v107, v108, v109
	v_cvt_pk_bf16_f32 v108, v218, v219
	v_cvt_pk_bf16_f32 v109, v220, v221
	s_and_saveexec_b64 s[10:11], s[6:7]
	s_cbranch_execz .Lpu3_2
	global_store_dwordx4 v[184:185], v[98:101], off offset:128
	global_store_dwordx4 v[184:185], v[102:105], off offset:144
.Lpu3_2:
	s_or_b64 exec, exec, s[10:11]
	s_waitcnt vmcnt(8)
	v_mfma_f32_32x32x16_bf16 v[2:17], v[106:109], v[222:225], v[2:17]
	v_mfma_f32_32x32x16_bf16 v[18:33], v[106:109], v[226:229], v[18:33]
	v_mfma_f32_32x32x16_bf16 v[34:49], v[106:109], v[230:233], v[34:49]
	v_mfma_f32_32x32x16_bf16 v[50:65], v[106:109], v[234:237], v[50:65]
	global_load_dwordx4 v[222:225], v[110:111], off offset:2560
	global_load_dwordx4 v[226:229], v[134:135], off offset:2560
	global_load_dwordx4 v[230:233], v[136:137], off offset:2560
	global_load_dwordx4 v[234:237], v[138:139], off offset:2560
	s_waitcnt lgkmcnt(3)
	v_lshlrev_b32_e32 v98, 16, v248
	v_and_b32_e32 v99, 0xffff0000, v248
	v_lshlrev_b32_e32 v100, 16, v249
	v_and_b32_e32 v101, 0xffff0000, v249
	v_lshlrev_b32_e32 v102, 16, v250
	v_and_b32_e32 v103, 0xffff0000, v250
	v_lshlrev_b32_e32 v104, 16, v251
	v_and_b32_e32 v105, 0xffff0000, v251
	ds_read_b128 v[248:251], v163 offset:4240
	s_waitcnt lgkmcnt(3)
	v_lshlrev_b32_e32 v216, 16, v252
	v_and_b32_e32 v217, 0xffff0000, v252
	v_pk_add_f32 v[106:107], v[98:99], v[216:217]
	v_lshlrev_b32_e32 v216, 16, v253
	v_and_b32_e32 v217, 0xffff0000, v253
	v_pk_add_f32 v[108:109], v[100:101], v[216:217]
	v_lshlrev_b32_e32 v216, 16, v254
	v_and_b32_e32 v217, 0xffff0000, v254
	v_pk_add_f32 v[218:219], v[102:103], v[216:217]
	v_lshlrev_b32_e32 v216, 16, v255
	v_and_b32_e32 v217, 0xffff0000, v255
	v_pk_add_f32 v[220:221], v[104:105], v[216:217]
	ds_read_b128 v[252:255], v163 offset:3968
	v_fma_f32 v106, v159, v106, -v98
	v_fma_f32 v107, v159, v107, -v99
	v_fma_f32 v108, v159, v108, -v100
	v_fma_f32 v109, v159, v109, -v101
	v_fma_f32 v218, v159, v218, -v102
	v_fma_f32 v219, v159, v219, -v103
	v_fma_f32 v220, v159, v220, -v104
	v_fma_f32 v221, v159, v221, -v105
	v_cvt_pk_bf16_f32 v106, v106, v107
	v_cvt_pk_bf16_f32 v107, v108, v109
	v_cvt_pk_bf16_f32 v108, v218, v219
	v_cvt_pk_bf16_f32 v109, v220, v221
	s_and_saveexec_b64 s[10:11], s[6:7]
	s_cbranch_execz .Lpu3_3
	global_store_dwordx4 v[184:185], v[98:101], off offset:192
	global_store_dwordx4 v[184:185], v[102:105], off offset:208
.Lpu3_3:
	s_or_b64 exec, exec, s[10:11]
	s_waitcnt vmcnt(8)
	v_mfma_f32_32x32x16_bf16 v[2:17], v[106:109], v[70:73], v[2:17]
	v_mfma_f32_32x32x16_bf16 v[18:33], v[106:109], v[74:77], v[18:33]
	v_mfma_f32_32x32x16_bf16 v[34:49], v[106:109], v[78:81], v[34:49]
	v_mfma_f32_32x32x16_bf16 v[50:65], v[106:109], v[66:69], v[50:65]
	global_load_dwordx4 v[70:73], v[110:111], off offset:3072
	global_load_dwordx4 v[74:77], v[134:135], off offset:3072
	global_load_dwordx4 v[78:81], v[136:137], off offset:3072
	global_load_dwordx4 v[66:69], v[138:139], off offset:3072
	s_waitcnt lgkmcnt(3)
	v_lshlrev_b32_e32 v98, 16, v238
	v_and_b32_e32 v99, 0xffff0000, v238
	v_lshlrev_b32_e32 v100, 16, v239
	v_and_b32_e32 v101, 0xffff0000, v239
	v_lshlrev_b32_e32 v102, 16, v240
	v_and_b32_e32 v103, 0xffff0000, v240
	v_lshlrev_b32_e32 v104, 16, v241
	v_and_b32_e32 v105, 0xffff0000, v241
	ds_read_b128 v[238:241], v163 offset:4272
	s_waitcnt lgkmcnt(3)
	v_lshlrev_b32_e32 v216, 16, v242
	v_and_b32_e32 v217, 0xffff0000, v242
	v_pk_add_f32 v[106:107], v[98:99], v[216:217]
	v_lshlrev_b32_e32 v216, 16, v243
	v_and_b32_e32 v217, 0xffff0000, v243
	v_pk_add_f32 v[108:109], v[100:101], v[216:217]
	v_lshlrev_b32_e32 v216, 16, v244
	v_and_b32_e32 v217, 0xffff0000, v244
	v_pk_add_f32 v[218:219], v[102:103], v[216:217]
	v_lshlrev_b32_e32 v216, 16, v245
	v_and_b32_e32 v217, 0xffff0000, v245
	v_pk_add_f32 v[220:221], v[104:105], v[216:217]
	ds_read_b128 v[242:245], v163 offset:4000
	v_fma_f32 v106, v159, v106, -v98
	v_fma_f32 v107, v159, v107, -v99
	v_fma_f32 v108, v159, v108, -v100
	v_fma_f32 v109, v159, v109, -v101
	v_fma_f32 v218, v159, v218, -v102
	v_fma_f32 v219, v159, v219, -v103
	v_fma_f32 v220, v159, v220, -v104
	v_fma_f32 v221, v159, v221, -v105
	v_cvt_pk_bf16_f32 v106, v106, v107
	v_cvt_pk_bf16_f32 v107, v108, v109
	v_cvt_pk_bf16_f32 v108, v218, v219
	v_cvt_pk_bf16_f32 v109, v220, v221
	s_and_saveexec_b64 s[10:11], s[6:7]
	s_cbranch_execz .Lpu3_4
	global_store_dwordx4 v[184:185], v[98:101], off offset:256
	global_store_dwordx4 v[184:185], v[102:105], off offset:272
.Lpu3_4:
	s_or_b64 exec, exec, s[10:11]
	s_waitcnt vmcnt(8)
	v_mfma_f32_32x32x16_bf16 v[2:17], v[106:109], v[82:85], v[2:17]
	v_mfma_f32_32x32x16_bf16 v[18:33], v[106:109], v[86:89], v[18:33]
	v_mfma_f32_32x32x16_bf16 v[34:49], v[106:109], v[90:93], v[34:49]
	v_mfma_f32_32x32x16_bf16 v[50:65], v[106:109], v[94:97], v[50:65]
	global_load_dwordx4 v[82:85], v[110:111], off offset:3584
	global_load_dwordx4 v[86:89], v[134:135], off offset:3584
	global_load_dwordx4 v[90:93], v[136:137], off offset:3584
	global_load_dwordx4 v[94:97], v[138:139], off offset:3584
	s_waitcnt lgkmcnt(3)
	v_lshlrev_b32_e32 v98, 16, v248
	v_and_b32_e32 v99, 0xffff0000, v248
	v_lshlrev_b32_e32 v100, 16, v249
	v_and_b32_e32 v101, 0xffff0000, v249
	v_lshlrev_b32_e32 v102, 16, v250
	v_and_b32_e32 v103, 0xffff0000, v250
	v_lshlrev_b32_e32 v104, 16, v251
	v_and_b32_e32 v105, 0xffff0000, v251
	ds_read_b128 v[248:251], v163 offset:4304
	s_waitcnt lgkmcnt(3)
	v_lshlrev_b32_e32 v216, 16, v252
	v_and_b32_e32 v217, 0xffff0000, v252
	v_pk_add_f32 v[106:107], v[98:99], v[216:217]
	v_lshlrev_b32_e32 v216, 16, v253
	v_and_b32_e32 v217, 0xffff0000, v253
	v_pk_add_f32 v[108:109], v[100:101], v[216:217]
	v_lshlrev_b32_e32 v216, 16, v254
	v_and_b32_e32 v217, 0xffff0000, v254
	v_pk_add_f32 v[218:219], v[102:103], v[216:217]
	v_lshlrev_b32_e32 v216, 16, v255
	v_and_b32_e32 v217, 0xffff0000, v255
	v_pk_add_f32 v[220:221], v[104:105], v[216:217]
	ds_read_b128 v[252:255], v163 offset:4032
	v_fma_f32 v106, v159, v106, -v98
	v_fma_f32 v107, v159, v107, -v99
	v_fma_f32 v108, v159, v108, -v100
	v_fma_f32 v109, v159, v109, -v101
	v_fma_f32 v218, v159, v218, -v102
	v_fma_f32 v219, v159, v219, -v103
	v_fma_f32 v220, v159, v220, -v104
	v_fma_f32 v221, v159, v221, -v105
	v_cvt_pk_bf16_f32 v106, v106, v107
	v_cvt_pk_bf16_f32 v107, v108, v109
	v_cvt_pk_bf16_f32 v108, v218, v219
	v_cvt_pk_bf16_f32 v109, v220, v221
	s_and_saveexec_b64 s[10:11], s[6:7]
	s_cbranch_execz .Lpu3_5
	global_store_dwordx4 v[184:185], v[98:101], off offset:320
	global_store_dwordx4 v[184:185], v[102:105], off offset:336
.Lpu3_5:
	s_or_b64 exec, exec, s[10:11]
	s_waitcnt vmcnt(8)
	v_mfma_f32_32x32x16_bf16 v[2:17], v[106:109], v[222:225], v[2:17]
	v_mfma_f32_32x32x16_bf16 v[18:33], v[106:109], v[226:229], v[18:33]
	v_mfma_f32_32x32x16_bf16 v[34:49], v[106:109], v[230:233], v[34:49]
	v_mfma_f32_32x32x16_bf16 v[50:65], v[106:109], v[234:237], v[50:65]
	s_waitcnt lgkmcnt(3)
	v_lshlrev_b32_e32 v98, 16, v238
	v_and_b32_e32 v99, 0xffff0000, v238
	v_lshlrev_b32_e32 v100, 16, v239
	v_and_b32_e32 v101, 0xffff0000, v239
	v_lshlrev_b32_e32 v102, 16, v240
	v_and_b32_e32 v103, 0xffff0000, v240
	v_lshlrev_b32_e32 v104, 16, v241
	v_and_b32_e32 v105, 0xffff0000, v241
	s_waitcnt lgkmcnt(2)
	v_lshlrev_b32_e32 v216, 16, v242
	v_and_b32_e32 v217, 0xffff0000, v242
	v_pk_add_f32 v[106:107], v[98:99], v[216:217]
	v_lshlrev_b32_e32 v216, 16, v243
	v_and_b32_e32 v217, 0xffff0000, v243
	v_pk_add_f32 v[108:109], v[100:101], v[216:217]
	v_lshlrev_b32_e32 v216, 16, v244
	v_and_b32_e32 v217, 0xffff0000, v244
	v_pk_add_f32 v[218:219], v[102:103], v[216:217]
	v_lshlrev_b32_e32 v216, 16, v245
	v_and_b32_e32 v217, 0xffff0000, v245
	v_pk_add_f32 v[220:221], v[104:105], v[216:217]
	v_fma_f32 v106, v159, v106, -v98
	v_fma_f32 v107, v159, v107, -v99
	v_fma_f32 v108, v159, v108, -v100
	v_fma_f32 v109, v159, v109, -v101
	v_fma_f32 v218, v159, v218, -v102
	v_fma_f32 v219, v159, v219, -v103
	v_fma_f32 v220, v159, v220, -v104
	v_fma_f32 v221, v159, v221, -v105
	v_cvt_pk_bf16_f32 v106, v106, v107
	v_cvt_pk_bf16_f32 v107, v108, v109
	v_cvt_pk_bf16_f32 v108, v218, v219
	v_cvt_pk_bf16_f32 v109, v220, v221
	s_and_saveexec_b64 s[10:11], s[6:7]
	s_cbranch_execz .Lpu3_6
	global_store_dwordx4 v[184:185], v[98:101], off offset:384
	global_store_dwordx4 v[184:185], v[102:105], off offset:400
.Lpu3_6:
	s_or_b64 exec, exec, s[10:11]
	s_waitcnt vmcnt(4)
	v_mfma_f32_32x32x16_bf16 v[2:17], v[106:109], v[70:73], v[2:17]
	v_mfma_f32_32x32x16_bf16 v[18:33], v[106:109], v[74:77], v[18:33]
	v_mfma_f32_32x32x16_bf16 v[34:49], v[106:109], v[78:81], v[34:49]
	v_mfma_f32_32x32x16_bf16 v[50:65], v[106:109], v[66:69], v[50:65]
	s_waitcnt lgkmcnt(1)
	v_lshlrev_b32_e32 v98, 16, v248
	v_and_b32_e32 v99, 0xffff0000, v248
	v_lshlrev_b32_e32 v100, 16, v249
	v_and_b32_e32 v101, 0xffff0000, v249
	v_lshlrev_b32_e32 v102, 16, v250
	v_and_b32_e32 v103, 0xffff0000, v250
	v_lshlrev_b32_e32 v104, 16, v251
	v_and_b32_e32 v105, 0xffff0000, v251
	s_waitcnt lgkmcnt(0)
	v_lshlrev_b32_e32 v216, 16, v252
	v_and_b32_e32 v217, 0xffff0000, v252
	v_pk_add_f32 v[106:107], v[98:99], v[216:217]
	v_lshlrev_b32_e32 v216, 16, v253
	v_and_b32_e32 v217, 0xffff0000, v253
	v_pk_add_f32 v[108:109], v[100:101], v[216:217]
	v_lshlrev_b32_e32 v216, 16, v254
	v_and_b32_e32 v217, 0xffff0000, v254
	v_pk_add_f32 v[218:219], v[102:103], v[216:217]
	v_lshlrev_b32_e32 v216, 16, v255
	v_and_b32_e32 v217, 0xffff0000, v255
	v_pk_add_f32 v[220:221], v[104:105], v[216:217]
	v_fma_f32 v106, v159, v106, -v98
	v_fma_f32 v107, v159, v107, -v99
	v_fma_f32 v108, v159, v108, -v100
	v_fma_f32 v109, v159, v109, -v101
	v_fma_f32 v218, v159, v218, -v102
	v_fma_f32 v219, v159, v219, -v103
	v_fma_f32 v220, v159, v220, -v104
	v_fma_f32 v221, v159, v221, -v105
	v_cvt_pk_bf16_f32 v106, v106, v107
	v_cvt_pk_bf16_f32 v107, v108, v109
	v_cvt_pk_bf16_f32 v108, v218, v219
	v_cvt_pk_bf16_f32 v109, v220, v221
	s_and_saveexec_b64 s[10:11], s[6:7]
	s_cbranch_execz .Lpu3_7
	global_store_dwordx4 v[184:185], v[98:101], off offset:448
	global_store_dwordx4 v[184:185], v[102:105], off offset:464
